# combined: GLA output stage load hoist + batched LDS fetches + dead div_scale removal on top of the mask/weight rewrites
# speedup vs baseline: 1.0036x; 1.0014x over previous
; #define MFMA32(a, b, c) __builtin_amdgcn_mfma_f32_32x32x16_bf16((a), (b), (c), 0, 0, 0)
; DI void gla_stage3(const Ctx& c0, int layer, int unit, int cb, LAS unsigned char* lds) {
;     ...
;     const bf16* qgp = (const bf16*)(c.ws + O_QG) + (row0 + r) * 256 + h * 64 + 8 * hi;
;     const float* sp = (const float*)(c.ws + O_UPD) + (size_t)unit * 8192;
;     const float* gn = c.a->in[I_GNORM] + (size_t)layer * 128;
;     bf16x8 qf[4];
; #pragma unroll
;     for (int s = 0; s < 4; ++s) qf[s] = *(const bf16x8*)(qgp + 16 * s);
;     f32x16 o[4];
; #pragma unroll
;     for (int vb = 0; vb < 4; ++vb) {
;         o[vb] = f32x16{};
; #pragma unroll
;         for (int s = 0; s < 4; ++s) { const float* s0 = sp + (size_t)(16 * s + 8 * hi) * 128 + 32 * vb + r;
;             const bf16x8 bfv = pack8(s0[0], s0[128], s0[256], s0[384], s0[512], s0[640], s0[768], s0[896]);
;             o[vb] = MFMA32(qf[s], bfv, o[vb]); }
.LBB0_604:
	s_mov_b64 s[2:3], s[84:85]
	s_mov_b64 s[0:1], s[86:87]
	s_ashr_i32 s2, s35, 8
	s_ashr_i32 s3, s2, 31
	s_lshl_b64 s[2:3], s[2:3], 12
	s_and_b32 s5, s8, 0xfc0
	s_or_b32 s2, s2, s5
	s_or_b64 s[2:3], s[2:3], s[6:7]
	v_mov_b32_e32 v3, s3
	v_or_b32_e32 v2, s2, v152
	s_bfe_u32 s4, s35, 0x20006
	v_lshlrev_b64 v[2:3], 9, v[2:3]
	v_lshl_add_u64 v[2:3], s[0:1], 0, v[2:3]
	s_lshl_b32 s10, s4, 7
	v_lshl_add_u64 v[2:3], v[2:3], 0, s[10:11]
	v_lshl_add_u64 v[2:3], v[2:3], 0, v[86:87]
	v_lshl_add_u64 v[4:5], v[2:3], 0, s[16:17]
	v_add_co_u32_e32 v2, vcc, s13, v2
	v_lshl_add_u64 v[90:91], s[0:1], 0, v[84:85]
	s_nop 0
	v_addc_co_u32_e32 v3, vcc, 0, v3, vcc
	global_load_dwordx4 v[50:53], v[2:3], off
	global_load_dwordx4 v[110:113], v[4:5], off offset:96
	global_load_dwordx4 v[106:109], v[4:5], off offset:64
	global_load_dwordx4 v[102:105], v[4:5], off offset:32
	v_add_co_u32_e32 v2, vcc, s24, v90
	s_lshl_b64 s[2:3], s[2:3], 10
	s_nop 0
	v_addc_co_u32_e32 v3, vcc, -1, v91, vcc
	v_add_co_u32_e32 v58, vcc, s28, v90
	global_load_dword v2, v[2:3], off
	s_nop 0
	v_addc_co_u32_e32 v59, vcc, -1, v91, vcc
	global_load_dword v3, v[58:59], off offset:384
	global_load_dword v4, v[58:59], off offset:896
	global_load_dword v5, v[58:59], off offset:1408
	global_load_dword v6, v[58:59], off offset:1920
	global_load_dword v7, v[58:59], off offset:2432
	global_load_dword v8, v[58:59], off offset:2944
	global_load_dword v9, v[58:59], off offset:3456
	v_add_co_u32_e32 v18, vcc, s25, v90
	s_lshl_b32 s4, s4, 8
	s_nop 0
	v_addc_co_u32_e32 v19, vcc, -1, v91, vcc
	v_add_co_u32_e32 v114, vcc, s29, v90
	global_load_dword v18, v[18:19], off
	s_nop 0
	v_addc_co_u32_e32 v115, vcc, -1, v91, vcc
	global_load_dword v19, v[114:115], off offset:384
	global_load_dword v20, v[114:115], off offset:896
	global_load_dword v21, v[114:115], off offset:1408
	global_load_dword v22, v[114:115], off offset:1920
	global_load_dword v23, v[114:115], off offset:2432
	global_load_dword v24, v[114:115], off offset:2944
	global_load_dword v25, v[114:115], off offset:3456
	s_add_u32 s0, s0, s2
	s_addc_u32 s1, s1, s3
	s_add_u32 s0, s0, s4
	s_addc_u32 s1, s1, 0
	s_add_i32 s35, s35, s12
	s_add_i32 s8, s8, s9
	v_lshl_add_u64 v[84:85], v[84:85], 0, s[14:15]
	s_cmpk_lt_i32 s35, 0x800
	v_add_co_u32_e32 v26, vcc, s26, v90
	s_nop 1
	v_addc_co_u32_e32 v27, vcc, -1, v91, vcc
	v_add_co_u32_e32 v118, vcc, s30, v90
	global_load_dword v26, v[26:27], off
	s_nop 0
	v_addc_co_u32_e32 v119, vcc, -1, v91, vcc
	global_load_dword v27, v[118:119], off offset:384
	global_load_dword v28, v[118:119], off offset:896
	global_load_dword v29, v[118:119], off offset:1408
	global_load_dword v30, v[118:119], off offset:1920
	global_load_dword v31, v[118:119], off offset:2432
	global_load_dword v32, v[118:119], off offset:2944
	global_load_dword v33, v[118:119], off offset:3456
	v_add_co_u32_e32 v42, vcc, s27, v90
	s_nop 1
	v_addc_co_u32_e32 v43, vcc, -1, v91, vcc
	v_add_co_u32_e32 v120, vcc, s31, v90
	global_load_dword v42, v[42:43], off
	s_nop 0
	v_addc_co_u32_e32 v121, vcc, -1, v91, vcc
	global_load_dword v43, v[120:121], off offset:384
	global_load_dword v44, v[120:121], off offset:896
	global_load_dword v45, v[120:121], off offset:1408
	global_load_dword v46, v[120:121], off offset:1920
	global_load_dword v47, v[120:121], off offset:2432
	global_load_dword v48, v[120:121], off offset:2944
	global_load_dword v49, v[120:121], off offset:3456
	s_waitcnt vmcnt(16) lgkmcnt(0)
	global_load_dword v41, v[114:115], off offset:3584
	global_load_dword v40, v[114:115], off offset:3072
	global_load_dword v39, v[114:115], off offset:2560
	global_load_dword v38, v[114:115], off offset:2048
	global_load_dword v37, v[114:115], off offset:1536
	global_load_dword v36, v[114:115], off offset:1024
	global_load_dword v35, v[114:115], off offset:512
	global_load_dword v34, v[114:115], off
	global_load_dword v145, v[58:59], off offset:3584
	global_load_dword v146, v[58:59], off offset:3072
	global_load_dword v143, v[58:59], off offset:2560
	global_load_dword v144, v[58:59], off offset:2048
	global_load_dword v141, v[58:59], off offset:1536
	global_load_dword v142, v[58:59], off offset:1024
	global_load_dword v139, v[58:59], off offset:512
	global_load_dword v140, v[58:59], off
	v_cvt_pk_bf16_f32 v2, v2, v3
	v_cvt_pk_bf16_f32 v3, v4, v5
	v_cvt_pk_bf16_f32 v4, v6, v7
	v_cvt_pk_bf16_f32 v5, v8, v9
	v_cvt_pk_bf16_f32 v18, v18, v19
	s_nop 0
	v_mfma_f32_32x32x16_bf16 v[2:17], v[50:53], v[2:5], 0
	v_cvt_pk_bf16_f32 v19, v20, v21
	v_cvt_pk_bf16_f32 v20, v22, v23
	v_cvt_pk_bf16_f32 v21, v24, v25
	s_nop 1
	v_mfma_f32_32x32x16_bf16 v[2:17], v[102:105], v[18:21], v[2:17]
	s_waitcnt vmcnt(24) lgkmcnt(0)
	global_load_dword v63, v[114:115], off offset:3712
	global_load_dword v62, v[114:115], off offset:3200
	global_load_dword v61, v[114:115], off offset:2688
	global_load_dword v60, v[114:115], off offset:2176
	global_load_dword v57, v[114:115], off offset:1664
	global_load_dword v56, v[114:115], off offset:1152
	global_load_dword v55, v[114:115], off offset:640
	global_load_dword v54, v[114:115], off offset:128
	global_load_dword v173, v[58:59], off offset:3712
	global_load_dword v176, v[58:59], off offset:3200
	global_load_dword v171, v[58:59], off offset:2688
	global_load_dword v174, v[58:59], off offset:2176
	global_load_dword v169, v[58:59], off offset:1664
	global_load_dword v172, v[58:59], off offset:1152
	global_load_dword v167, v[58:59], off offset:640
	global_load_dword v170, v[58:59], off offset:128
	global_load_dword v157, v[118:119], off offset:3584
	global_load_dword v160, v[118:119], off offset:3072
	global_load_dword v155, v[118:119], off offset:2560
	global_load_dword v158, v[118:119], off offset:2048
	global_load_dword v149, v[118:119], off offset:1536
	global_load_dword v156, v[118:119], off offset:1024
	global_load_dword v147, v[118:119], off offset:512
	global_load_dword v148, v[118:119], off
	v_cvt_pk_bf16_f32 v26, v26, v27
	v_cvt_pk_bf16_f32 v27, v28, v29
	v_cvt_pk_bf16_f32 v28, v30, v31
	v_cvt_pk_bf16_f32 v29, v32, v33
	s_nop 1
	v_mfma_f32_32x32x16_bf16 v[2:17], v[106:109], v[26:29], v[2:17]
	v_cmp_lt_i32_e32 vcc, v94, v95
	s_waitcnt vmcnt(20) lgkmcnt(0)
; #define MFMA32(a, b, c) __builtin_amdgcn_mfma_f32_32x32x16_bf16((a), (b), (c), 0, 0, 0)
; DI void gla_stage3(const Ctx& c0, int layer, int unit, int cb, LAS unsigned char* lds) {
;     ...
;     f32x16 o[4];
; #pragma unroll
;     for (int vb = 0; vb < 4; ++vb) {
;         o[vb] = f32x16{};
; #pragma unroll
;         for (int s = 0; s < 4; ++s) { const float* s0 = sp + (size_t)(16 * s + 8 * hi) * 128 + 32 * vb + r;
;             const bf16x8 bfv = pack8(s0[0], s0[128], s0[256], s0[384], s0[512], s0[640], s0[768], s0[896]);
;             o[vb] = MFMA32(qf[s], bfv, o[vb]); }
;         asm volatile("" ::: "memory");
;     }
	global_load_dword v127, v[114:115], off offset:3840
	global_load_dword v126, v[114:115], off offset:3328
	global_load_dword v125, v[114:115], off offset:2816
	global_load_dword v124, v[114:115], off offset:2304
	global_load_dword v123, v[114:115], off offset:1792
	global_load_dword v122, v[114:115], off offset:1280
	global_load_dword v117, v[114:115], off offset:768
	global_load_dword v116, v[114:115], off offset:256
	global_load_dword v214, v[58:59], off offset:3840
	global_load_dword v212, v[58:59], off offset:3328
	global_load_dword v205, v[58:59], off offset:2816
	global_load_dword v210, v[58:59], off offset:2304
	global_load_dword v203, v[58:59], off offset:1792
	global_load_dword v208, v[58:59], off offset:1280
	global_load_dword v201, v[58:59], off offset:768
	global_load_dword v206, v[58:59], off offset:256
	global_load_dword v199, v[120:121], off offset:3712
	global_load_dword v204, v[120:121], off offset:3200
	global_load_dword v197, v[120:121], off offset:2688
	global_load_dword v202, v[120:121], off offset:2176
	global_load_dword v195, v[120:121], off offset:1664
	global_load_dword v200, v[120:121], off offset:1152
	global_load_dword v183, v[120:121], off offset:640
	global_load_dword v198, v[120:121], off offset:128
	global_load_dword v181, v[118:119], off offset:3712
	global_load_dword v196, v[118:119], off offset:3200
	global_load_dword v179, v[118:119], off offset:2688
	global_load_dword v182, v[118:119], off offset:2176
	global_load_dword v177, v[118:119], off offset:1664
	global_load_dword v180, v[118:119], off offset:1152
	global_load_dword v175, v[118:119], off offset:640
	global_load_dword v178, v[118:119], off offset:128
	global_load_dword v165, v[120:121], off offset:3584
	global_load_dword v168, v[120:121], off offset:3072
	global_load_dword v163, v[120:121], off offset:2560
	global_load_dword v166, v[120:121], off offset:2048
	global_load_dword v161, v[120:121], off offset:1536
	global_load_dword v164, v[120:121], off offset:1024
	global_load_dword v159, v[120:121], off offset:512
	global_load_dword v162, v[120:121], off
	v_cvt_pk_bf16_f32 v42, v42, v43
	v_cvt_pk_bf16_f32 v43, v44, v45
	v_cvt_pk_bf16_f32 v44, v46, v47
	v_cvt_pk_bf16_f32 v45, v48, v49
	s_nop 1
	v_mfma_f32_32x32x16_bf16 v[2:17], v[110:113], v[42:45], v[2:17]
	s_waitcnt vmcnt(40) lgkmcnt(0)
	global_load_dword v238, v[82:83], off offset:384
	global_load_dword v236, v[82:83], off offset:256
	global_load_dword v234, v[82:83], off offset:128
	global_load_dword v232, v[82:83], off
	global_load_dword v90, v[90:91], off
	global_load_dword v230, v[120:121], off offset:3328
	global_load_dword v219, v[120:121], off offset:2816
	global_load_dword v228, v[120:121], off offset:2304
	global_load_dword v217, v[120:121], off offset:1792
	global_load_dword v226, v[120:121], off offset:1280
	global_load_dword v215, v[120:121], off offset:768
	global_load_dword v224, v[120:121], off offset:256
	global_load_dword v213, v[118:119], off offset:3840
	global_load_dword v222, v[118:119], off offset:3328
	global_load_dword v211, v[118:119], off offset:2816
	global_load_dword v220, v[118:119], off offset:2304
	global_load_dword v209, v[118:119], off offset:1792
	global_load_dword v218, v[118:119], off offset:1280
	global_load_dword v207, v[118:119], off offset:768
	global_load_dword v216, v[118:119], off offset:256
	v_cvt_pk_bf16_f32 v18, v140, v139
	v_cvt_pk_bf16_f32 v34, v34, v35
	v_cvt_pk_bf16_f32 v19, v142, v141
	v_cvt_pk_bf16_f32 v35, v36, v37
	v_cvt_pk_bf16_f32 v20, v144, v143
	v_cvt_pk_bf16_f32 v36, v38, v39
	v_cvt_pk_bf16_f32 v21, v146, v145
	v_cvt_pk_bf16_f32 v37, v40, v41
	s_nop 0
	v_mfma_f32_32x32x16_bf16 v[18:33], v[50:53], v[18:21], 0
	v_mfma_f32_32x32x16_bf16 v[18:33], v[102:105], v[34:37], v[18:33]
	s_waitcnt vmcnt(60) lgkmcnt(0)
	v_cvt_pk_bf16_f32 v34, v148, v147
	v_cvt_pk_bf16_f32 v35, v156, v149
	v_cvt_pk_bf16_f32 v36, v158, v155
	v_cvt_pk_bf16_f32 v37, v160, v157
	s_nop 1
	v_mfma_f32_32x32x16_bf16 v[18:33], v[106:109], v[34:37], v[18:33]
	s_waitcnt vmcnt(20) lgkmcnt(0)
	v_cvt_pk_bf16_f32 v34, v162, v159
	v_cvt_pk_bf16_f32 v35, v164, v161
	v_cvt_pk_bf16_f32 v36, v166, v163
	v_cvt_pk_bf16_f32 v37, v168, v165
	s_nop 1
	v_mfma_f32_32x32x16_bf16 v[18:33], v[110:113], v[34:37], v[18:33]
	s_waitcnt vmcnt(62) lgkmcnt(0)
	v_cvt_pk_bf16_f32 v34, v170, v167
	v_cvt_pk_bf16_f32 v54, v54, v55
	v_cvt_pk_bf16_f32 v35, v172, v169
	v_cvt_pk_bf16_f32 v55, v56, v57
	v_cvt_pk_bf16_f32 v36, v174, v171
	v_cvt_pk_bf16_f32 v56, v60, v61
	v_cvt_pk_bf16_f32 v37, v176, v173
	v_cvt_pk_bf16_f32 v57, v62, v63
	s_nop 0
	v_mfma_f32_32x32x16_bf16 v[34:49], v[50:53], v[34:37], 0
	v_mfma_f32_32x32x16_bf16 v[34:49], v[102:105], v[54:57], v[34:49]
	s_waitcnt vmcnt(28) lgkmcnt(0)
	v_cvt_pk_bf16_f32 v54, v178, v175
	v_cvt_pk_bf16_f32 v55, v180, v177
	v_cvt_pk_bf16_f32 v56, v182, v179
	v_cvt_pk_bf16_f32 v57, v196, v181
	s_nop 1
	v_mfma_f32_32x32x16_bf16 v[34:49], v[106:109], v[54:57], v[34:49]
	s_waitcnt vmcnt(36) lgkmcnt(0)
	v_cvt_pk_bf16_f32 v54, v198, v183
	v_cvt_pk_bf16_f32 v55, v200, v195
	v_cvt_pk_bf16_f32 v56, v202, v197
	v_cvt_pk_bf16_f32 v57, v204, v199
	s_nop 1
	v_mfma_f32_32x32x16_bf16 v[34:49], v[110:113], v[54:57], v[34:49]
	s_nop 0
	s_nop 0
	s_waitcnt vmcnt(44) lgkmcnt(0)
	v_cvt_pk_bf16_f32 v54, v206, v201
	v_cvt_pk_bf16_f32 v114, v116, v117
	v_cvt_pk_bf16_f32 v55, v208, v203
	v_cvt_pk_bf16_f32 v115, v122, v123
	v_cvt_pk_bf16_f32 v56, v210, v205
	v_cvt_pk_bf16_f32 v116, v124, v125
	v_cvt_pk_bf16_f32 v57, v212, v214
	v_cvt_pk_bf16_f32 v117, v126, v127
	s_nop 0
	v_mfma_f32_32x32x16_bf16 v[50:65], v[50:53], v[54:57], 0
	v_mfma_f32_32x32x16_bf16 v[50:65], v[102:105], v[114:117], v[50:65]
	s_waitcnt vmcnt(0) lgkmcnt(0)
; #define LAS __attribute__((address_space(3)))
; #define LDS_WAIT() asm volatile("s_waitcnt lgkmcnt(0)" ::: "memory")
; DI float bf2f(bf16 b) { return __uint_as_float(((unsigned)b) << 16); }
; DI void g3_tile_in(const bf16* g, LAS unsigned char* R, int lane) {
; #pragma unroll
;     for (int it = 0; it < 8; ++it) { const int row = 4 * it + (lane >> 4), ch = lane & 15;
;         *(LAS u32x4*)(R + row * G3_PITCH + ch * 16) = *(const u32x4*)(g + (size_t)row * 512 + ch * 8); }
;     LDS_WAIT();
; }
; DI void gla_stage3(const Ctx& c0, int layer, int unit, int cb, LAS unsigned char* lds) {
;     ...
;     g3_tile_in((const bf16*)(c.ws + O_OINTRA) + row0 * 512 + h * 128, R, lane);
; #pragma unroll
;     for (int vb = 0; vb < 4; ++vb) {
; #pragma unroll
;         for (int rg = 0; rg < 16; ++rg) o[vb][rg] += bf2f(*(const LAS bf16*)(Re + ((rg & 3) + 8 * (rg >> 2)) * G3_PITCH + 64 * vb));
;         asm volatile("" ::: "memory");
;     }
	v_cvt_pk_bf16_f32 v102, v216, v207
	v_cvt_pk_bf16_f32 v103, v218, v209
	v_cvt_pk_bf16_f32 v104, v220, v211
	v_cvt_pk_bf16_f32 v105, v222, v213
	s_nop 1
	v_mfma_f32_32x32x16_bf16 v[50:65], v[106:109], v[102:105], v[50:65]
	s_nop 0
	s_waitcnt vmcnt(8) lgkmcnt(0)
	v_cvt_pk_bf16_f32 v102, v224, v215
	v_cvt_pk_bf16_f32 v103, v226, v217
	v_cvt_pk_bf16_f32 v104, v228, v219
	v_cvt_pk_bf16_f32 v105, v230, v90
	v_lshl_add_u64 v[90:91], s[0:1], 0, v[88:89]
	v_lshl_add_u64 v[106:107], v[90:91], 0, s[18:19]
	v_mfma_f32_32x32x16_bf16 v[50:65], v[110:113], v[102:105], v[50:65]
	v_lshl_add_u64 v[102:103], v[106:107], 0, v[66:67]
	global_load_dwordx4 v[102:105], v[102:103], off
	s_waitcnt vmcnt(0) lgkmcnt(0)
	v_lshl_add_u64 v[168:169], v[90:91], 0, s[20:21]
	v_lshl_add_u64 v[140:141], v[168:169], 0, v[70:71]
	global_load_dwordx4 v[174:177], v[140:141], off
	v_lshl_add_u64 v[140:141], v[106:107], 0, v[70:71]
	global_load_dwordx4 v[146:149], v[140:141], off
	v_lshl_add_u64 v[144:145], v[106:107], 0, v[68:69]
	global_load_dwordx4 v[140:143], v[144:145], off
	ds_write_b128 v92, v[102:105]
	s_waitcnt vmcnt(0) lgkmcnt(0)
	v_lshl_add_u64 v[144:145], v[168:169], 0, v[76:77]
	global_load_dwordx4 v[200:203], v[144:145], off
	v_lshl_add_u64 v[144:145], v[168:169], 0, v[74:75]
	global_load_dwordx4 v[196:199], v[144:145], off
	v_lshl_add_u64 v[144:145], v[168:169], 0, v[72:73]
	global_load_dwordx4 v[178:181], v[144:145], off
	v_lshl_add_u64 v[144:145], v[106:107], 0, v[74:75]
	global_load_dwordx4 v[156:159], v[144:145], off
	v_lshl_add_u64 v[102:103], v[106:107], 0, v[72:73]
	global_load_dwordx4 v[102:105], v[102:103], off
	ds_write_b128 v92, v[140:143] offset:1088
	s_waitcnt vmcnt(5) lgkmcnt(0)
	v_lshl_add_u64 v[140:141], v[168:169], 0, v[78:79]
	global_load_dwordx4 v[204:207], v[140:141], off
	v_lshl_add_u64 v[140:141], v[106:107], 0, v[78:79]
	global_load_dwordx4 v[160:163], v[140:141], off
	v_lshl_add_u64 v[144:145], v[106:107], 0, v[76:77]
	global_load_dwordx4 v[140:143], v[144:145], off
	ds_write_b128 v92, v[146:149] offset:2176
	s_waitcnt vmcnt(3) lgkmcnt(0)
	v_lshl_add_u64 v[144:145], v[168:169], 0, v[66:67]
	global_load_dwordx4 v[164:167], v[144:145], off
	v_lshl_add_u64 v[148:149], v[106:107], 0, v[80:81]
	global_load_dwordx4 v[144:147], v[148:149], off
	ds_write_b128 v92, v[102:105] offset:3264
	s_waitcnt vmcnt(6) lgkmcnt(0)
	v_lshl_add_u64 v[148:149], v[168:169], 0, v[68:69]
	global_load_dwordx4 v[170:173], v[148:149], off
	ds_write_b128 v92, v[156:159] offset:4352
	s_waitcnt vmcnt(3) lgkmcnt(0)
	ds_write_b128 v92, v[140:143] offset:5440
	s_waitcnt vmcnt(4) lgkmcnt(0)
	ds_write_b128 v92, v[160:163] offset:6528
	s_waitcnt vmcnt(1) lgkmcnt(0)
	ds_write_b128 v92, v[144:147] offset:7616
	s_waitcnt lgkmcnt(0)
	ds_read_u16 v138, v1
	ds_read_u16 v137, v1 offset:272
	ds_read_u16 v136, v1 offset:544
	ds_read_u16 v135, v1 offset:816
	ds_read_u16 v134, v1 offset:2176
	ds_read_u16 v133, v1 offset:2448
	ds_read_u16 v132, v1 offset:2720
	ds_read_u16 v131, v1 offset:2992
	s_waitcnt lgkmcnt(0)
	v_lshlrev_b32_e32 v138, 16, v138
	v_add_f32_e32 v138, v2, v138
	v_lshlrev_b32_e32 v137, 16, v137
	v_add_f32_e32 v137, v3, v137
	v_lshlrev_b32_e32 v136, 16, v136
	v_add_f32_e32 v136, v4, v136
	v_lshlrev_b32_e32 v135, 16, v135
	v_add_f32_e32 v135, v5, v135
	v_lshlrev_b32_e32 v134, 16, v134
	v_add_f32_e32 v134, v6, v134
	v_lshlrev_b32_e32 v133, 16, v133
	v_add_f32_e32 v133, v7, v133
	v_lshlrev_b32_e32 v132, 16, v132
	v_add_f32_e32 v132, v8, v132
	v_lshlrev_b32_e32 v131, 16, v131
	v_add_f32_e32 v131, v9, v131
	ds_read_u16 v130, v1 offset:4352
	ds_read_u16 v129, v1 offset:4624
	ds_read_u16 v128, v1 offset:4896
	ds_read_u16 v127, v1 offset:5168
	ds_read_u16 v126, v1 offset:6528
	ds_read_u16 v125, v1 offset:6800
	ds_read_u16 v124, v1 offset:7072
	s_waitcnt lgkmcnt(0)
	v_lshlrev_b32_e32 v130, 16, v130
	v_add_f32_e32 v130, v10, v130
	v_lshlrev_b32_e32 v129, 16, v129
	v_add_f32_e32 v129, v11, v129
	v_lshlrev_b32_e32 v128, 16, v128
	v_add_f32_e32 v128, v12, v128
	v_lshlrev_b32_e32 v127, 16, v127
	v_add_f32_e32 v127, v13, v127
	v_lshlrev_b32_e32 v126, 16, v126
	v_add_f32_e32 v126, v14, v126
	v_lshlrev_b32_e32 v125, 16, v125
	v_add_f32_e32 v125, v15, v125
	v_lshlrev_b32_e32 v124, 16, v124
	v_add_f32_e32 v124, v16, v124
	ds_read_u16 v2, v1 offset:7344
	s_waitcnt lgkmcnt(0)
	v_lshlrev_b32_e32 v2, 16, v2
	v_add_f32_e32 v123, v17, v2
	ds_read_u16 v122, v1 offset:64
	ds_read_u16 v121, v1 offset:336
	ds_read_u16 v120, v1 offset:608
	ds_read_u16 v119, v1 offset:880
	ds_read_u16 v118, v1 offset:2240
	ds_read_u16 v117, v1 offset:2512
	ds_read_u16 v116, v1 offset:2784
	ds_read_u16 v115, v1 offset:3056
	s_waitcnt lgkmcnt(0)
	v_lshlrev_b32_e32 v122, 16, v122
	v_add_f32_e32 v122, v18, v122
	v_lshlrev_b32_e32 v121, 16, v121
	v_add_f32_e32 v121, v19, v121
	v_lshlrev_b32_e32 v120, 16, v120
	v_add_f32_e32 v120, v20, v120
	v_lshlrev_b32_e32 v119, 16, v119
	v_add_f32_e32 v119, v21, v119
	v_lshlrev_b32_e32 v118, 16, v118
	v_add_f32_e32 v118, v22, v118
	v_lshlrev_b32_e32 v117, 16, v117
	v_add_f32_e32 v117, v23, v117
	v_lshlrev_b32_e32 v116, 16, v116
	v_add_f32_e32 v116, v24, v116
	v_lshlrev_b32_e32 v115, 16, v115
	v_add_f32_e32 v115, v25, v115
	ds_read_u16 v114, v1 offset:4416
	ds_read_u16 v113, v1 offset:4688
	ds_read_u16 v112, v1 offset:4960
	ds_read_u16 v111, v1 offset:5232
	ds_read_u16 v110, v1 offset:6592
	ds_read_u16 v109, v1 offset:6864
	ds_read_u16 v108, v1 offset:7136
	s_waitcnt lgkmcnt(0)
; #define LAS __attribute__((address_space(3)))
; DI float bf2f(bf16 b) { return __uint_as_float(((unsigned)b) << 16); }
; DI void gla_stage3(const Ctx& c0, int layer, int unit, int cb, LAS unsigned char* lds) {
;     ...
;     for (int vb = 0; vb < 4; ++vb) {
; #pragma unroll
;         for (int rg = 0; rg < 16; ++rg) o[vb][rg] += bf2f(*(const LAS bf16*)(Re + ((rg & 3) + 8 * (rg >> 2)) * G3_PITCH + 64 * vb));
;         asm volatile("" ::: "memory");
;     }
;     float rs[16];
; #pragma unroll
;     for (int rg = 0; rg < 16; ++rg) { float ss = o[0][rg] * o[0][rg] + o[1][rg] * o[1][rg] + o[2][rg] * o[2][rg] + o[3][rg] * o[3][rg];
;         ss += __shfl_xor(ss, 1); ss += __shfl_xor(ss, 2); ss += __shfl_xor(ss, 4); ss += __shfl_xor(ss, 8); ss += __shfl_xor(ss, 16);
;         rs[rg] = 1.f / sqrtf(ss * (1.f / 128.f) + EPS); }
	v_lshlrev_b32_e32 v114, 16, v114
	v_add_f32_e32 v114, v26, v114
	v_lshlrev_b32_e32 v113, 16, v113
	v_add_f32_e32 v113, v27, v113
	v_lshlrev_b32_e32 v112, 16, v112
	v_add_f32_e32 v112, v28, v112
	v_lshlrev_b32_e32 v111, 16, v111
	v_add_f32_e32 v111, v29, v111
	v_lshlrev_b32_e32 v110, 16, v110
	v_add_f32_e32 v110, v30, v110
	v_lshlrev_b32_e32 v109, 16, v109
	v_add_f32_e32 v109, v31, v109
	v_lshlrev_b32_e32 v108, 16, v108
	v_add_f32_e32 v108, v32, v108
	ds_read_u16 v2, v1 offset:7408
	s_waitcnt lgkmcnt(0)
	v_lshlrev_b32_e32 v2, 16, v2
	v_add_f32_e32 v107, v33, v2
	ds_read_u16 v2, v1 offset:128
	s_waitcnt lgkmcnt(0)
	v_lshlrev_b32_e32 v2, 16, v2
	v_add_f32_e32 v106, v34, v2
	ds_read_u16 v2, v1 offset:400
	s_waitcnt lgkmcnt(0)
	v_lshlrev_b32_e32 v2, 16, v2
	v_add_f32_e32 v105, v35, v2
	ds_read_u16 v2, v1 offset:672
	s_waitcnt lgkmcnt(0)
	v_lshlrev_b32_e32 v2, 16, v2
	v_add_f32_e32 v104, v36, v2
	ds_read_u16 v2, v1 offset:944
	s_waitcnt lgkmcnt(0)
	v_lshlrev_b32_e32 v2, 16, v2
	v_add_f32_e32 v103, v37, v2
	ds_read_u16 v2, v1 offset:2304
	s_waitcnt lgkmcnt(0)
	v_lshlrev_b32_e32 v2, 16, v2
	v_add_f32_e32 v102, v38, v2
	ds_read_u16 v2, v1 offset:2576
	s_waitcnt lgkmcnt(0)
	v_lshlrev_b32_e32 v2, 16, v2
	v_add_f32_e32 v39, v39, v2
	ds_read_u16 v2, v1 offset:2848
	s_waitcnt lgkmcnt(0)
	v_lshlrev_b32_e32 v2, 16, v2
	v_add_f32_e32 v38, v40, v2
	ds_read_u16 v2, v1 offset:3120
	s_waitcnt lgkmcnt(0)
	v_lshlrev_b32_e32 v2, 16, v2
	v_add_f32_e32 v37, v41, v2
	ds_read_u16 v36, v1 offset:4480
	ds_read_u16 v34, v1 offset:4752
	ds_read_u16 v33, v1 offset:5024
	ds_read_u16 v32, v1 offset:5296
	ds_read_u16 v30, v1 offset:6656
	ds_read_u16 v29, v1 offset:6928
	ds_read_u16 v28, v1 offset:7200
	s_waitcnt lgkmcnt(0)
	v_lshlrev_b32_e32 v36, 16, v36
	v_add_f32_e32 v36, v42, v36
	v_lshlrev_b32_e32 v34, 16, v34
	v_add_f32_e32 v34, v43, v34
	v_lshlrev_b32_e32 v33, 16, v33
	v_add_f32_e32 v33, v44, v33
	v_lshlrev_b32_e32 v32, 16, v32
	v_add_f32_e32 v32, v45, v32
	v_lshlrev_b32_e32 v30, 16, v30
	v_add_f32_e32 v30, v46, v30
	v_lshlrev_b32_e32 v29, 16, v29
	v_add_f32_e32 v29, v47, v29
	v_lshlrev_b32_e32 v28, 16, v28
	v_add_f32_e32 v28, v48, v28
	ds_read_u16 v2, v1 offset:7472
	s_waitcnt lgkmcnt(0)
	v_lshlrev_b32_e32 v2, 16, v2
	v_add_f32_e32 v26, v49, v2
	ds_read_u16 v19, v1 offset:192
	ds_read_u16 v18, v1 offset:464
	ds_read_u16 v17, v1 offset:736
	ds_read_u16 v16, v1 offset:1008
	ds_read_u16 v15, v1 offset:2368
	ds_read_u16 v14, v1 offset:2640
	ds_read_u16 v13, v1 offset:2912
	ds_read_u16 v12, v1 offset:3184
	s_waitcnt lgkmcnt(0)
	v_lshlrev_b32_e32 v19, 16, v19
	v_add_f32_e32 v19, v50, v19
	v_lshlrev_b32_e32 v18, 16, v18
	v_add_f32_e32 v18, v51, v18
	v_lshlrev_b32_e32 v17, 16, v17
	v_add_f32_e32 v17, v52, v17
	v_lshlrev_b32_e32 v16, 16, v16
	v_add_f32_e32 v16, v53, v16
	v_lshlrev_b32_e32 v15, 16, v15
	v_add_f32_e32 v15, v54, v15
	v_lshlrev_b32_e32 v14, 16, v14
	v_add_f32_e32 v14, v55, v14
	v_lshlrev_b32_e32 v13, 16, v13
	v_add_f32_e32 v13, v56, v13
	v_lshlrev_b32_e32 v12, 16, v12
	v_add_f32_e32 v12, v57, v12
	ds_read_u16 v11, v1 offset:4544
	ds_read_u16 v10, v1 offset:4816
	ds_read_u16 v9, v1 offset:5088
	ds_read_u16 v8, v1 offset:5360
	ds_read_u16 v7, v1 offset:6720
	ds_read_u16 v6, v1 offset:6992
	ds_read_u16 v5, v1 offset:7264
	s_waitcnt lgkmcnt(0)
	v_lshlrev_b32_e32 v11, 16, v11
	v_add_f32_e32 v11, v58, v11
	v_lshlrev_b32_e32 v10, 16, v10
	v_add_f32_e32 v10, v59, v10
	v_lshlrev_b32_e32 v9, 16, v9
	v_add_f32_e32 v9, v60, v9
	v_lshlrev_b32_e32 v8, 16, v8
	v_add_f32_e32 v8, v61, v8
	v_lshlrev_b32_e32 v7, 16, v7
	v_add_f32_e32 v7, v62, v7
	v_lshlrev_b32_e32 v6, 16, v6
	v_add_f32_e32 v6, v63, v6
	v_lshlrev_b32_e32 v5, 16, v5
	v_add_f32_e32 v5, v64, v5
	ds_read_u16 v2, v1 offset:7536
	s_waitcnt lgkmcnt(0)
	s_waitcnt lgkmcnt(0)
	v_lshlrev_b32_e32 v2, 16, v2
	v_add_f32_e32 v4, v65, v2
	v_cndmask_b32_e32 v2, v93, v94, vcc
	v_cmp_lt_i32_e32 vcc, v96, v95
	v_lshlrev_b32_e32 v2, 2, v2
	s_nop 0
	v_cndmask_b32_e32 v3, v93, v96, vcc
	v_cmp_lt_i32_e32 vcc, v97, v95
	v_lshlrev_b32_e32 v3, 2, v3
	s_nop 0
	v_cndmask_b32_e32 v20, v93, v97, vcc
	v_cmp_lt_i32_e32 vcc, v98, v95
	v_lshlrev_b32_e32 v20, 2, v20
	s_nop 0
	v_cndmask_b32_e32 v21, v93, v98, vcc
	v_cmp_lt_i32_e32 vcc, v99, v95
	v_lshlrev_b32_e32 v47, 2, v21
	s_nop 0
	v_cndmask_b32_e32 v21, v93, v99, vcc
	v_lshlrev_b32_e32 v48, 2, v21
	v_mul_f32_e32 v21, v122, v122
	v_fmac_f32_e32 v21, v138, v138
	v_fmac_f32_e32 v21, v106, v106
	v_fmac_f32_e32 v21, v19, v19
	s_nop 1
	v_add_f32_dpp v21, v21, v21 quad_perm:[1,0,3,2] row_mask:0xf bank_mask:0xf
	s_nop 1
	v_add_f32_dpp v21, v21, v21 quad_perm:[2,3,0,1] row_mask:0xf bank_mask:0xf
	s_nop 1
	v_add_f32_dpp v21, v21, v21 row_half_mirror row_mask:0xf bank_mask:0xf
	s_nop 1
	v_add_f32_dpp v21, v21, v21 row_mirror row_mask:0xf bank_mask:0xf
	v_mov_b32_e32 v22, v21
	v_mov_b32_e32 v23, v21
	s_nop 1
	v_permlane16_swap_b32_e32 v22, v23
	v_add_f32_e32 v21, v22, v23
	v_fmamk_f32 v21, v21, 0x3c000000, v100
	v_cmp_gt_f32_e32 vcc, s34, v21
	v_mul_f32_e32 v22, 0x4f800000, v21
	s_nop 0
	v_cndmask_b32_e32 v21, v21, v22, vcc
	v_sqrt_f32_e32 v22, v21
	s_nop 0
	v_add_u32_e32 v23, -1, v22
	v_fma_f32 v24, -v23, v22, v21
	v_cmp_ge_f32_e64 s[4:5], 0, v24
	v_add_u32_e32 v24, 1, v22
	s_nop 0
	v_cndmask_b32_e64 v23, v22, v23, s[4:5]
	v_fma_f32 v22, -v24, v22, v21
	v_cmp_lt_f32_e64 s[4:5], 0, v22
	s_nop 1
	v_cndmask_b32_e64 v22, v23, v24, s[4:5]
	v_mul_f32_e32 v23, 0x37800000, v22
	v_cndmask_b32_e32 v22, v22, v23, vcc
	v_cmp_class_f32_e32 vcc, v21, v101
	s_nop 1
	v_cndmask_b32_e32 v21, v22, v21, vcc
	s_nop 0
	v_div_scale_f32 v24, vcc, 1.0, v21, 1.0
	v_rcp_f32_e32 v46, v21
	v_mul_f32_e32 v21, v121, v121
; DI void gla_stage3(const Ctx& c0, int layer, int unit, int cb, LAS unsigned char* lds) {
;     ...
;     float rs[16];
; #pragma unroll
;     for (int rg = 0; rg < 16; ++rg) { float ss = o[0][rg] * o[0][rg] + o[1][rg] * o[1][rg] + o[2][rg] * o[2][rg] + o[3][rg] * o[3][rg];
;         ss += __shfl_xor(ss, 1); ss += __shfl_xor(ss, 2); ss += __shfl_xor(ss, 4); ss += __shfl_xor(ss, 8); ss += __shfl_xor(ss, 16);
;         rs[rg] = 1.f / sqrtf(ss * (1.f / 128.f) + EPS); }
	v_fmac_f32_e32 v21, v137, v137
	v_fmac_f32_e32 v21, v105, v105
	v_fmac_f32_e32 v21, v18, v18
	s_nop 1
	v_add_f32_dpp v21, v21, v21 quad_perm:[1,0,3,2] row_mask:0xf bank_mask:0xf
	v_mul_f32_e32 v19, v19, v46
	s_nop 1
	v_add_f32_dpp v21, v21, v21 quad_perm:[2,3,0,1] row_mask:0xf bank_mask:0xf
	s_nop 1
	v_add_f32_dpp v21, v21, v21 row_half_mirror row_mask:0xf bank_mask:0xf
	s_nop 1
	v_add_f32_dpp v21, v21, v21 row_mirror row_mask:0xf bank_mask:0xf
	v_mov_b32_e32 v22, v21
	v_mov_b32_e32 v23, v21
	s_nop 1
	v_permlane16_swap_b32_e32 v22, v23
	v_add_f32_e32 v21, v22, v23
	v_fmamk_f32 v21, v21, 0x3c000000, v100
	v_cmp_gt_f32_e32 vcc, s34, v21
	v_mul_f32_e32 v22, 0x4f800000, v21
	s_nop 0
	v_cndmask_b32_e32 v21, v21, v22, vcc
	v_sqrt_f32_e32 v22, v21
	s_nop 0
	v_add_u32_e32 v23, -1, v22
	v_fma_f32 v24, -v23, v22, v21
	v_cmp_ge_f32_e64 s[4:5], 0, v24
	v_add_u32_e32 v24, 1, v22
	s_nop 0
	v_cndmask_b32_e64 v23, v22, v23, s[4:5]
	v_fma_f32 v22, -v24, v22, v21
	v_cmp_lt_f32_e64 s[4:5], 0, v22
	s_nop 1
	v_cndmask_b32_e64 v22, v23, v24, s[4:5]
	v_mul_f32_e32 v23, 0x37800000, v22
	v_cndmask_b32_e32 v22, v22, v23, vcc
	v_cmp_class_f32_e32 vcc, v21, v101
	s_nop 1
	v_cndmask_b32_e32 v21, v22, v21, vcc
	s_nop 0
	v_div_scale_f32 v24, vcc, 1.0, v21, 1.0
	v_rcp_f32_e32 v45, v21
	v_mul_f32_e32 v21, v120, v120
	v_fmac_f32_e32 v21, v136, v136
	v_fmac_f32_e32 v21, v104, v104
	v_fmac_f32_e32 v21, v17, v17
	s_nop 1
	v_add_f32_dpp v21, v21, v21 quad_perm:[1,0,3,2] row_mask:0xf bank_mask:0xf
	v_mul_f32_e32 v18, v18, v45
	s_nop 1
	v_add_f32_dpp v21, v21, v21 quad_perm:[2,3,0,1] row_mask:0xf bank_mask:0xf
	s_nop 1
	v_add_f32_dpp v21, v21, v21 row_half_mirror row_mask:0xf bank_mask:0xf
	s_nop 1
	v_add_f32_dpp v21, v21, v21 row_mirror row_mask:0xf bank_mask:0xf
	v_mov_b32_e32 v22, v21
	v_mov_b32_e32 v23, v21
	s_nop 1
	v_permlane16_swap_b32_e32 v22, v23
	v_add_f32_e32 v21, v22, v23
	v_fmamk_f32 v21, v21, 0x3c000000, v100
	v_cmp_gt_f32_e32 vcc, s34, v21
	v_mul_f32_e32 v22, 0x4f800000, v21
	s_nop 0
	v_cndmask_b32_e32 v21, v21, v22, vcc
	v_sqrt_f32_e32 v22, v21
	s_nop 0
	v_add_u32_e32 v23, -1, v22
	v_fma_f32 v24, -v23, v22, v21
	v_cmp_ge_f32_e64 s[4:5], 0, v24
	v_add_u32_e32 v24, 1, v22
	s_nop 0
	v_cndmask_b32_e64 v23, v22, v23, s[4:5]
	v_fma_f32 v22, -v24, v22, v21
	v_cmp_lt_f32_e64 s[4:5], 0, v22
	s_nop 1
	v_cndmask_b32_e64 v22, v23, v24, s[4:5]
	v_mul_f32_e32 v23, 0x37800000, v22
	v_cndmask_b32_e32 v22, v22, v23, vcc
	v_cmp_class_f32_e32 vcc, v21, v101
	s_nop 1
	v_cndmask_b32_e32 v21, v22, v21, vcc
	s_nop 0
	v_div_scale_f32 v24, vcc, 1.0, v21, 1.0
	v_rcp_f32_e32 v44, v21
	v_mul_f32_e32 v21, v119, v119
	v_fmac_f32_e32 v21, v135, v135
	v_fmac_f32_e32 v21, v103, v103
	v_fmac_f32_e32 v21, v16, v16
	s_nop 1
	v_add_f32_dpp v21, v21, v21 quad_perm:[1,0,3,2] row_mask:0xf bank_mask:0xf
	v_mul_f32_e32 v17, v17, v44
	s_nop 1
	v_add_f32_dpp v21, v21, v21 quad_perm:[2,3,0,1] row_mask:0xf bank_mask:0xf
	s_nop 1
	v_add_f32_dpp v21, v21, v21 row_half_mirror row_mask:0xf bank_mask:0xf
	s_nop 1
	v_add_f32_dpp v21, v21, v21 row_mirror row_mask:0xf bank_mask:0xf
	v_mov_b32_e32 v22, v21
	v_mov_b32_e32 v23, v21
	s_nop 1
	v_permlane16_swap_b32_e32 v22, v23
	v_add_f32_e32 v21, v22, v23
	v_fmamk_f32 v21, v21, 0x3c000000, v100
	v_cmp_gt_f32_e32 vcc, s34, v21
	v_mul_f32_e32 v22, 0x4f800000, v21
	s_nop 0
	v_cndmask_b32_e32 v21, v21, v22, vcc
	v_sqrt_f32_e32 v22, v21
	s_nop 0
	v_add_u32_e32 v23, -1, v22
	v_fma_f32 v24, -v23, v22, v21
	v_cmp_ge_f32_e64 s[4:5], 0, v24
	v_add_u32_e32 v24, 1, v22
	s_nop 0
	v_cndmask_b32_e64 v23, v22, v23, s[4:5]
	v_fma_f32 v22, -v24, v22, v21
	v_cmp_lt_f32_e64 s[4:5], 0, v22
	s_nop 1
	v_cndmask_b32_e64 v22, v23, v24, s[4:5]
	v_mul_f32_e32 v23, 0x37800000, v22
	v_cndmask_b32_e32 v22, v22, v23, vcc
	v_cmp_class_f32_e32 vcc, v21, v101
	s_nop 1
	v_cndmask_b32_e32 v21, v22, v21, vcc
	s_nop 0
	v_div_scale_f32 v24, vcc, 1.0, v21, 1.0
	v_rcp_f32_e32 v43, v21
	v_mul_f32_e32 v21, v118, v118
	v_fmac_f32_e32 v21, v134, v134
	v_fmac_f32_e32 v21, v102, v102
	v_fmac_f32_e32 v21, v15, v15
	s_nop 1
	v_add_f32_dpp v21, v21, v21 quad_perm:[1,0,3,2] row_mask:0xf bank_mask:0xf
	v_mul_f32_e32 v16, v16, v43
	s_nop 1
	v_add_f32_dpp v21, v21, v21 quad_perm:[2,3,0,1] row_mask:0xf bank_mask:0xf
	s_nop 1
	v_add_f32_dpp v21, v21, v21 row_half_mirror row_mask:0xf bank_mask:0xf
	s_nop 1
	v_add_f32_dpp v21, v21, v21 row_mirror row_mask:0xf bank_mask:0xf
	v_mov_b32_e32 v22, v21
	v_mov_b32_e32 v23, v21
	s_nop 1
	v_permlane16_swap_b32_e32 v22, v23
	v_add_f32_e32 v21, v22, v23
	v_fmamk_f32 v21, v21, 0x3c000000, v100
	v_cmp_gt_f32_e32 vcc, s34, v21
	v_mul_f32_e32 v22, 0x4f800000, v21
	s_nop 0
	v_cndmask_b32_e32 v21, v21, v22, vcc
	v_sqrt_f32_e32 v22, v21
	s_nop 0
	v_add_u32_e32 v23, -1, v22
	v_fma_f32 v24, -v23, v22, v21
	v_cmp_ge_f32_e64 s[4:5], 0, v24
	v_add_u32_e32 v24, 1, v22
	s_nop 0
	v_cndmask_b32_e64 v23, v22, v23, s[4:5]
	v_fma_f32 v22, -v24, v22, v21
	v_cmp_lt_f32_e64 s[4:5], 0, v22
	s_nop 1
	v_cndmask_b32_e64 v22, v23, v24, s[4:5]
	v_mul_f32_e32 v23, 0x37800000, v22
	v_cndmask_b32_e32 v22, v22, v23, vcc
	v_cmp_class_f32_e32 vcc, v21, v101
	s_nop 1
	v_cndmask_b32_e32 v21, v22, v21, vcc
	s_nop 0
	v_div_scale_f32 v24, vcc, 1.0, v21, 1.0
	v_rcp_f32_e32 v42, v21
	v_mul_f32_e32 v21, v117, v117
	v_fmac_f32_e32 v21, v133, v133
	v_fmac_f32_e32 v21, v39, v39
	v_fmac_f32_e32 v21, v14, v14
	s_nop 1
	v_add_f32_dpp v21, v21, v21 quad_perm:[1,0,3,2] row_mask:0xf bank_mask:0xf
	v_mul_f32_e32 v15, v15, v42
	s_nop 1
	v_add_f32_dpp v21, v21, v21 quad_perm:[2,3,0,1] row_mask:0xf bank_mask:0xf
	s_nop 1
	v_add_f32_dpp v21, v21, v21 row_half_mirror row_mask:0xf bank_mask:0xf
	s_nop 1
	v_add_f32_dpp v21, v21, v21 row_mirror row_mask:0xf bank_mask:0xf
; DI void gla_stage3(const Ctx& c0, int layer, int unit, int cb, LAS unsigned char* lds) {
;     ...
;     float rs[16];
; #pragma unroll
;     for (int rg = 0; rg < 16; ++rg) { float ss = o[0][rg] * o[0][rg] + o[1][rg] * o[1][rg] + o[2][rg] * o[2][rg] + o[3][rg] * o[3][rg];
;         ss += __shfl_xor(ss, 1); ss += __shfl_xor(ss, 2); ss += __shfl_xor(ss, 4); ss += __shfl_xor(ss, 8); ss += __shfl_xor(ss, 16);
;         rs[rg] = 1.f / sqrtf(ss * (1.f / 128.f) + EPS); }
	v_mov_b32_e32 v22, v21
	v_mov_b32_e32 v23, v21
	s_nop 1
	v_permlane16_swap_b32_e32 v22, v23
	v_add_f32_e32 v21, v22, v23
	v_fmamk_f32 v21, v21, 0x3c000000, v100
	v_cmp_gt_f32_e32 vcc, s34, v21
	v_mul_f32_e32 v22, 0x4f800000, v21
	s_nop 0
	v_cndmask_b32_e32 v21, v21, v22, vcc
	v_sqrt_f32_e32 v22, v21
	s_nop 0
	v_add_u32_e32 v23, -1, v22
	v_fma_f32 v24, -v23, v22, v21
	v_cmp_ge_f32_e64 s[4:5], 0, v24
	v_add_u32_e32 v24, 1, v22
	s_nop 0
	v_cndmask_b32_e64 v23, v22, v23, s[4:5]
	v_fma_f32 v22, -v24, v22, v21
	v_cmp_lt_f32_e64 s[4:5], 0, v22
	s_nop 1
	v_cndmask_b32_e64 v22, v23, v24, s[4:5]
	v_mul_f32_e32 v23, 0x37800000, v22
	v_cndmask_b32_e32 v22, v22, v23, vcc
	v_cmp_class_f32_e32 vcc, v21, v101
	s_nop 1
	v_cndmask_b32_e32 v21, v22, v21, vcc
	s_nop 0
	v_div_scale_f32 v24, vcc, 1.0, v21, 1.0
	v_rcp_f32_e32 v41, v21
	v_mul_f32_e32 v21, v116, v116
	v_fmac_f32_e32 v21, v132, v132
	v_fmac_f32_e32 v21, v38, v38
	v_fmac_f32_e32 v21, v13, v13
	s_nop 1
	v_add_f32_dpp v21, v21, v21 quad_perm:[1,0,3,2] row_mask:0xf bank_mask:0xf
	v_mul_f32_e32 v39, v39, v41
	v_mul_f32_e32 v14, v14, v41
	s_nop 1
	v_add_f32_dpp v21, v21, v21 quad_perm:[2,3,0,1] row_mask:0xf bank_mask:0xf
	s_nop 1
	v_add_f32_dpp v21, v21, v21 row_half_mirror row_mask:0xf bank_mask:0xf
	s_nop 1
	v_add_f32_dpp v21, v21, v21 row_mirror row_mask:0xf bank_mask:0xf
	v_mov_b32_e32 v22, v21
	v_mov_b32_e32 v23, v21
	s_nop 1
	v_permlane16_swap_b32_e32 v22, v23
	v_add_f32_e32 v21, v22, v23
	v_fmamk_f32 v21, v21, 0x3c000000, v100
	v_cmp_gt_f32_e32 vcc, s34, v21
	v_mul_f32_e32 v22, 0x4f800000, v21
	s_nop 0
	v_cndmask_b32_e32 v21, v21, v22, vcc
	v_sqrt_f32_e32 v22, v21
	s_nop 0
	v_add_u32_e32 v23, -1, v22
	v_fma_f32 v24, -v23, v22, v21
	v_cmp_ge_f32_e64 s[4:5], 0, v24
	v_add_u32_e32 v24, 1, v22
	s_nop 0
	v_cndmask_b32_e64 v23, v22, v23, s[4:5]
	v_fma_f32 v22, -v24, v22, v21
	v_cmp_lt_f32_e64 s[4:5], 0, v22
	s_nop 1
	v_cndmask_b32_e64 v22, v23, v24, s[4:5]
	v_mul_f32_e32 v23, 0x37800000, v22
	v_cndmask_b32_e32 v22, v22, v23, vcc
	v_cmp_class_f32_e32 vcc, v21, v101
	s_nop 1
	v_cndmask_b32_e32 v21, v22, v21, vcc
	s_nop 0
	v_div_scale_f32 v24, vcc, 1.0, v21, 1.0
	v_rcp_f32_e32 v40, v21
	v_mul_f32_e32 v21, v115, v115
	v_fmac_f32_e32 v21, v131, v131
	v_fmac_f32_e32 v21, v37, v37
	v_fmac_f32_e32 v21, v12, v12
	s_nop 1
	v_add_f32_dpp v21, v21, v21 quad_perm:[1,0,3,2] row_mask:0xf bank_mask:0xf
	v_mul_f32_e32 v38, v38, v40
	v_mul_f32_e32 v13, v13, v40
	s_nop 1
	v_add_f32_dpp v21, v21, v21 quad_perm:[2,3,0,1] row_mask:0xf bank_mask:0xf
	s_nop 1
	v_add_f32_dpp v21, v21, v21 row_half_mirror row_mask:0xf bank_mask:0xf
	s_nop 1
	v_add_f32_dpp v21, v21, v21 row_mirror row_mask:0xf bank_mask:0xf
	v_mov_b32_e32 v22, v21
	v_mov_b32_e32 v23, v21
	s_nop 1
	v_permlane16_swap_b32_e32 v22, v23
	v_add_f32_e32 v21, v22, v23
	v_fmamk_f32 v21, v21, 0x3c000000, v100
	v_cmp_gt_f32_e32 vcc, s34, v21
	v_mul_f32_e32 v22, 0x4f800000, v21
	s_nop 0
	v_cndmask_b32_e32 v21, v21, v22, vcc
	v_sqrt_f32_e32 v22, v21
	s_nop 0
	v_add_u32_e32 v23, -1, v22
	v_fma_f32 v24, -v23, v22, v21
	v_cmp_ge_f32_e64 s[4:5], 0, v24
	v_add_u32_e32 v24, 1, v22
	s_nop 0
	v_cndmask_b32_e64 v23, v22, v23, s[4:5]
	v_fma_f32 v22, -v24, v22, v21
	v_cmp_lt_f32_e64 s[4:5], 0, v22
	s_nop 1
	v_cndmask_b32_e64 v22, v23, v24, s[4:5]
	v_mul_f32_e32 v23, 0x37800000, v22
	v_cndmask_b32_e32 v22, v22, v23, vcc
	v_cmp_class_f32_e32 vcc, v21, v101
	s_nop 1
	v_cndmask_b32_e32 v21, v22, v21, vcc
	s_nop 0
	v_div_scale_f32 v24, vcc, 1.0, v21, 1.0
	v_rcp_f32_e32 v35, v21
	v_mul_f32_e32 v21, v114, v114
	v_fmac_f32_e32 v21, v130, v130
	v_fmac_f32_e32 v21, v36, v36
	v_fmac_f32_e32 v21, v11, v11
	s_nop 1
	v_add_f32_dpp v21, v21, v21 quad_perm:[1,0,3,2] row_mask:0xf bank_mask:0xf
	v_mul_f32_e32 v37, v37, v35
	v_mul_f32_e32 v12, v12, v35
	s_nop 1
	v_add_f32_dpp v21, v21, v21 quad_perm:[2,3,0,1] row_mask:0xf bank_mask:0xf
	s_nop 1
	v_add_f32_dpp v21, v21, v21 row_half_mirror row_mask:0xf bank_mask:0xf
	s_nop 1
	v_add_f32_dpp v21, v21, v21 row_mirror row_mask:0xf bank_mask:0xf
	v_mov_b32_e32 v22, v21
	v_mov_b32_e32 v23, v21
	s_nop 1
	v_permlane16_swap_b32_e32 v22, v23
	v_add_f32_e32 v21, v22, v23
	v_fmamk_f32 v21, v21, 0x3c000000, v100
	v_cmp_gt_f32_e32 vcc, s34, v21
	v_mul_f32_e32 v22, 0x4f800000, v21
	s_nop 0
	v_cndmask_b32_e32 v21, v21, v22, vcc
	v_sqrt_f32_e32 v22, v21
	s_nop 0
	v_add_u32_e32 v23, -1, v22
	v_fma_f32 v24, -v23, v22, v21
	v_cmp_ge_f32_e64 s[4:5], 0, v24
	v_add_u32_e32 v24, 1, v22
	s_nop 0
	v_cndmask_b32_e64 v23, v22, v23, s[4:5]
	v_fma_f32 v22, -v24, v22, v21
	v_cmp_lt_f32_e64 s[4:5], 0, v22
	s_nop 1
	v_cndmask_b32_e64 v22, v23, v24, s[4:5]
	v_mul_f32_e32 v23, 0x37800000, v22
	v_cndmask_b32_e32 v22, v22, v23, vcc
	v_cmp_class_f32_e32 vcc, v21, v101
	s_nop 1
	v_cndmask_b32_e32 v21, v22, v21, vcc
	s_nop 0
	v_div_scale_f32 v24, vcc, 1.0, v21, 1.0
	v_rcp_f32_e32 v31, v21
	v_mul_f32_e32 v21, v113, v113
	v_fmac_f32_e32 v21, v129, v129
	v_fmac_f32_e32 v21, v34, v34
	v_fmac_f32_e32 v21, v10, v10
	s_nop 1
	v_add_f32_dpp v21, v21, v21 quad_perm:[1,0,3,2] row_mask:0xf bank_mask:0xf
	v_mul_f32_e32 v36, v36, v31
	v_mul_f32_e32 v11, v11, v31
	s_nop 1
	v_add_f32_dpp v21, v21, v21 quad_perm:[2,3,0,1] row_mask:0xf bank_mask:0xf
	s_nop 1
	v_add_f32_dpp v21, v21, v21 row_half_mirror row_mask:0xf bank_mask:0xf
	s_nop 1
	v_add_f32_dpp v21, v21, v21 row_mirror row_mask:0xf bank_mask:0xf
	v_mov_b32_e32 v22, v21
	v_mov_b32_e32 v23, v21
	s_nop 1
	v_permlane16_swap_b32_e32 v22, v23
	v_add_f32_e32 v21, v22, v23
	v_fmamk_f32 v21, v21, 0x3c000000, v100
	v_cmp_gt_f32_e32 vcc, s34, v21
	v_mul_f32_e32 v22, 0x4f800000, v21
	s_nop 0
	v_cndmask_b32_e32 v21, v21, v22, vcc
	v_sqrt_f32_e32 v22, v21
	s_nop 0
; DI void gla_stage3(const Ctx& c0, int layer, int unit, int cb, LAS unsigned char* lds) {
;     ...
;     float rs[16];
; #pragma unroll
;     for (int rg = 0; rg < 16; ++rg) { float ss = o[0][rg] * o[0][rg] + o[1][rg] * o[1][rg] + o[2][rg] * o[2][rg] + o[3][rg] * o[3][rg];
;         ss += __shfl_xor(ss, 1); ss += __shfl_xor(ss, 2); ss += __shfl_xor(ss, 4); ss += __shfl_xor(ss, 8); ss += __shfl_xor(ss, 16);
;         rs[rg] = 1.f / sqrtf(ss * (1.f / 128.f) + EPS); }
	v_add_u32_e32 v23, -1, v22
	v_fma_f32 v24, -v23, v22, v21
	v_cmp_ge_f32_e64 s[4:5], 0, v24
	v_add_u32_e32 v24, 1, v22
	s_nop 0
	v_cndmask_b32_e64 v23, v22, v23, s[4:5]
	v_fma_f32 v22, -v24, v22, v21
	v_cmp_lt_f32_e64 s[4:5], 0, v22
	s_nop 1
	v_cndmask_b32_e64 v22, v23, v24, s[4:5]
	v_mul_f32_e32 v23, 0x37800000, v22
	v_cndmask_b32_e32 v22, v22, v23, vcc
	v_cmp_class_f32_e32 vcc, v21, v101
	s_nop 1
	v_cndmask_b32_e32 v21, v22, v21, vcc
	s_nop 0
	v_div_scale_f32 v24, vcc, 1.0, v21, 1.0
	v_rcp_f32_e32 v27, v21
	v_mul_f32_e32 v21, v112, v112
	v_fmac_f32_e32 v21, v128, v128
	v_fmac_f32_e32 v21, v33, v33
	v_fmac_f32_e32 v21, v9, v9
	s_nop 1
	v_add_f32_dpp v21, v21, v21 quad_perm:[1,0,3,2] row_mask:0xf bank_mask:0xf
	v_mul_f32_e32 v34, v34, v27
	v_mul_f32_e32 v10, v10, v27
	s_nop 1
	v_add_f32_dpp v21, v21, v21 quad_perm:[2,3,0,1] row_mask:0xf bank_mask:0xf
	s_nop 1
	v_add_f32_dpp v21, v21, v21 row_half_mirror row_mask:0xf bank_mask:0xf
	s_nop 1
	v_add_f32_dpp v21, v21, v21 row_mirror row_mask:0xf bank_mask:0xf
	v_mov_b32_e32 v22, v21
	v_mov_b32_e32 v23, v21
	s_nop 1
	v_permlane16_swap_b32_e32 v22, v23
	v_add_f32_e32 v21, v22, v23
	v_fmamk_f32 v21, v21, 0x3c000000, v100
	v_cmp_gt_f32_e32 vcc, s34, v21
	v_mul_f32_e32 v22, 0x4f800000, v21
	s_nop 0
	v_cndmask_b32_e32 v21, v21, v22, vcc
	v_sqrt_f32_e32 v22, v21
	s_nop 0
	v_add_u32_e32 v23, -1, v22
	v_fma_f32 v24, -v23, v22, v21
	v_cmp_ge_f32_e64 s[4:5], 0, v24
	v_add_u32_e32 v24, 1, v22
	s_nop 0
	v_cndmask_b32_e64 v23, v22, v23, s[4:5]
	v_fma_f32 v22, -v24, v22, v21
	v_cmp_lt_f32_e64 s[4:5], 0, v22
	s_nop 1
	v_cndmask_b32_e64 v22, v23, v24, s[4:5]
	v_mul_f32_e32 v23, 0x37800000, v22
	v_cndmask_b32_e32 v22, v22, v23, vcc
	v_cmp_class_f32_e32 vcc, v21, v101
	s_nop 1
	v_cndmask_b32_e32 v21, v22, v21, vcc
	s_nop 0
	v_div_scale_f32 v24, vcc, 1.0, v21, 1.0
	v_rcp_f32_e32 v25, v21
	v_mul_f32_e32 v21, v111, v111
	v_fmac_f32_e32 v21, v127, v127
	v_fmac_f32_e32 v21, v32, v32
	v_fmac_f32_e32 v21, v8, v8
	s_nop 1
	v_add_f32_dpp v21, v21, v21 quad_perm:[1,0,3,2] row_mask:0xf bank_mask:0xf
	v_mul_f32_e32 v33, v33, v25
	v_mul_f32_e32 v9, v9, v25
	s_nop 1
	v_add_f32_dpp v21, v21, v21 quad_perm:[2,3,0,1] row_mask:0xf bank_mask:0xf
	s_nop 1
	v_add_f32_dpp v21, v21, v21 row_half_mirror row_mask:0xf bank_mask:0xf
	s_nop 1
	v_add_f32_dpp v21, v21, v21 row_mirror row_mask:0xf bank_mask:0xf
	v_mov_b32_e32 v22, v21
	v_mov_b32_e32 v23, v21
	s_nop 1
	v_permlane16_swap_b32_e32 v22, v23
	v_add_f32_e32 v21, v22, v23
	v_fmamk_f32 v21, v21, 0x3c000000, v100
	v_cmp_gt_f32_e32 vcc, s34, v21
	v_mul_f32_e32 v22, 0x4f800000, v21
	s_nop 0
	v_cndmask_b32_e32 v21, v21, v22, vcc
	v_sqrt_f32_e32 v22, v21
	s_nop 0
	v_add_u32_e32 v23, -1, v22
	v_fma_f32 v24, -v23, v22, v21
	v_cmp_ge_f32_e64 s[4:5], 0, v24
	v_add_u32_e32 v24, 1, v22
	s_nop 0
	v_cndmask_b32_e64 v23, v22, v23, s[4:5]
	v_fma_f32 v22, -v24, v22, v21
	v_cmp_lt_f32_e64 s[4:5], 0, v22
	s_nop 1
	v_cndmask_b32_e64 v22, v23, v24, s[4:5]
	v_mul_f32_e32 v23, 0x37800000, v22
	v_cndmask_b32_e32 v22, v22, v23, vcc
	v_cmp_class_f32_e32 vcc, v21, v101
	s_nop 1
	v_cndmask_b32_e32 v21, v22, v21, vcc
	s_nop 0
	v_div_scale_f32 v24, vcc, 1.0, v21, 1.0
	v_rcp_f32_e32 v24, v21
	v_mul_f32_e32 v21, v110, v110
	v_fmac_f32_e32 v21, v126, v126
	v_fmac_f32_e32 v21, v30, v30
	v_fmac_f32_e32 v21, v7, v7
	s_nop 1
	v_add_f32_dpp v21, v21, v21 quad_perm:[1,0,3,2] row_mask:0xf bank_mask:0xf
	v_mul_f32_e32 v32, v32, v24
	v_mul_f32_e32 v8, v8, v24
	s_nop 1
	v_add_f32_dpp v21, v21, v21 quad_perm:[2,3,0,1] row_mask:0xf bank_mask:0xf
	s_nop 1
	v_add_f32_dpp v21, v21, v21 row_half_mirror row_mask:0xf bank_mask:0xf
	s_nop 1
	v_add_f32_dpp v21, v21, v21 row_mirror row_mask:0xf bank_mask:0xf
	v_mov_b32_e32 v22, v21
	v_mov_b32_e32 v23, v21
	s_nop 1
	v_permlane16_swap_b32_e32 v22, v23
	v_add_f32_e32 v21, v22, v23
	v_fmamk_f32 v21, v21, 0x3c000000, v100
	v_cmp_gt_f32_e32 vcc, s34, v21
	v_mul_f32_e32 v22, 0x4f800000, v21
	s_nop 0
	v_cndmask_b32_e32 v21, v21, v22, vcc
	v_sqrt_f32_e32 v22, v21
	s_nop 0
	v_add_u32_e32 v23, -1, v22
	v_fma_f32 v49, -v23, v22, v21
	v_cmp_ge_f32_e64 s[4:5], 0, v49
	v_add_u32_e32 v49, 1, v22
	s_nop 0
	v_cndmask_b32_e64 v23, v22, v23, s[4:5]
	v_fma_f32 v22, -v49, v22, v21
	v_cmp_lt_f32_e64 s[4:5], 0, v22
	s_nop 1
	v_cndmask_b32_e64 v22, v23, v49, s[4:5]
	v_mul_f32_e32 v23, 0x37800000, v22
	v_cndmask_b32_e32 v22, v22, v23, vcc
	v_cmp_class_f32_e32 vcc, v21, v101
	s_nop 1
	v_cndmask_b32_e32 v21, v22, v21, vcc
	s_nop 0
	v_div_scale_f32 v49, vcc, 1.0, v21, 1.0
	v_rcp_f32_e32 v23, v21
	v_mul_f32_e32 v21, v109, v109
	v_fmac_f32_e32 v21, v125, v125
	v_fmac_f32_e32 v21, v29, v29
	v_fmac_f32_e32 v21, v6, v6
	s_nop 1
	v_add_f32_dpp v21, v21, v21 quad_perm:[1,0,3,2] row_mask:0xf bank_mask:0xf
	v_mul_f32_e32 v30, v30, v23
	v_mul_f32_e32 v7, v7, v23
	s_nop 1
	v_add_f32_dpp v21, v21, v21 quad_perm:[2,3,0,1] row_mask:0xf bank_mask:0xf
	s_nop 1
	v_add_f32_dpp v21, v21, v21 row_half_mirror row_mask:0xf bank_mask:0xf
	s_nop 1
	v_add_f32_dpp v21, v21, v21 row_mirror row_mask:0xf bank_mask:0xf
	v_mov_b32_e32 v22, v21
	v_mov_b32_e32 v49, v21
	s_nop 1
	v_permlane16_swap_b32_e32 v22, v49
	v_add_f32_e32 v21, v22, v49
	v_fmamk_f32 v21, v21, 0x3c000000, v100
	v_cmp_gt_f32_e32 vcc, s34, v21
	v_mul_f32_e32 v22, 0x4f800000, v21
	s_nop 0
	v_cndmask_b32_e32 v21, v21, v22, vcc
	v_sqrt_f32_e32 v22, v21
	s_nop 0
	v_add_u32_e32 v49, -1, v22
	v_fma_f32 v50, -v49, v22, v21
	v_cmp_ge_f32_e64 s[4:5], 0, v50
	v_add_u32_e32 v50, 1, v22
	s_nop 0
	v_cndmask_b32_e64 v49, v22, v49, s[4:5]
	v_fma_f32 v22, -v50, v22, v21
	v_cmp_lt_f32_e64 s[4:5], 0, v22
	s_nop 1
	v_cndmask_b32_e64 v22, v49, v50, s[4:5]
	v_mul_f32_e32 v49, 0x37800000, v22
; #define LAS __attribute__((address_space(3)))
; #define LDS_WAIT() asm volatile("s_waitcnt lgkmcnt(0)" ::: "memory")
; DI unsigned cvtpk(float lo, float hi) { f32x2 v = {lo, hi}; bf16x2_t b = __builtin_convertvector(v, bf16x2_t); return __builtin_bit_cast(unsigned, b); }
; DI float bf2f(bf16 b) { return __uint_as_float(((unsigned)b) << 16); }
; DI float siluf_(float x) { return x / (1.f + __expf(-x)); }
; DI void gla_stage3(const Ctx& c0, int layer, int unit, int cb, LAS unsigned char* lds) {
;     ...
;     float rs[16];
; #pragma unroll
;     for (int rg = 0; rg < 16; ++rg) { float ss = o[0][rg] * o[0][rg] + o[1][rg] * o[1][rg] + o[2][rg] * o[2][rg] + o[3][rg] * o[3][rg];
;         ss += __shfl_xor(ss, 1); ss += __shfl_xor(ss, 2); ss += __shfl_xor(ss, 4); ss += __shfl_xor(ss, 8); ss += __shfl_xor(ss, 16);
;         rs[rg] = 1.f / sqrtf(ss * (1.f / 128.f) + EPS); }
;     LDS_WAIT();
;     g3_tile_in((const bf16*)(c.ws + O_GR) + row0 * 512 + h * 128, R, lane);
; #pragma unroll
;     for (int vb = 0; vb < 4; ++vb) { const float g = gn[32 * vb + r];
; #pragma unroll
;         for (int rg = 0; rg < 16; ++rg) { LAS bf16* e = (LAS bf16*)(R + (4 * hi) * G3_PITCH + r * 2 + ((rg & 3) + 8 * (rg >> 2)) * G3_PITCH + 64 * vb);
;             const float z = bf2f(*e);
;             *e = (bf16)(cvtpk(o[vb][rg] * rs[rg] * g * siluf_(z), 0.f) & 0xffffu); }
	v_cndmask_b32_e32 v22, v22, v49, vcc
	v_cmp_class_f32_e32 vcc, v21, v101
	s_nop 1
	v_cndmask_b32_e32 v21, v22, v21, vcc
	s_nop 0
	v_div_scale_f32 v50, vcc, 1.0, v21, 1.0
	v_rcp_f32_e32 v22, v21
	v_mul_f32_e32 v21, v108, v108
	v_fmac_f32_e32 v21, v124, v124
	v_fmac_f32_e32 v21, v28, v28
	v_fmac_f32_e32 v21, v5, v5
	s_nop 1
	v_add_f32_dpp v21, v21, v21 quad_perm:[1,0,3,2] row_mask:0xf bank_mask:0xf
	v_mul_f32_e32 v29, v29, v22
	v_mul_f32_e32 v6, v6, v22
	s_nop 1
	v_add_f32_dpp v21, v21, v21 quad_perm:[2,3,0,1] row_mask:0xf bank_mask:0xf
	s_nop 1
	v_add_f32_dpp v21, v21, v21 row_half_mirror row_mask:0xf bank_mask:0xf
	s_nop 1
	v_add_f32_dpp v21, v21, v21 row_mirror row_mask:0xf bank_mask:0xf
	v_mov_b32_e32 v49, v21
	v_mov_b32_e32 v50, v21
	s_nop 1
	v_permlane16_swap_b32_e32 v49, v50
	v_add_f32_e32 v21, v49, v50
	v_fmamk_f32 v21, v21, 0x3c000000, v100
	v_cmp_gt_f32_e32 vcc, s34, v21
	v_mul_f32_e32 v49, 0x4f800000, v21
	s_nop 0
	v_cndmask_b32_e32 v21, v21, v49, vcc
	v_sqrt_f32_e32 v49, v21
	s_nop 0
	v_add_u32_e32 v50, -1, v49
	v_fma_f32 v51, -v50, v49, v21
	v_cmp_ge_f32_e64 s[4:5], 0, v51
	v_add_u32_e32 v51, 1, v49
	s_nop 0
	v_cndmask_b32_e64 v50, v49, v50, s[4:5]
	v_fma_f32 v49, -v51, v49, v21
	v_cmp_lt_f32_e64 s[4:5], 0, v49
	s_nop 1
	v_cndmask_b32_e64 v49, v50, v51, s[4:5]
	v_mul_f32_e32 v50, 0x37800000, v49
	v_cndmask_b32_e32 v49, v49, v50, vcc
	v_cmp_class_f32_e32 vcc, v21, v101
	s_nop 1
	v_cndmask_b32_e32 v21, v49, v21, vcc
	s_nop 0
	v_div_scale_f32 v51, vcc, 1.0, v21, 1.0
	v_rcp_f32_e32 v21, v21
	v_mul_f32_e32 v49, v107, v107
	v_fmac_f32_e32 v49, v123, v123
	v_fmac_f32_e32 v49, v26, v26
	v_fmac_f32_e32 v49, v4, v4
	ds_bpermute_b32 v2, v2, v49
	v_mul_f32_e32 v28, v28, v21
	v_mul_f32_e32 v5, v5, v21
	s_waitcnt lgkmcnt(0)
	v_add_f32_e32 v2, v49, v2
	ds_bpermute_b32 v3, v3, v2
	s_waitcnt lgkmcnt(0)
	v_add_f32_e32 v2, v2, v3
	ds_bpermute_b32 v3, v20, v2
	s_waitcnt lgkmcnt(0)
	v_add_f32_e32 v2, v2, v3
	ds_bpermute_b32 v3, v47, v2
	s_waitcnt lgkmcnt(0)
	v_add_f32_e32 v2, v2, v3
	ds_bpermute_b32 v3, v48, v2
	s_waitcnt lgkmcnt(0)
	v_add_f32_e32 v2, v2, v3
	v_fmamk_f32 v2, v2, 0x3c000000, v100
	v_cmp_gt_f32_e32 vcc, s34, v2
	v_mul_f32_e32 v3, 0x4f800000, v2
	s_nop 0
	v_cndmask_b32_e32 v2, v2, v3, vcc
	v_sqrt_f32_e32 v3, v2
	s_nop 0
	v_add_u32_e32 v20, -1, v3
	v_fma_f32 v47, -v20, v3, v2
	v_cmp_ge_f32_e64 s[4:5], 0, v47
	v_add_u32_e32 v47, 1, v3
	s_nop 0
	v_cndmask_b32_e64 v20, v3, v20, s[4:5]
	v_fma_f32 v3, -v47, v3, v2
	v_cmp_lt_f32_e64 s[4:5], 0, v3
	s_nop 1
	v_cndmask_b32_e64 v3, v20, v47, s[4:5]
	v_mul_f32_e32 v20, 0x37800000, v3
	v_cndmask_b32_e32 v3, v3, v20, vcc
	v_cmp_class_f32_e32 vcc, v2, v101
	s_nop 1
	v_cndmask_b32_e32 v2, v3, v2, vcc
	s_nop 0
	v_rcp_f32_e32 v20, v2
	v_mul_f32_e32 v47, v138, v46
	v_mul_f32_e32 v26, v26, v20
	v_mul_f32_e32 v4, v4, v20
	s_waitcnt vmcnt(2) lgkmcnt(0)
	ds_write_b128 v92, v[164:167]
	s_waitcnt vmcnt(0) lgkmcnt(0)
	ds_write_b128 v92, v[170:173] offset:1088
	s_waitcnt vmcnt(13) lgkmcnt(0)
	ds_write_b128 v92, v[174:177] offset:2176
	s_waitcnt vmcnt(8) lgkmcnt(0)
	ds_write_b128 v92, v[178:181] offset:3264
	s_waitcnt vmcnt(9) lgkmcnt(0)
	ds_write_b128 v92, v[196:199] offset:4352
	s_waitcnt vmcnt(10) lgkmcnt(0)
	ds_write_b128 v92, v[200:203] offset:5440
	v_lshl_add_u64 v[2:3], v[168:169], 0, v[80:81]
	s_waitcnt vmcnt(5) lgkmcnt(0)
	ds_write_b128 v92, v[204:207] offset:6528
	global_load_dwordx4 v[48:51], v[2:3], off
	s_waitcnt vmcnt(0) lgkmcnt(0)
	ds_write_b128 v92, v[48:51] offset:7616
	s_waitcnt lgkmcnt(0)
	ds_read_u16 v3, v1
	s_waitcnt lgkmcnt(0)
	v_lshlrev_b32_e32 v3, 16, v3
	v_mul_f32_e32 v48, 0xbfb8aa3b, v3
	v_exp_f32_e32 v48, v48
	s_waitcnt vmcnt(0)
	v_mul_f32_e32 v47, v47, v232
	v_add_f32_e32 v48, 1.0, v48
	v_rcp_f32_e32 v49, v48
	s_nop 0
	v_mul_f32_e32 v3, v3, v49
	v_mul_f32_e32 v3, v47, v3
	v_cvt_pk_bf16_f32 v3, v3, v3
	ds_write_b16 v1, v3
	ds_read_u16 v3, v1 offset:272
	v_mul_f32_e32 v47, v137, v45
	v_mul_f32_e32 v47, v47, v232
	s_waitcnt lgkmcnt(0)
	v_lshlrev_b32_e32 v3, 16, v3
	v_mul_f32_e32 v48, 0xbfb8aa3b, v3
	v_exp_f32_e32 v48, v48
	s_nop 0
	v_add_f32_e32 v48, 1.0, v48
	v_rcp_f32_e32 v49, v48
	s_nop 0
	v_mul_f32_e32 v3, v3, v49
	v_mul_f32_e32 v3, v47, v3
	v_cvt_pk_bf16_f32 v3, v3, v3
	ds_write_b16 v1, v3 offset:272
	ds_read_u16 v3, v1 offset:544
	v_mul_f32_e32 v47, v136, v44
	v_mul_f32_e32 v47, v47, v232
	s_waitcnt lgkmcnt(0)
	v_lshlrev_b32_e32 v3, 16, v3
	v_mul_f32_e32 v48, 0xbfb8aa3b, v3
	v_exp_f32_e32 v48, v48
	s_nop 0
	v_add_f32_e32 v48, 1.0, v48
	v_rcp_f32_e32 v49, v48
	s_nop 0
	v_mul_f32_e32 v3, v3, v49
	v_mul_f32_e32 v3, v47, v3
	v_cvt_pk_bf16_f32 v3, v3, v3
	ds_write_b16 v1, v3 offset:544
	ds_read_u16 v3, v1 offset:816
	v_mul_f32_e32 v47, v135, v43
	v_mul_f32_e32 v47, v47, v232
	s_waitcnt lgkmcnt(0)
	v_lshlrev_b32_e32 v3, 16, v3
	v_mul_f32_e32 v48, 0xbfb8aa3b, v3
	v_exp_f32_e32 v48, v48
	s_nop 0
	v_add_f32_e32 v48, 1.0, v48
	v_rcp_f32_e32 v49, v48
	s_nop 0
	v_mul_f32_e32 v3, v3, v49
	v_mul_f32_e32 v3, v47, v3
	v_cvt_pk_bf16_f32 v3, v3, v3
	ds_write_b16 v1, v3 offset:816
	ds_read_u16 v3, v1 offset:2176
	v_mul_f32_e32 v47, v134, v42
	v_mul_f32_e32 v47, v47, v232
	s_waitcnt lgkmcnt(0)
	v_lshlrev_b32_e32 v3, 16, v3
	v_mul_f32_e32 v48, 0xbfb8aa3b, v3
	v_exp_f32_e32 v48, v48
	s_nop 0
	v_add_f32_e32 v48, 1.0, v48
	v_rcp_f32_e32 v49, v48
	s_nop 0
	v_mul_f32_e32 v3, v3, v49
	v_mul_f32_e32 v3, v47, v3
	v_cvt_pk_bf16_f32 v3, v3, v3
	ds_write_b16 v1, v3 offset:2176
	ds_read_u16 v3, v1 offset:2448
	v_mul_f32_e32 v47, v133, v41
	v_mul_f32_e32 v47, v47, v232
	s_waitcnt lgkmcnt(0)
; #define LAS __attribute__((address_space(3)))
; DI unsigned cvtpk(float lo, float hi) { f32x2 v = {lo, hi}; bf16x2_t b = __builtin_convertvector(v, bf16x2_t); return __builtin_bit_cast(unsigned, b); }
; DI float bf2f(bf16 b) { return __uint_as_float(((unsigned)b) << 16); }
; DI float siluf_(float x) { return x / (1.f + __expf(-x)); }
; DI void gla_stage3(const Ctx& c0, int layer, int unit, int cb, LAS unsigned char* lds) {
;     ...
;     for (int vb = 0; vb < 4; ++vb) { const float g = gn[32 * vb + r];
; #pragma unroll
;         for (int rg = 0; rg < 16; ++rg) { LAS bf16* e = (LAS bf16*)(R + (4 * hi) * G3_PITCH + r * 2 + ((rg & 3) + 8 * (rg >> 2)) * G3_PITCH + 64 * vb);
;             const float z = bf2f(*e);
;             *e = (bf16)(cvtpk(o[vb][rg] * rs[rg] * g * siluf_(z), 0.f) & 0xffffu); }
;         asm volatile("" ::: "memory"); }
	v_lshlrev_b32_e32 v3, 16, v3
	v_mul_f32_e32 v48, 0xbfb8aa3b, v3
	v_exp_f32_e32 v48, v48
	s_nop 0
	v_add_f32_e32 v48, 1.0, v48
	v_rcp_f32_e32 v49, v48
	s_nop 0
	v_mul_f32_e32 v3, v3, v49
	v_mul_f32_e32 v3, v47, v3
	v_cvt_pk_bf16_f32 v3, v3, v3
	ds_write_b16 v1, v3 offset:2448
	ds_read_u16 v3, v1 offset:2720
	v_mul_f32_e32 v47, v132, v40
	v_mul_f32_e32 v47, v47, v232
	s_waitcnt lgkmcnt(0)
	v_lshlrev_b32_e32 v3, 16, v3
	v_mul_f32_e32 v48, 0xbfb8aa3b, v3
	v_exp_f32_e32 v48, v48
	s_nop 0
	v_add_f32_e32 v48, 1.0, v48
	v_rcp_f32_e32 v49, v48
	s_nop 0
	v_mul_f32_e32 v3, v3, v49
	v_mul_f32_e32 v3, v47, v3
	v_cvt_pk_bf16_f32 v3, v3, v3
	ds_write_b16 v1, v3 offset:2720
	ds_read_u16 v3, v1 offset:2992
	v_mul_f32_e32 v47, v131, v35
	v_mul_f32_e32 v47, v47, v232
	s_waitcnt lgkmcnt(0)
	v_lshlrev_b32_e32 v3, 16, v3
	v_mul_f32_e32 v48, 0xbfb8aa3b, v3
	v_exp_f32_e32 v48, v48
	s_nop 0
	v_add_f32_e32 v48, 1.0, v48
	v_rcp_f32_e32 v49, v48
	s_nop 0
	v_mul_f32_e32 v3, v3, v49
	v_mul_f32_e32 v3, v47, v3
	v_cvt_pk_bf16_f32 v3, v3, v3
	ds_write_b16 v1, v3 offset:2992
	ds_read_u16 v3, v1 offset:4352
	v_mul_f32_e32 v47, v130, v31
	v_mul_f32_e32 v47, v47, v232
	s_waitcnt lgkmcnt(0)
	v_lshlrev_b32_e32 v3, 16, v3
	v_mul_f32_e32 v48, 0xbfb8aa3b, v3
	v_exp_f32_e32 v48, v48
	s_nop 0
	v_add_f32_e32 v48, 1.0, v48
	v_rcp_f32_e32 v49, v48
	s_nop 0
	v_mul_f32_e32 v3, v3, v49
	v_mul_f32_e32 v3, v47, v3
	v_cvt_pk_bf16_f32 v3, v3, v3
	ds_write_b16 v1, v3 offset:4352
	ds_read_u16 v3, v1 offset:4624
	v_mul_f32_e32 v47, v129, v27
	v_mul_f32_e32 v47, v47, v232
	s_waitcnt lgkmcnt(0)
	v_lshlrev_b32_e32 v3, 16, v3
	v_mul_f32_e32 v48, 0xbfb8aa3b, v3
	v_exp_f32_e32 v48, v48
	s_nop 0
	v_add_f32_e32 v48, 1.0, v48
	v_rcp_f32_e32 v49, v48
	s_nop 0
	v_mul_f32_e32 v3, v3, v49
	v_mul_f32_e32 v3, v47, v3
	v_cvt_pk_bf16_f32 v3, v3, v3
	ds_write_b16 v1, v3 offset:4624
	ds_read_u16 v3, v1 offset:4896
	v_mul_f32_e32 v47, v128, v25
	v_mul_f32_e32 v47, v47, v232
	s_waitcnt lgkmcnt(0)
	v_lshlrev_b32_e32 v3, 16, v3
	v_mul_f32_e32 v48, 0xbfb8aa3b, v3
	v_exp_f32_e32 v48, v48
	s_nop 0
	v_add_f32_e32 v48, 1.0, v48
	v_rcp_f32_e32 v49, v48
	s_nop 0
	v_mul_f32_e32 v3, v3, v49
	v_mul_f32_e32 v3, v47, v3
	v_cvt_pk_bf16_f32 v3, v3, v3
	ds_write_b16 v1, v3 offset:4896
	ds_read_u16 v3, v1 offset:5168
	v_mul_f32_e32 v47, v127, v24
	v_mul_f32_e32 v47, v47, v232
	s_waitcnt lgkmcnt(0)
	v_lshlrev_b32_e32 v3, 16, v3
	v_mul_f32_e32 v48, 0xbfb8aa3b, v3
	v_exp_f32_e32 v48, v48
	s_nop 0
	v_add_f32_e32 v48, 1.0, v48
	v_rcp_f32_e32 v49, v48
	s_nop 0
	v_mul_f32_e32 v3, v3, v49
	v_mul_f32_e32 v3, v47, v3
	v_cvt_pk_bf16_f32 v3, v3, v3
	ds_write_b16 v1, v3 offset:5168
	ds_read_u16 v3, v1 offset:6528
	v_mul_f32_e32 v47, v126, v23
	v_mul_f32_e32 v47, v47, v232
	s_waitcnt lgkmcnt(0)
	v_lshlrev_b32_e32 v3, 16, v3
	v_mul_f32_e32 v48, 0xbfb8aa3b, v3
	v_exp_f32_e32 v48, v48
	s_nop 0
	v_add_f32_e32 v48, 1.0, v48
	v_rcp_f32_e32 v49, v48
	s_nop 0
	v_mul_f32_e32 v3, v3, v49
	v_mul_f32_e32 v3, v47, v3
	v_cvt_pk_bf16_f32 v3, v3, v3
	ds_write_b16 v1, v3 offset:6528
	ds_read_u16 v3, v1 offset:6800
	v_mul_f32_e32 v47, v125, v22
	v_mul_f32_e32 v47, v47, v232
	s_waitcnt lgkmcnt(0)
	v_lshlrev_b32_e32 v3, 16, v3
	v_mul_f32_e32 v48, 0xbfb8aa3b, v3
	v_exp_f32_e32 v48, v48
	s_nop 0
	v_add_f32_e32 v48, 1.0, v48
	v_rcp_f32_e32 v49, v48
	s_nop 0
	v_mul_f32_e32 v3, v3, v49
	v_mul_f32_e32 v3, v47, v3
	v_cvt_pk_bf16_f32 v3, v3, v3
	ds_write_b16 v1, v3 offset:6800
	ds_read_u16 v3, v1 offset:7072
	v_mul_f32_e32 v47, v124, v21
	v_mul_f32_e32 v47, v47, v232
	s_waitcnt lgkmcnt(0)
	v_lshlrev_b32_e32 v3, 16, v3
	v_mul_f32_e32 v48, 0xbfb8aa3b, v3
	v_exp_f32_e32 v48, v48
	s_nop 0
	v_add_f32_e32 v48, 1.0, v48
	v_rcp_f32_e32 v49, v48
	s_nop 0
	v_mul_f32_e32 v3, v3, v49
	v_mul_f32_e32 v3, v47, v3
	v_cvt_pk_bf16_f32 v3, v3, v3
	ds_write_b16 v1, v3 offset:7072
	ds_read_u16 v3, v1 offset:7344
	v_mul_f32_e32 v47, v123, v20
	v_mul_f32_e32 v2, v47, v232
	s_waitcnt lgkmcnt(0)
	v_lshlrev_b32_e32 v3, 16, v3
	v_mul_f32_e32 v47, 0xbfb8aa3b, v3
	v_exp_f32_e32 v47, v47
	s_nop 0
	v_add_f32_e32 v47, 1.0, v47
	v_div_scale_f32 v48, s[0:1], v47, v47, v3
	s_nop 0
	v_rcp_f32_e32 v48, v47
	s_nop 0
	v_mul_f32_e32 v3, v3, v48
	v_mul_f32_e32 v2, v2, v3
	v_cvt_pk_bf16_f32 v2, v2, s0
	ds_write_b16 v1, v2 offset:7344
	ds_read_u16 v3, v1 offset:64
	v_mul_f32_e32 v47, v122, v46
	s_waitcnt lgkmcnt(0)
	v_lshlrev_b32_e32 v3, 16, v3
	v_mul_f32_e32 v48, 0xbfb8aa3b, v3
	v_exp_f32_e32 v48, v48
	s_waitcnt vmcnt(0)
	v_mul_f32_e32 v47, v47, v234
	v_add_f32_e32 v48, 1.0, v48
	v_rcp_f32_e32 v49, v48
	s_nop 0
	v_mul_f32_e32 v3, v3, v49
	v_mul_f32_e32 v3, v47, v3
	v_cvt_pk_bf16_f32 v3, v3, v3
	ds_write_b16 v1, v3 offset:64
	ds_read_u16 v3, v1 offset:336
	v_mul_f32_e32 v47, v121, v45
	v_mul_f32_e32 v47, v47, v234
	s_waitcnt lgkmcnt(0)
	v_lshlrev_b32_e32 v3, 16, v3
	v_mul_f32_e32 v48, 0xbfb8aa3b, v3
	v_exp_f32_e32 v48, v48
	s_nop 0
	v_add_f32_e32 v48, 1.0, v48
	v_rcp_f32_e32 v49, v48
	s_nop 0
	v_mul_f32_e32 v3, v3, v49
	v_mul_f32_e32 v3, v47, v3
	v_cvt_pk_bf16_f32 v3, v3, v3
	ds_write_b16 v1, v3 offset:336
	ds_read_u16 v3, v1 offset:608
	v_mul_f32_e32 v47, v120, v44
	v_mul_f32_e32 v47, v47, v234
	s_waitcnt lgkmcnt(0)
	v_lshlrev_b32_e32 v3, 16, v3
	v_mul_f32_e32 v48, 0xbfb8aa3b, v3
	v_exp_f32_e32 v48, v48
	s_nop 0
	v_add_f32_e32 v48, 1.0, v48
	v_rcp_f32_e32 v49, v48
	s_nop 0
	v_mul_f32_e32 v3, v3, v49
	v_mul_f32_e32 v3, v47, v3
	v_cvt_pk_bf16_f32 v3, v3, v3
	ds_write_b16 v1, v3 offset:608
	ds_read_u16 v3, v1 offset:880
	v_mul_f32_e32 v47, v119, v43
	v_mul_f32_e32 v47, v47, v234
	s_waitcnt lgkmcnt(0)
; #define LAS __attribute__((address_space(3)))
; DI unsigned cvtpk(float lo, float hi) { f32x2 v = {lo, hi}; bf16x2_t b = __builtin_convertvector(v, bf16x2_t); return __builtin_bit_cast(unsigned, b); }
; DI float bf2f(bf16 b) { return __uint_as_float(((unsigned)b) << 16); }
; DI float siluf_(float x) { return x / (1.f + __expf(-x)); }
; DI void gla_stage3(const Ctx& c0, int layer, int unit, int cb, LAS unsigned char* lds) {
;     ...
;     for (int vb = 0; vb < 4; ++vb) { const float g = gn[32 * vb + r];
; #pragma unroll
;         for (int rg = 0; rg < 16; ++rg) { LAS bf16* e = (LAS bf16*)(R + (4 * hi) * G3_PITCH + r * 2 + ((rg & 3) + 8 * (rg >> 2)) * G3_PITCH + 64 * vb);
;             const float z = bf2f(*e);
;             *e = (bf16)(cvtpk(o[vb][rg] * rs[rg] * g * siluf_(z), 0.f) & 0xffffu); }
;         asm volatile("" ::: "memory"); }
	v_lshlrev_b32_e32 v3, 16, v3
	v_mul_f32_e32 v48, 0xbfb8aa3b, v3
	v_exp_f32_e32 v48, v48
	s_nop 0
	v_add_f32_e32 v48, 1.0, v48
	v_rcp_f32_e32 v49, v48
	s_nop 0
	v_mul_f32_e32 v3, v3, v49
	v_mul_f32_e32 v3, v47, v3
	v_cvt_pk_bf16_f32 v3, v3, v3
	ds_write_b16 v1, v3 offset:880
	ds_read_u16 v3, v1 offset:2240
	v_mul_f32_e32 v47, v118, v42
	v_mul_f32_e32 v47, v47, v234
	s_waitcnt lgkmcnt(0)
	v_lshlrev_b32_e32 v3, 16, v3
	v_mul_f32_e32 v48, 0xbfb8aa3b, v3
	v_exp_f32_e32 v48, v48
	s_nop 0
	v_add_f32_e32 v48, 1.0, v48
	v_rcp_f32_e32 v49, v48
	s_nop 0
	v_mul_f32_e32 v3, v3, v49
	v_mul_f32_e32 v3, v47, v3
	v_cvt_pk_bf16_f32 v3, v3, v3
	ds_write_b16 v1, v3 offset:2240
	ds_read_u16 v3, v1 offset:2512
	v_mul_f32_e32 v47, v117, v41
	v_mul_f32_e32 v47, v47, v234
	s_waitcnt lgkmcnt(0)
	v_lshlrev_b32_e32 v3, 16, v3
	v_mul_f32_e32 v48, 0xbfb8aa3b, v3
	v_exp_f32_e32 v48, v48
	s_nop 0
	v_add_f32_e32 v48, 1.0, v48
	v_rcp_f32_e32 v49, v48
	s_nop 0
	v_mul_f32_e32 v3, v3, v49
	v_mul_f32_e32 v3, v47, v3
	v_cvt_pk_bf16_f32 v3, v3, v3
	ds_write_b16 v1, v3 offset:2512
	ds_read_u16 v3, v1 offset:2784
	v_mul_f32_e32 v47, v116, v40
	v_mul_f32_e32 v47, v47, v234
	s_waitcnt lgkmcnt(0)
	v_lshlrev_b32_e32 v3, 16, v3
	v_mul_f32_e32 v48, 0xbfb8aa3b, v3
	v_exp_f32_e32 v48, v48
	s_nop 0
	v_add_f32_e32 v48, 1.0, v48
	v_rcp_f32_e32 v49, v48
	s_nop 0
	v_mul_f32_e32 v3, v3, v49
	v_mul_f32_e32 v3, v47, v3
	v_cvt_pk_bf16_f32 v3, v3, v3
	ds_write_b16 v1, v3 offset:2784
	ds_read_u16 v3, v1 offset:3056
	v_mul_f32_e32 v47, v115, v35
	v_mul_f32_e32 v47, v47, v234
	s_waitcnt lgkmcnt(0)
	v_lshlrev_b32_e32 v3, 16, v3
	v_mul_f32_e32 v48, 0xbfb8aa3b, v3
	v_exp_f32_e32 v48, v48
	s_nop 0
	v_add_f32_e32 v48, 1.0, v48
	v_rcp_f32_e32 v49, v48
	s_nop 0
	v_mul_f32_e32 v3, v3, v49
	v_mul_f32_e32 v3, v47, v3
	v_cvt_pk_bf16_f32 v3, v3, v3
	ds_write_b16 v1, v3 offset:3056
	ds_read_u16 v3, v1 offset:4416
	v_mul_f32_e32 v47, v114, v31
	v_mul_f32_e32 v47, v47, v234
	s_waitcnt lgkmcnt(0)
	v_lshlrev_b32_e32 v3, 16, v3
	v_mul_f32_e32 v48, 0xbfb8aa3b, v3
	v_exp_f32_e32 v48, v48
	s_nop 0
	v_add_f32_e32 v48, 1.0, v48
	v_rcp_f32_e32 v49, v48
	s_nop 0
	v_mul_f32_e32 v3, v3, v49
	v_mul_f32_e32 v3, v47, v3
	v_cvt_pk_bf16_f32 v3, v3, v3
	ds_write_b16 v1, v3 offset:4416
	ds_read_u16 v3, v1 offset:4688
	v_mul_f32_e32 v47, v113, v27
	v_mul_f32_e32 v47, v47, v234
	s_waitcnt lgkmcnt(0)
	v_lshlrev_b32_e32 v3, 16, v3
	v_mul_f32_e32 v48, 0xbfb8aa3b, v3
	v_exp_f32_e32 v48, v48
	s_nop 0
	v_add_f32_e32 v48, 1.0, v48
	v_rcp_f32_e32 v49, v48
	s_nop 0
	v_mul_f32_e32 v3, v3, v49
	v_mul_f32_e32 v3, v47, v3
	v_cvt_pk_bf16_f32 v3, v3, v3
	ds_write_b16 v1, v3 offset:4688
	ds_read_u16 v3, v1 offset:4960
	v_mul_f32_e32 v47, v112, v25
	v_mul_f32_e32 v47, v47, v234
	s_waitcnt lgkmcnt(0)
	v_lshlrev_b32_e32 v3, 16, v3
	v_mul_f32_e32 v48, 0xbfb8aa3b, v3
	v_exp_f32_e32 v48, v48
	s_nop 0
	v_add_f32_e32 v48, 1.0, v48
	v_rcp_f32_e32 v49, v48
	s_nop 0
	v_mul_f32_e32 v3, v3, v49
	v_mul_f32_e32 v3, v47, v3
	v_cvt_pk_bf16_f32 v3, v3, v3
	ds_write_b16 v1, v3 offset:4960
	ds_read_u16 v3, v1 offset:5232
	v_mul_f32_e32 v47, v111, v24
	v_mul_f32_e32 v47, v47, v234
	s_waitcnt lgkmcnt(0)
	v_lshlrev_b32_e32 v3, 16, v3
	v_mul_f32_e32 v48, 0xbfb8aa3b, v3
	v_exp_f32_e32 v48, v48
	s_nop 0
	v_add_f32_e32 v48, 1.0, v48
	v_rcp_f32_e32 v49, v48
	s_nop 0
	v_mul_f32_e32 v3, v3, v49
	v_mul_f32_e32 v3, v47, v3
	v_cvt_pk_bf16_f32 v3, v3, v3
	ds_write_b16 v1, v3 offset:5232
	ds_read_u16 v3, v1 offset:6592
	v_mul_f32_e32 v47, v110, v23
	v_mul_f32_e32 v47, v47, v234
	s_waitcnt lgkmcnt(0)
	v_lshlrev_b32_e32 v3, 16, v3
	v_mul_f32_e32 v48, 0xbfb8aa3b, v3
	v_exp_f32_e32 v48, v48
	s_nop 0
	v_add_f32_e32 v48, 1.0, v48
	v_rcp_f32_e32 v49, v48
	s_nop 0
	v_mul_f32_e32 v3, v3, v49
	v_mul_f32_e32 v3, v47, v3
	v_cvt_pk_bf16_f32 v3, v3, v3
	ds_write_b16 v1, v3 offset:6592
	ds_read_u16 v3, v1 offset:6864
	v_mul_f32_e32 v47, v109, v22
	v_mul_f32_e32 v47, v47, v234
	s_waitcnt lgkmcnt(0)
	v_lshlrev_b32_e32 v3, 16, v3
	v_mul_f32_e32 v48, 0xbfb8aa3b, v3
	v_exp_f32_e32 v48, v48
	s_nop 0
	v_add_f32_e32 v48, 1.0, v48
	v_rcp_f32_e32 v49, v48
	s_nop 0
	v_mul_f32_e32 v3, v3, v49
	v_mul_f32_e32 v3, v47, v3
	v_cvt_pk_bf16_f32 v3, v3, v3
	ds_write_b16 v1, v3 offset:6864
	ds_read_u16 v3, v1 offset:7136
	v_mul_f32_e32 v47, v108, v21
	v_mul_f32_e32 v47, v47, v234
	s_waitcnt lgkmcnt(0)
	v_lshlrev_b32_e32 v3, 16, v3
	v_mul_f32_e32 v48, 0xbfb8aa3b, v3
	v_exp_f32_e32 v48, v48
	s_nop 0
	v_add_f32_e32 v48, 1.0, v48
	v_rcp_f32_e32 v49, v48
	s_nop 0
	v_mul_f32_e32 v3, v3, v49
	v_mul_f32_e32 v3, v47, v3
	v_cvt_pk_bf16_f32 v3, v3, v3
	ds_write_b16 v1, v3 offset:7136
	ds_read_u16 v3, v1 offset:7408
	v_mul_f32_e32 v47, v107, v20
	v_mul_f32_e32 v2, v47, v234
	s_waitcnt lgkmcnt(0)
	v_lshlrev_b32_e32 v3, 16, v3
	v_mul_f32_e32 v47, 0xbfb8aa3b, v3
	v_exp_f32_e32 v47, v47
	s_nop 0
	v_add_f32_e32 v47, 1.0, v47
	v_div_scale_f32 v48, s[0:1], v47, v47, v3
	s_nop 0
	v_rcp_f32_e32 v48, v47
	s_nop 0
	v_mul_f32_e32 v3, v3, v48
	v_mul_f32_e32 v2, v2, v3
	v_cvt_pk_bf16_f32 v2, v2, s0
	ds_write_b16 v1, v2 offset:7408
	ds_read_u16 v3, v1 offset:128
	v_mul_f32_e32 v47, v106, v46
	s_waitcnt lgkmcnt(0)
	v_lshlrev_b32_e32 v3, 16, v3
	v_mul_f32_e32 v48, 0xbfb8aa3b, v3
	v_exp_f32_e32 v48, v48
	s_waitcnt vmcnt(0)
	v_mul_f32_e32 v47, v47, v236
	v_add_f32_e32 v48, 1.0, v48
	v_div_scale_f32 v49, s[0:1], v48, v48, v3
	v_mul_f32_e32 v39, v39, v236
	v_mul_f32_e32 v38, v38, v236
	v_mul_f32_e32 v37, v37, v236
	v_rcp_f32_e32 v49, v48
	s_nop 0
	v_mul_f32_e32 v3, v3, v49
	v_mul_f32_e32 v3, v47, v3
	v_cvt_pk_bf16_f32 v3, v3, s0
	ds_write_b16 v1, v3 offset:128
	ds_read_u16 v3, v1 offset:400
	v_mul_f32_e32 v47, v105, v45
	v_mul_f32_e32 v47, v47, v236
	v_mul_f32_e32 v36, v36, v236
	v_mul_f32_e32 v34, v34, v236
	s_waitcnt lgkmcnt(0)
; #define LAS __attribute__((address_space(3)))
; DI unsigned cvtpk(float lo, float hi) { f32x2 v = {lo, hi}; bf16x2_t b = __builtin_convertvector(v, bf16x2_t); return __builtin_bit_cast(unsigned, b); }
; DI float bf2f(bf16 b) { return __uint_as_float(((unsigned)b) << 16); }
; DI float siluf_(float x) { return x / (1.f + __expf(-x)); }
; DI void gla_stage3(const Ctx& c0, int layer, int unit, int cb, LAS unsigned char* lds) {
;     ...
;     for (int vb = 0; vb < 4; ++vb) { const float g = gn[32 * vb + r];
; #pragma unroll
;         for (int rg = 0; rg < 16; ++rg) { LAS bf16* e = (LAS bf16*)(R + (4 * hi) * G3_PITCH + r * 2 + ((rg & 3) + 8 * (rg >> 2)) * G3_PITCH + 64 * vb);
;             const float z = bf2f(*e);
;             *e = (bf16)(cvtpk(o[vb][rg] * rs[rg] * g * siluf_(z), 0.f) & 0xffffu); }
;         asm volatile("" ::: "memory"); }
	v_lshlrev_b32_e32 v3, 16, v3
	v_mul_f32_e32 v48, 0xbfb8aa3b, v3
	v_exp_f32_e32 v48, v48
	v_mul_f32_e32 v33, v33, v236
	v_mul_f32_e32 v32, v32, v236
	v_mul_f32_e32 v30, v30, v236
	v_add_f32_e32 v48, 1.0, v48
	v_div_scale_f32 v49, s[0:1], v48, v48, v3
	v_mul_f32_e32 v29, v29, v236
	v_mul_f32_e32 v28, v28, v236
	v_rcp_f32_e32 v49, v48
	s_nop 0
	v_mul_f32_e32 v3, v3, v49
	v_mul_f32_e32 v3, v47, v3
	v_cvt_pk_bf16_f32 v3, v3, s0
	ds_write_b16 v1, v3 offset:400
	ds_read_u16 v3, v1 offset:672
	v_mul_f32_e32 v47, v104, v44
	v_mul_f32_e32 v47, v47, v236
	s_waitcnt lgkmcnt(0)
	v_lshlrev_b32_e32 v3, 16, v3
	v_mul_f32_e32 v48, 0xbfb8aa3b, v3
	v_exp_f32_e32 v48, v48
	s_nop 0
	v_add_f32_e32 v48, 1.0, v48
	v_rcp_f32_e32 v49, v48
	s_nop 0
	v_mul_f32_e32 v3, v3, v49
	v_mul_f32_e32 v3, v47, v3
	v_cvt_pk_bf16_f32 v3, v3, v3
	ds_write_b16 v1, v3 offset:672
	ds_read_u16 v3, v1 offset:944
	v_mul_f32_e32 v47, v103, v43
	v_mul_f32_e32 v47, v47, v236
	s_waitcnt lgkmcnt(0)
	v_lshlrev_b32_e32 v3, 16, v3
	v_mul_f32_e32 v48, 0xbfb8aa3b, v3
	v_exp_f32_e32 v48, v48
	s_nop 0
	v_add_f32_e32 v48, 1.0, v48
	v_rcp_f32_e32 v49, v48
	s_nop 0
	v_mul_f32_e32 v3, v3, v49
	v_mul_f32_e32 v3, v47, v3
	v_cvt_pk_bf16_f32 v3, v3, v3
	ds_write_b16 v1, v3 offset:944
	ds_read_u16 v3, v1 offset:2304
	v_mul_f32_e32 v47, v102, v42
	v_mul_f32_e32 v47, v47, v236
	v_mul_f32_e32 v2, v26, v236
	s_waitcnt lgkmcnt(0)
	v_lshlrev_b32_e32 v3, 16, v3
	v_mul_f32_e32 v48, 0xbfb8aa3b, v3
	v_exp_f32_e32 v48, v48
	s_nop 0
	v_add_f32_e32 v48, 1.0, v48
	v_rcp_f32_e32 v49, v48
	s_nop 0
	v_mul_f32_e32 v3, v3, v49
	v_mul_f32_e32 v3, v47, v3
	v_cvt_pk_bf16_f32 v3, v3, v3
	ds_write_b16 v1, v3 offset:2304
	ds_read_u16 v3, v1 offset:2576
	s_waitcnt lgkmcnt(0)
	v_lshlrev_b32_e32 v3, 16, v3
	v_mul_f32_e32 v47, 0xbfb8aa3b, v3
	v_exp_f32_e32 v47, v47
	s_nop 0
	v_add_f32_e32 v47, 1.0, v47
	v_rcp_f32_e32 v48, v47
	s_nop 0
	v_mul_f32_e32 v3, v3, v48
	v_mul_f32_e32 v3, v39, v3
	v_cvt_pk_bf16_f32 v3, v3, v3
	ds_write_b16 v1, v3 offset:2576
	ds_read_u16 v3, v1 offset:2848
	s_waitcnt lgkmcnt(0)
	v_lshlrev_b32_e32 v3, 16, v3
	v_mul_f32_e32 v39, 0xbfb8aa3b, v3
	v_exp_f32_e32 v39, v39
	s_nop 0
	v_add_f32_e32 v39, 1.0, v39
	v_rcp_f32_e32 v47, v39
	s_nop 0
	v_mul_f32_e32 v3, v3, v47
	v_mul_f32_e32 v3, v38, v3
	v_cvt_pk_bf16_f32 v3, v3, v3
	ds_write_b16 v1, v3 offset:2848
	ds_read_u16 v3, v1 offset:3120
	s_waitcnt lgkmcnt(0)
	v_lshlrev_b32_e32 v3, 16, v3
	v_mul_f32_e32 v38, 0xbfb8aa3b, v3
	v_exp_f32_e32 v38, v38
	s_nop 0
	v_add_f32_e32 v38, 1.0, v38
	v_rcp_f32_e32 v39, v38
	s_nop 0
	v_mul_f32_e32 v3, v3, v39
	v_mul_f32_e32 v3, v37, v3
	v_cvt_pk_bf16_f32 v3, v3, v3
	ds_write_b16 v1, v3 offset:3120
	ds_read_u16 v3, v1 offset:4480
	s_waitcnt lgkmcnt(0)
	v_lshlrev_b32_e32 v3, 16, v3
	v_mul_f32_e32 v37, 0xbfb8aa3b, v3
	v_exp_f32_e32 v37, v37
	s_nop 0
	v_add_f32_e32 v37, 1.0, v37
	v_rcp_f32_e32 v38, v37
	s_nop 0
	v_mul_f32_e32 v3, v3, v38
	v_mul_f32_e32 v3, v36, v3
	v_cvt_pk_bf16_f32 v3, v3, v3
	ds_write_b16 v1, v3 offset:4480
	ds_read_u16 v3, v1 offset:4752
	s_waitcnt lgkmcnt(0)
	v_lshlrev_b32_e32 v3, 16, v3
	v_mul_f32_e32 v36, 0xbfb8aa3b, v3
	v_exp_f32_e32 v36, v36
	s_nop 0
	v_add_f32_e32 v36, 1.0, v36
	v_rcp_f32_e32 v37, v36
	s_nop 0
	v_mul_f32_e32 v3, v3, v37
	v_mul_f32_e32 v3, v34, v3
	v_cvt_pk_bf16_f32 v3, v3, v3
	ds_write_b16 v1, v3 offset:4752
	ds_read_u16 v3, v1 offset:5024
	s_waitcnt lgkmcnt(0)
	v_lshlrev_b32_e32 v3, 16, v3
	v_mul_f32_e32 v34, 0xbfb8aa3b, v3
	v_exp_f32_e32 v34, v34
	s_nop 0
	v_add_f32_e32 v34, 1.0, v34
	v_rcp_f32_e32 v36, v34
	s_nop 0
	v_mul_f32_e32 v3, v3, v36
	v_mul_f32_e32 v3, v33, v3
	v_cvt_pk_bf16_f32 v3, v3, v3
	ds_write_b16 v1, v3 offset:5024
	ds_read_u16 v3, v1 offset:5296
	s_waitcnt lgkmcnt(0)
	v_lshlrev_b32_e32 v3, 16, v3
	v_mul_f32_e32 v33, 0xbfb8aa3b, v3
	v_exp_f32_e32 v33, v33
	s_nop 0
	v_add_f32_e32 v33, 1.0, v33
	v_rcp_f32_e32 v34, v33
	s_nop 0
	v_mul_f32_e32 v3, v3, v34
	v_mul_f32_e32 v3, v32, v3
	v_cvt_pk_bf16_f32 v3, v3, v3
	ds_write_b16 v1, v3 offset:5296
	ds_read_u16 v3, v1 offset:6656
	s_waitcnt lgkmcnt(0)
	v_lshlrev_b32_e32 v3, 16, v3
	v_mul_f32_e32 v32, 0xbfb8aa3b, v3
	v_exp_f32_e32 v32, v32
	s_nop 0
	v_add_f32_e32 v32, 1.0, v32
	v_rcp_f32_e32 v33, v32
	s_nop 0
	v_mul_f32_e32 v3, v3, v33
	v_mul_f32_e32 v3, v30, v3
	v_cvt_pk_bf16_f32 v3, v3, v3
	ds_write_b16 v1, v3 offset:6656
	ds_read_u16 v3, v1 offset:6928
	s_waitcnt lgkmcnt(0)
	v_lshlrev_b32_e32 v3, 16, v3
	v_mul_f32_e32 v30, 0xbfb8aa3b, v3
	v_exp_f32_e32 v30, v30
	s_nop 0
	v_add_f32_e32 v30, 1.0, v30
	v_rcp_f32_e32 v32, v30
	s_nop 0
	v_mul_f32_e32 v3, v3, v32
	v_mul_f32_e32 v3, v29, v3
	v_cvt_pk_bf16_f32 v3, v3, v3
	ds_write_b16 v1, v3 offset:6928
	ds_read_u16 v3, v1 offset:7200
	s_waitcnt lgkmcnt(0)
	v_lshlrev_b32_e32 v3, 16, v3
	v_mul_f32_e32 v29, 0xbfb8aa3b, v3
	v_exp_f32_e32 v29, v29
	s_nop 0
	v_add_f32_e32 v29, 1.0, v29
	v_rcp_f32_e32 v30, v29
	s_nop 0
	v_mul_f32_e32 v3, v3, v30
	v_mul_f32_e32 v3, v28, v3
	v_cvt_pk_bf16_f32 v3, v3, v3
	ds_write_b16 v1, v3 offset:7200
	ds_read_u16 v3, v1 offset:7472
	s_waitcnt lgkmcnt(0)
	v_lshlrev_b32_e32 v3, 16, v3
	v_mul_f32_e32 v26, 0xbfb8aa3b, v3
	v_exp_f32_e32 v26, v26
	s_nop 0
	v_add_f32_e32 v26, 1.0, v26
	v_div_scale_f32 v28, s[0:1], v26, v26, v3
	s_nop 0
	v_rcp_f32_e32 v28, v26
	s_nop 0
	v_mul_f32_e32 v3, v3, v28
	v_mul_f32_e32 v2, v2, v3
	v_cvt_pk_bf16_f32 v2, v2, s0
	ds_write_b16 v1, v2 offset:7472
	ds_read_u16 v3, v1 offset:192
	s_waitcnt lgkmcnt(0)
	v_lshlrev_b32_e32 v3, 16, v3
	v_mul_f32_e32 v26, 0xbfb8aa3b, v3
	v_exp_f32_e32 v26, v26
	s_waitcnt vmcnt(31)
; #define LAS __attribute__((address_space(3)))
; #define LDS_WAIT() asm volatile("s_waitcnt lgkmcnt(0)" ::: "memory")
; DI unsigned cvtpk(float lo, float hi) { f32x2 v = {lo, hi}; bf16x2_t b = __builtin_convertvector(v, bf16x2_t); return __builtin_bit_cast(unsigned, b); }
; DI float bf2f(bf16 b) { return __uint_as_float(((unsigned)b) << 16); }
; DI float siluf_(float x) { return x / (1.f + __expf(-x)); }
; DI void g3_tile_out(bf16* g, const LAS unsigned char* R, int lane) {
;     LDS_WAIT();
; #pragma unroll
;     for (int it = 0; it < 8; ++it) { const int row = 4 * it + (lane >> 4), ch = lane & 15;
;         *(u32x4*)(g + (size_t)row * 512 + ch * 8) = *(const LAS u32x4*)(R + row * G3_PITCH + ch * 16); }
;     LDS_WAIT();
; DI void gla_stage3(const Ctx& c0, int layer, int unit, int cb, LAS unsigned char* lds) {
;     ...
;     for (int vb = 0; vb < 4; ++vb) { const float g = gn[32 * vb + r];
; #pragma unroll
;         for (int rg = 0; rg < 16; ++rg) { LAS bf16* e = (LAS bf16*)(R + (4 * hi) * G3_PITCH + r * 2 + ((rg & 3) + 8 * (rg >> 2)) * G3_PITCH + 64 * vb);
;             const float z = bf2f(*e);
;             *e = (bf16)(cvtpk(o[vb][rg] * rs[rg] * g * siluf_(z), 0.f) & 0xffffu); }
;         asm volatile("" ::: "memory"); }
;     g3_tile_out((bf16*)(c.ws + O_OGLA) + row0 * 512 + h * 128, R, lane);
	v_mul_f32_e32 v19, v19, v238
	v_add_f32_e32 v26, 1.0, v26
	v_div_scale_f32 v28, s[0:1], v26, v26, v3
	v_mul_f32_e32 v18, v18, v238
	v_mul_f32_e32 v17, v17, v238
	v_mul_f32_e32 v16, v16, v238
	v_rcp_f32_e32 v28, v26
	s_nop 0
	v_mul_f32_e32 v3, v3, v28
	v_mul_f32_e32 v3, v19, v3
	v_cvt_pk_bf16_f32 v3, v3, s0
	ds_write_b16 v1, v3 offset:192
	ds_read_u16 v3, v1 offset:464
	v_mul_f32_e32 v15, v15, v238
	v_mul_f32_e32 v14, v14, v238
	v_mul_f32_e32 v13, v13, v238
	v_mul_f32_e32 v12, v12, v238
	s_waitcnt lgkmcnt(0)
	v_lshlrev_b32_e32 v3, 16, v3
	v_mul_f32_e32 v19, 0xbfb8aa3b, v3
	v_exp_f32_e32 v19, v19
	v_mul_f32_e32 v11, v11, v238
	v_mul_f32_e32 v10, v10, v238
	v_mul_f32_e32 v9, v9, v238
	v_add_f32_e32 v19, 1.0, v19
	v_div_scale_f32 v26, s[0:1], v19, v19, v3
	v_mul_f32_e32 v8, v8, v238
	v_mul_f32_e32 v7, v7, v238
	v_mul_f32_e32 v6, v6, v238
	v_rcp_f32_e32 v26, v19
	s_nop 0
	v_mul_f32_e32 v3, v3, v26
	v_mul_f32_e32 v3, v18, v3
	v_cvt_pk_bf16_f32 v3, v3, s0
	ds_write_b16 v1, v3 offset:464
	ds_read_u16 v3, v1 offset:736
	v_mul_f32_e32 v5, v5, v238
	v_mul_f32_e32 v2, v4, v238
	s_waitcnt lgkmcnt(0)
	v_lshlrev_b32_e32 v3, 16, v3
	v_mul_f32_e32 v18, 0xbfb8aa3b, v3
	v_exp_f32_e32 v18, v18
	s_nop 0
	v_add_f32_e32 v18, 1.0, v18
	v_rcp_f32_e32 v19, v18
	s_nop 0
	v_mul_f32_e32 v3, v3, v19
	v_mul_f32_e32 v3, v17, v3
	v_cvt_pk_bf16_f32 v3, v3, v3
	ds_write_b16 v1, v3 offset:736
	ds_read_u16 v3, v1 offset:1008
	s_waitcnt lgkmcnt(0)
	v_lshlrev_b32_e32 v3, 16, v3
	v_mul_f32_e32 v17, 0xbfb8aa3b, v3
	v_exp_f32_e32 v17, v17
	s_nop 0
	v_add_f32_e32 v17, 1.0, v17
	v_rcp_f32_e32 v18, v17
	s_nop 0
	v_mul_f32_e32 v3, v3, v18
	v_mul_f32_e32 v3, v16, v3
	v_cvt_pk_bf16_f32 v3, v3, v3
	ds_write_b16 v1, v3 offset:1008
	ds_read_u16 v3, v1 offset:2368
	s_waitcnt lgkmcnt(0)
	v_lshlrev_b32_e32 v3, 16, v3
	v_mul_f32_e32 v16, 0xbfb8aa3b, v3
	v_exp_f32_e32 v16, v16
	s_nop 0
	v_add_f32_e32 v16, 1.0, v16
	v_rcp_f32_e32 v17, v16
	s_nop 0
	v_mul_f32_e32 v3, v3, v17
	v_mul_f32_e32 v3, v15, v3
	v_cvt_pk_bf16_f32 v3, v3, v3
	ds_write_b16 v1, v3 offset:2368
	ds_read_u16 v3, v1 offset:2640
	s_waitcnt lgkmcnt(0)
	v_lshlrev_b32_e32 v3, 16, v3
	v_mul_f32_e32 v15, 0xbfb8aa3b, v3
	v_exp_f32_e32 v15, v15
	s_nop 0
	v_add_f32_e32 v15, 1.0, v15
	v_rcp_f32_e32 v16, v15
	s_nop 0
	v_mul_f32_e32 v3, v3, v16
	v_mul_f32_e32 v3, v14, v3
	v_cvt_pk_bf16_f32 v3, v3, v3
	ds_write_b16 v1, v3 offset:2640
	ds_read_u16 v3, v1 offset:2912
	s_waitcnt lgkmcnt(0)
	v_lshlrev_b32_e32 v3, 16, v3
	v_mul_f32_e32 v14, 0xbfb8aa3b, v3
	v_exp_f32_e32 v14, v14
	s_nop 0
	v_add_f32_e32 v14, 1.0, v14
	v_rcp_f32_e32 v15, v14
	s_nop 0
	v_mul_f32_e32 v3, v3, v15
	v_mul_f32_e32 v3, v13, v3
	v_cvt_pk_bf16_f32 v3, v3, v3
	ds_write_b16 v1, v3 offset:2912
	ds_read_u16 v3, v1 offset:3184
	s_waitcnt lgkmcnt(0)
	v_lshlrev_b32_e32 v3, 16, v3
	v_mul_f32_e32 v13, 0xbfb8aa3b, v3
	v_exp_f32_e32 v13, v13
	s_nop 0
	v_add_f32_e32 v13, 1.0, v13
	v_rcp_f32_e32 v14, v13
	s_nop 0
	v_mul_f32_e32 v3, v3, v14
	v_mul_f32_e32 v3, v12, v3
	v_cvt_pk_bf16_f32 v3, v3, v3
	ds_write_b16 v1, v3 offset:3184
	ds_read_u16 v3, v1 offset:4544
	s_waitcnt lgkmcnt(0)
	v_lshlrev_b32_e32 v3, 16, v3
	v_mul_f32_e32 v12, 0xbfb8aa3b, v3
	v_exp_f32_e32 v12, v12
	s_nop 0
	v_add_f32_e32 v12, 1.0, v12
	v_rcp_f32_e32 v13, v12
	s_nop 0
	v_mul_f32_e32 v3, v3, v13
	v_mul_f32_e32 v3, v11, v3
	v_cvt_pk_bf16_f32 v3, v3, v3
	ds_write_b16 v1, v3 offset:4544
	ds_read_u16 v3, v1 offset:4816
	s_waitcnt lgkmcnt(0)
	v_lshlrev_b32_e32 v3, 16, v3
	v_mul_f32_e32 v11, 0xbfb8aa3b, v3
	v_exp_f32_e32 v11, v11
	s_nop 0
	v_add_f32_e32 v11, 1.0, v11
	v_rcp_f32_e32 v12, v11
	s_nop 0
	v_mul_f32_e32 v3, v3, v12
	v_mul_f32_e32 v3, v10, v3
	v_cvt_pk_bf16_f32 v3, v3, v3
	ds_write_b16 v1, v3 offset:4816
	ds_read_u16 v3, v1 offset:5088
	s_waitcnt lgkmcnt(0)
	v_lshlrev_b32_e32 v3, 16, v3
	v_mul_f32_e32 v10, 0xbfb8aa3b, v3
	v_exp_f32_e32 v10, v10
	s_nop 0
	v_add_f32_e32 v10, 1.0, v10
	v_rcp_f32_e32 v11, v10
	s_nop 0
	v_mul_f32_e32 v3, v3, v11
	v_mul_f32_e32 v3, v9, v3
	v_cvt_pk_bf16_f32 v3, v3, v3
	ds_write_b16 v1, v3 offset:5088
	ds_read_u16 v3, v1 offset:5360
	s_waitcnt lgkmcnt(0)
	v_lshlrev_b32_e32 v3, 16, v3
	v_mul_f32_e32 v9, 0xbfb8aa3b, v3
	v_exp_f32_e32 v9, v9
	s_nop 0
	v_add_f32_e32 v9, 1.0, v9
	v_rcp_f32_e32 v10, v9
	s_nop 0
	v_mul_f32_e32 v3, v3, v10
	v_mul_f32_e32 v3, v8, v3
	v_cvt_pk_bf16_f32 v3, v3, v3
	ds_write_b16 v1, v3 offset:5360
	ds_read_u16 v3, v1 offset:6720
	s_waitcnt lgkmcnt(0)
	v_lshlrev_b32_e32 v3, 16, v3
	v_mul_f32_e32 v8, 0xbfb8aa3b, v3
	v_exp_f32_e32 v8, v8
	s_nop 0
	v_add_f32_e32 v8, 1.0, v8
	v_rcp_f32_e32 v9, v8
	s_nop 0
	v_mul_f32_e32 v3, v3, v9
	v_mul_f32_e32 v3, v7, v3
	v_cvt_pk_bf16_f32 v3, v3, v3
	ds_write_b16 v1, v3 offset:6720
	ds_read_u16 v3, v1 offset:6992
	s_waitcnt lgkmcnt(0)
	v_lshlrev_b32_e32 v3, 16, v3
	v_mul_f32_e32 v7, 0xbfb8aa3b, v3
	v_exp_f32_e32 v7, v7
	s_nop 0
	v_add_f32_e32 v7, 1.0, v7
	v_rcp_f32_e32 v8, v7
	s_nop 0
	v_mul_f32_e32 v3, v3, v8
	v_mul_f32_e32 v3, v6, v3
	v_cvt_pk_bf16_f32 v3, v3, v3
	ds_write_b16 v1, v3 offset:6992
	ds_read_u16 v3, v1 offset:7264
	s_waitcnt lgkmcnt(0)
	v_lshlrev_b32_e32 v3, 16, v3
	v_mul_f32_e32 v6, 0xbfb8aa3b, v3
	v_exp_f32_e32 v6, v6
	s_nop 0
	v_add_f32_e32 v6, 1.0, v6
	v_rcp_f32_e32 v7, v6
	s_nop 0
	v_mul_f32_e32 v3, v3, v7
	v_mul_f32_e32 v3, v5, v3
	v_cvt_pk_bf16_f32 v3, v3, v3
	ds_write_b16 v1, v3 offset:7264
	ds_read_u16 v3, v1 offset:7536
	s_waitcnt lgkmcnt(0)
	v_lshlrev_b32_e32 v3, 16, v3
	v_mul_f32_e32 v4, 0xbfb8aa3b, v3
	v_exp_f32_e32 v4, v4
	s_nop 0
	v_add_f32_e32 v4, 1.0, v4
	v_div_scale_f32 v5, s[0:1], v4, v4, v3
	s_nop 0
	v_rcp_f32_e32 v5, v4
	s_nop 0
	v_mul_f32_e32 v3, v3, v5
	v_mul_f32_e32 v2, v2, v3
	v_cvt_pk_bf16_f32 v2, v2, s0
	ds_write_b16 v1, v2 offset:7536
	s_waitcnt lgkmcnt(0)
	ds_read_b128 v[2:5], v92
	v_lshl_add_u64 v[6:7], v[90:91], 0, s[22:23]
	v_lshl_add_u64 v[8:9], v[6:7], 0, v[66:67]
	s_waitcnt lgkmcnt(0)
	global_store_dwordx4 v[8:9], v[2:5], off
	ds_read_b128 v[2:5], v92 offset:1088
	v_lshl_add_u64 v[8:9], v[6:7], 0, v[68:69]
	s_waitcnt lgkmcnt(0)
	global_store_dwordx4 v[8:9], v[2:5], off
	ds_read_b128 v[2:5], v92 offset:2176
	v_lshl_add_u64 v[8:9], v[6:7], 0, v[70:71]
	s_waitcnt lgkmcnt(0)
	global_store_dwordx4 v[8:9], v[2:5], off
	ds_read_b128 v[2:5], v92 offset:3264
	v_lshl_add_u64 v[8:9], v[6:7], 0, v[72:73]
	s_waitcnt lgkmcnt(0)
	global_store_dwordx4 v[8:9], v[2:5], off
	ds_read_b128 v[2:5], v92 offset:4352
	v_lshl_add_u64 v[8:9], v[6:7], 0, v[74:75]
	s_waitcnt lgkmcnt(0)
	global_store_dwordx4 v[8:9], v[2:5], off
	ds_read_b128 v[2:5], v92 offset:5440
	v_lshl_add_u64 v[8:9], v[6:7], 0, v[76:77]
	s_waitcnt lgkmcnt(0)
	global_store_dwordx4 v[8:9], v[2:5], off
	ds_read_b128 v[2:5], v92 offset:6528
	v_lshl_add_u64 v[8:9], v[6:7], 0, v[78:79]
	v_lshl_add_u64 v[6:7], v[6:7], 0, v[80:81]
	s_waitcnt lgkmcnt(0)
	global_store_dwordx4 v[8:9], v[2:5], off
	ds_read_b128 v[2:5], v92 offset:7616
	s_waitcnt lgkmcnt(0)
	global_store_dwordx4 v[6:7], v[2:5], off
	s_waitcnt lgkmcnt(0)
	s_cbranch_scc1 .LBB0_604

; #define MFMA32(a, b, c) __builtin_amdgcn_mfma_f32_32x32x16_bf16((a), (b), (c), 0, 0, 0)
; DI void gla_stage3(const Ctx& c0, int layer, int unit, int cb, LAS unsigned char* lds) {
;     ...
;     const bf16* qgp = (const bf16*)(c.ws + O_QG) + (row0 + r) * 256 + h * 64 + 8 * hi;
;     const float* sp = (const float*)(c.ws + O_UPD) + (size_t)unit * 8192;
;     const float* gn = c.a->in[I_GNORM] + (size_t)layer * 128;
;     bf16x8 qf[4];
; #pragma unroll
;     for (int s = 0; s < 4; ++s) qf[s] = *(const bf16x8*)(qgp + 16 * s);
;     f32x16 o[4];
; #pragma unroll
;     for (int vb = 0; vb < 4; ++vb) {
;         o[vb] = f32x16{};
; #pragma unroll
;         for (int s = 0; s < 4; ++s) { const float* s0 = sp + (size_t)(16 * s + 8 * hi) * 128 + 32 * vb + r;
;             const bf16x8 bfv = pack8(s0[0], s0[128], s0[256], s0[384], s0[512], s0[640], s0[768], s0[896]);
;             o[vb] = MFMA32(qf[s], bfv, o[vb]); }
.LBB0_1216:
	s_mov_b64 s[0:1], s[74:75]
	s_mov_b64 s[2:3], s[72:73]
	s_ashr_i32 s2, s34, 8
	s_ashr_i32 s3, s2, 31
	s_lshl_b64 s[2:3], s[2:3], 12
	s_and_b32 s9, s4, 0xfc0
	s_or_b32 s2, s2, s9
	s_or_b64 s[2:3], s[2:3], s[10:11]
	v_mov_b32_e32 v3, s3
	v_or_b32_e32 v2, s2, v152
	s_bfe_u32 s8, s34, 0x20006
	v_lshlrev_b64 v[2:3], 9, v[2:3]
	v_lshl_add_u64 v[2:3], s[0:1], 0, v[2:3]
	s_lshl_b32 s12, s8, 7
	v_lshl_add_u64 v[2:3], v[2:3], 0, s[12:13]
	v_lshl_add_u64 v[2:3], v[2:3], 0, v[86:87]
	v_lshl_add_u64 v[4:5], v[2:3], 0, s[18:19]
	v_add_co_u32_e32 v2, vcc, s6, v2
	v_lshl_add_u64 v[90:91], s[0:1], 0, v[84:85]
	s_nop 0
	v_addc_co_u32_e32 v3, vcc, 0, v3, vcc
	global_load_dwordx4 v[50:53], v[2:3], off
	global_load_dwordx4 v[110:113], v[4:5], off offset:96
	global_load_dwordx4 v[106:109], v[4:5], off offset:64
	global_load_dwordx4 v[102:105], v[4:5], off offset:32
	v_add_co_u32_e32 v2, vcc, s7, v90
	s_lshl_b64 s[2:3], s[2:3], 10
	s_nop 0
	v_addc_co_u32_e32 v3, vcc, -1, v91, vcc
	v_add_co_u32_e32 v58, vcc, s28, v90
	global_load_dword v2, v[2:3], off
	s_nop 0
	v_addc_co_u32_e32 v59, vcc, -1, v91, vcc
	global_load_dword v3, v[58:59], off offset:384
	global_load_dword v4, v[58:59], off offset:896
	global_load_dword v5, v[58:59], off offset:1408
	global_load_dword v6, v[58:59], off offset:1920
	global_load_dword v7, v[58:59], off offset:2432
	global_load_dword v8, v[58:59], off offset:2944
	global_load_dword v9, v[58:59], off offset:3456
	v_add_co_u32_e32 v18, vcc, s15, v90
	s_lshl_b32 s8, s8, 8
	s_nop 0
	v_addc_co_u32_e32 v19, vcc, -1, v91, vcc
	v_add_co_u32_e32 v114, vcc, s29, v90
	global_load_dword v18, v[18:19], off
	s_nop 0
	v_addc_co_u32_e32 v115, vcc, -1, v91, vcc
	global_load_dword v19, v[114:115], off offset:384
	global_load_dword v20, v[114:115], off offset:896
	global_load_dword v21, v[114:115], off offset:1408
	global_load_dword v22, v[114:115], off offset:1920
	global_load_dword v23, v[114:115], off offset:2432
	global_load_dword v24, v[114:115], off offset:2944
	global_load_dword v25, v[114:115], off offset:3456
	s_add_u32 s0, s0, s2
	s_addc_u32 s1, s1, s3
	s_add_u32 s0, s0, s8
	s_addc_u32 s1, s1, 0
	s_add_i32 s34, s34, s14
	s_add_i32 s4, s4, s5
	v_lshl_add_u64 v[84:85], v[84:85], 0, s[16:17]
	s_cmpk_lt_i32 s34, 0x800
	v_add_co_u32_e32 v26, vcc, s26, v90
	s_nop 1
	v_addc_co_u32_e32 v27, vcc, -1, v91, vcc
	v_add_co_u32_e32 v118, vcc, s30, v90
	global_load_dword v26, v[26:27], off
	s_nop 0
	v_addc_co_u32_e32 v119, vcc, -1, v91, vcc
	global_load_dword v27, v[118:119], off offset:384
	global_load_dword v28, v[118:119], off offset:896
	global_load_dword v29, v[118:119], off offset:1408
	global_load_dword v30, v[118:119], off offset:1920
	global_load_dword v31, v[118:119], off offset:2432
	global_load_dword v32, v[118:119], off offset:2944
	global_load_dword v33, v[118:119], off offset:3456
	v_add_co_u32_e32 v42, vcc, s27, v90
	s_nop 1
	v_addc_co_u32_e32 v43, vcc, -1, v91, vcc
	v_add_co_u32_e32 v120, vcc, s31, v90
	global_load_dword v42, v[42:43], off
	s_nop 0
	v_addc_co_u32_e32 v121, vcc, -1, v91, vcc
	global_load_dword v43, v[120:121], off offset:384
	global_load_dword v44, v[120:121], off offset:896
	global_load_dword v45, v[120:121], off offset:1408
	global_load_dword v46, v[120:121], off offset:1920
	global_load_dword v47, v[120:121], off offset:2432
	global_load_dword v48, v[120:121], off offset:2944
	global_load_dword v49, v[120:121], off offset:3456
	s_waitcnt vmcnt(16) lgkmcnt(0)
	global_load_dword v41, v[114:115], off offset:3584
	global_load_dword v40, v[114:115], off offset:3072
	global_load_dword v39, v[114:115], off offset:2560
	global_load_dword v38, v[114:115], off offset:2048
	global_load_dword v37, v[114:115], off offset:1536
	global_load_dword v36, v[114:115], off offset:1024
	global_load_dword v35, v[114:115], off offset:512
	global_load_dword v34, v[114:115], off
	global_load_dword v145, v[58:59], off offset:3584
	global_load_dword v146, v[58:59], off offset:3072
	global_load_dword v143, v[58:59], off offset:2560
	global_load_dword v144, v[58:59], off offset:2048
	global_load_dword v141, v[58:59], off offset:1536
	global_load_dword v142, v[58:59], off offset:1024
	global_load_dword v139, v[58:59], off offset:512
	global_load_dword v140, v[58:59], off
	v_cvt_pk_bf16_f32 v2, v2, v3
	v_cvt_pk_bf16_f32 v3, v4, v5
	v_cvt_pk_bf16_f32 v4, v6, v7
	v_cvt_pk_bf16_f32 v5, v8, v9
	v_cvt_pk_bf16_f32 v18, v18, v19
	s_nop 0
	v_mfma_f32_32x32x16_bf16 v[2:17], v[50:53], v[2:5], 0
	v_cvt_pk_bf16_f32 v19, v20, v21
	v_cvt_pk_bf16_f32 v20, v22, v23
	v_cvt_pk_bf16_f32 v21, v24, v25
	s_nop 1
	v_mfma_f32_32x32x16_bf16 v[2:17], v[102:105], v[18:21], v[2:17]
	s_waitcnt vmcnt(24) lgkmcnt(0)
	global_load_dword v63, v[114:115], off offset:3712
	global_load_dword v62, v[114:115], off offset:3200
	global_load_dword v61, v[114:115], off offset:2688
	global_load_dword v60, v[114:115], off offset:2176
	global_load_dword v57, v[114:115], off offset:1664
	global_load_dword v56, v[114:115], off offset:1152
	global_load_dword v55, v[114:115], off offset:640
	global_load_dword v54, v[114:115], off offset:128
	global_load_dword v173, v[58:59], off offset:3712
	global_load_dword v176, v[58:59], off offset:3200
	global_load_dword v171, v[58:59], off offset:2688
	global_load_dword v174, v[58:59], off offset:2176
	global_load_dword v169, v[58:59], off offset:1664
	global_load_dword v172, v[58:59], off offset:1152
	global_load_dword v167, v[58:59], off offset:640
	global_load_dword v170, v[58:59], off offset:128
	global_load_dword v157, v[118:119], off offset:3584
	global_load_dword v160, v[118:119], off offset:3072
	global_load_dword v155, v[118:119], off offset:2560
	global_load_dword v158, v[118:119], off offset:2048
	global_load_dword v149, v[118:119], off offset:1536
	global_load_dword v156, v[118:119], off offset:1024
	global_load_dword v147, v[118:119], off offset:512
	global_load_dword v148, v[118:119], off
	v_cvt_pk_bf16_f32 v26, v26, v27
	v_cvt_pk_bf16_f32 v27, v28, v29
	v_cvt_pk_bf16_f32 v28, v30, v31
	v_cvt_pk_bf16_f32 v29, v32, v33
	s_nop 1
	v_mfma_f32_32x32x16_bf16 v[2:17], v[106:109], v[26:29], v[2:17]
	v_cmp_lt_i32_e32 vcc, v94, v95
	s_waitcnt vmcnt(20) lgkmcnt(0)
; #define MFMA32(a, b, c) __builtin_amdgcn_mfma_f32_32x32x16_bf16((a), (b), (c), 0, 0, 0)
; DI void gla_stage3(const Ctx& c0, int layer, int unit, int cb, LAS unsigned char* lds) {
;     ...
;     f32x16 o[4];
; #pragma unroll
;     for (int vb = 0; vb < 4; ++vb) {
;         o[vb] = f32x16{};
; #pragma unroll
;         for (int s = 0; s < 4; ++s) { const float* s0 = sp + (size_t)(16 * s + 8 * hi) * 128 + 32 * vb + r;
;             const bf16x8 bfv = pack8(s0[0], s0[128], s0[256], s0[384], s0[512], s0[640], s0[768], s0[896]);
;             o[vb] = MFMA32(qf[s], bfv, o[vb]); }
;         asm volatile("" ::: "memory");
;     }
	global_load_dword v127, v[114:115], off offset:3840
	global_load_dword v126, v[114:115], off offset:3328
	global_load_dword v125, v[114:115], off offset:2816
	global_load_dword v124, v[114:115], off offset:2304
	global_load_dword v123, v[114:115], off offset:1792
	global_load_dword v122, v[114:115], off offset:1280
	global_load_dword v117, v[114:115], off offset:768
	global_load_dword v116, v[114:115], off offset:256
	global_load_dword v214, v[58:59], off offset:3840
	global_load_dword v212, v[58:59], off offset:3328
	global_load_dword v205, v[58:59], off offset:2816
	global_load_dword v210, v[58:59], off offset:2304
	global_load_dword v203, v[58:59], off offset:1792
	global_load_dword v208, v[58:59], off offset:1280
	global_load_dword v201, v[58:59], off offset:768
	global_load_dword v206, v[58:59], off offset:256
	global_load_dword v199, v[120:121], off offset:3712
	global_load_dword v204, v[120:121], off offset:3200
	global_load_dword v197, v[120:121], off offset:2688
	global_load_dword v202, v[120:121], off offset:2176
	global_load_dword v195, v[120:121], off offset:1664
	global_load_dword v200, v[120:121], off offset:1152
	global_load_dword v183, v[120:121], off offset:640
	global_load_dword v198, v[120:121], off offset:128
	global_load_dword v181, v[118:119], off offset:3712
	global_load_dword v196, v[118:119], off offset:3200
	global_load_dword v179, v[118:119], off offset:2688
	global_load_dword v182, v[118:119], off offset:2176
	global_load_dword v177, v[118:119], off offset:1664
	global_load_dword v180, v[118:119], off offset:1152
	global_load_dword v175, v[118:119], off offset:640
	global_load_dword v178, v[118:119], off offset:128
	global_load_dword v165, v[120:121], off offset:3584
	global_load_dword v168, v[120:121], off offset:3072
	global_load_dword v163, v[120:121], off offset:2560
	global_load_dword v166, v[120:121], off offset:2048
	global_load_dword v161, v[120:121], off offset:1536
	global_load_dword v164, v[120:121], off offset:1024
	global_load_dword v159, v[120:121], off offset:512
	global_load_dword v162, v[120:121], off
	v_cvt_pk_bf16_f32 v42, v42, v43
	v_cvt_pk_bf16_f32 v43, v44, v45
	v_cvt_pk_bf16_f32 v44, v46, v47
	v_cvt_pk_bf16_f32 v45, v48, v49
	s_nop 1
	v_mfma_f32_32x32x16_bf16 v[2:17], v[110:113], v[42:45], v[2:17]
	s_waitcnt vmcnt(40) lgkmcnt(0)
	global_load_dword v238, v[82:83], off offset:896
	global_load_dword v236, v[82:83], off offset:768
	global_load_dword v234, v[82:83], off offset:640
	global_load_dword v232, v[82:83], off offset:512
	global_load_dword v90, v[90:91], off
	global_load_dword v230, v[120:121], off offset:3328
	global_load_dword v219, v[120:121], off offset:2816
	global_load_dword v228, v[120:121], off offset:2304
	global_load_dword v217, v[120:121], off offset:1792
	global_load_dword v226, v[120:121], off offset:1280
	global_load_dword v215, v[120:121], off offset:768
	global_load_dword v224, v[120:121], off offset:256
	global_load_dword v213, v[118:119], off offset:3840
	global_load_dword v222, v[118:119], off offset:3328
	global_load_dword v211, v[118:119], off offset:2816
	global_load_dword v220, v[118:119], off offset:2304
	global_load_dword v209, v[118:119], off offset:1792
	global_load_dword v218, v[118:119], off offset:1280
	global_load_dword v207, v[118:119], off offset:768
	global_load_dword v216, v[118:119], off offset:256
	v_cvt_pk_bf16_f32 v18, v140, v139
	v_cvt_pk_bf16_f32 v34, v34, v35
	v_cvt_pk_bf16_f32 v19, v142, v141
	v_cvt_pk_bf16_f32 v35, v36, v37
	v_cvt_pk_bf16_f32 v20, v144, v143
	v_cvt_pk_bf16_f32 v36, v38, v39
	v_cvt_pk_bf16_f32 v21, v146, v145
	v_cvt_pk_bf16_f32 v37, v40, v41
	s_nop 0
	v_mfma_f32_32x32x16_bf16 v[18:33], v[50:53], v[18:21], 0
	v_mfma_f32_32x32x16_bf16 v[18:33], v[102:105], v[34:37], v[18:33]
	s_waitcnt vmcnt(60) lgkmcnt(0)
	v_cvt_pk_bf16_f32 v34, v148, v147
	v_cvt_pk_bf16_f32 v35, v156, v149
	v_cvt_pk_bf16_f32 v36, v158, v155
	v_cvt_pk_bf16_f32 v37, v160, v157
	s_nop 1
	v_mfma_f32_32x32x16_bf16 v[18:33], v[106:109], v[34:37], v[18:33]
	s_waitcnt vmcnt(20) lgkmcnt(0)
	v_cvt_pk_bf16_f32 v34, v162, v159
	v_cvt_pk_bf16_f32 v35, v164, v161
	v_cvt_pk_bf16_f32 v36, v166, v163
	v_cvt_pk_bf16_f32 v37, v168, v165
	s_nop 1
	v_mfma_f32_32x32x16_bf16 v[18:33], v[110:113], v[34:37], v[18:33]
	s_waitcnt vmcnt(62) lgkmcnt(0)
	v_cvt_pk_bf16_f32 v34, v170, v167
	v_cvt_pk_bf16_f32 v54, v54, v55
	v_cvt_pk_bf16_f32 v35, v172, v169
	v_cvt_pk_bf16_f32 v55, v56, v57
	v_cvt_pk_bf16_f32 v36, v174, v171
	v_cvt_pk_bf16_f32 v56, v60, v61
	v_cvt_pk_bf16_f32 v37, v176, v173
	v_cvt_pk_bf16_f32 v57, v62, v63
	s_nop 0
	v_mfma_f32_32x32x16_bf16 v[34:49], v[50:53], v[34:37], 0
	v_mfma_f32_32x32x16_bf16 v[34:49], v[102:105], v[54:57], v[34:49]
	s_waitcnt vmcnt(28) lgkmcnt(0)
	v_cvt_pk_bf16_f32 v54, v178, v175
	v_cvt_pk_bf16_f32 v55, v180, v177
	v_cvt_pk_bf16_f32 v56, v182, v179
	v_cvt_pk_bf16_f32 v57, v196, v181
	s_nop 1
	v_mfma_f32_32x32x16_bf16 v[34:49], v[106:109], v[54:57], v[34:49]
	s_waitcnt vmcnt(36) lgkmcnt(0)
	v_cvt_pk_bf16_f32 v54, v198, v183
	v_cvt_pk_bf16_f32 v55, v200, v195
	v_cvt_pk_bf16_f32 v56, v202, v197
	v_cvt_pk_bf16_f32 v57, v204, v199
	s_nop 1
	v_mfma_f32_32x32x16_bf16 v[34:49], v[110:113], v[54:57], v[34:49]
	s_nop 0
	s_nop 0
	s_waitcnt vmcnt(44) lgkmcnt(0)
	v_cvt_pk_bf16_f32 v54, v206, v201
	v_cvt_pk_bf16_f32 v114, v116, v117
	v_cvt_pk_bf16_f32 v55, v208, v203
	v_cvt_pk_bf16_f32 v115, v122, v123
	v_cvt_pk_bf16_f32 v56, v210, v205
	v_cvt_pk_bf16_f32 v116, v124, v125
	v_cvt_pk_bf16_f32 v57, v212, v214
	v_cvt_pk_bf16_f32 v117, v126, v127
	s_nop 0
	v_mfma_f32_32x32x16_bf16 v[50:65], v[50:53], v[54:57], 0
	v_mfma_f32_32x32x16_bf16 v[50:65], v[102:105], v[114:117], v[50:65]
	s_waitcnt vmcnt(0) lgkmcnt(0)
; #define LAS __attribute__((address_space(3)))
; #define LDS_WAIT() asm volatile("s_waitcnt lgkmcnt(0)" ::: "memory")
; DI float bf2f(bf16 b) { return __uint_as_float(((unsigned)b) << 16); }
; DI void g3_tile_in(const bf16* g, LAS unsigned char* R, int lane) {
; #pragma unroll
;     for (int it = 0; it < 8; ++it) { const int row = 4 * it + (lane >> 4), ch = lane & 15;
;         *(LAS u32x4*)(R + row * G3_PITCH + ch * 16) = *(const u32x4*)(g + (size_t)row * 512 + ch * 8); }
;     LDS_WAIT();
; }
; DI void gla_stage3(const Ctx& c0, int layer, int unit, int cb, LAS unsigned char* lds) {
;     ...
;     g3_tile_in((const bf16*)(c.ws + O_OINTRA) + row0 * 512 + h * 128, R, lane);
; #pragma unroll
;     for (int vb = 0; vb < 4; ++vb) {
; #pragma unroll
;         for (int rg = 0; rg < 16; ++rg) o[vb][rg] += bf2f(*(const LAS bf16*)(Re + ((rg & 3) + 8 * (rg >> 2)) * G3_PITCH + 64 * vb));
;         asm volatile("" ::: "memory");
;     }
	v_cvt_pk_bf16_f32 v102, v216, v207
	v_cvt_pk_bf16_f32 v103, v218, v209
	v_cvt_pk_bf16_f32 v104, v220, v211
	v_cvt_pk_bf16_f32 v105, v222, v213
	s_nop 1
	v_mfma_f32_32x32x16_bf16 v[50:65], v[106:109], v[102:105], v[50:65]
	s_nop 0
	s_waitcnt vmcnt(8) lgkmcnt(0)
	v_cvt_pk_bf16_f32 v102, v224, v215
	v_cvt_pk_bf16_f32 v103, v226, v217
	v_cvt_pk_bf16_f32 v104, v228, v219
	v_cvt_pk_bf16_f32 v105, v230, v90
	v_lshl_add_u64 v[90:91], s[0:1], 0, v[88:89]
	v_lshl_add_u64 v[106:107], v[90:91], 0, s[20:21]
	v_mfma_f32_32x32x16_bf16 v[50:65], v[110:113], v[102:105], v[50:65]
	v_lshl_add_u64 v[102:103], v[106:107], 0, v[66:67]
	global_load_dwordx4 v[102:105], v[102:103], off
	s_waitcnt vmcnt(0) lgkmcnt(0)
	v_lshl_add_u64 v[168:169], v[90:91], 0, s[22:23]
	v_lshl_add_u64 v[140:141], v[168:169], 0, v[70:71]
	global_load_dwordx4 v[174:177], v[140:141], off
	v_lshl_add_u64 v[140:141], v[106:107], 0, v[70:71]
	global_load_dwordx4 v[146:149], v[140:141], off
	v_lshl_add_u64 v[144:145], v[106:107], 0, v[68:69]
	global_load_dwordx4 v[140:143], v[144:145], off
	ds_write_b128 v92, v[102:105]
	s_waitcnt vmcnt(0) lgkmcnt(0)
	v_lshl_add_u64 v[144:145], v[168:169], 0, v[76:77]
	global_load_dwordx4 v[200:203], v[144:145], off
	v_lshl_add_u64 v[144:145], v[168:169], 0, v[74:75]
	global_load_dwordx4 v[196:199], v[144:145], off
	v_lshl_add_u64 v[144:145], v[168:169], 0, v[72:73]
	global_load_dwordx4 v[178:181], v[144:145], off
	v_lshl_add_u64 v[144:145], v[106:107], 0, v[74:75]
	global_load_dwordx4 v[156:159], v[144:145], off
	v_lshl_add_u64 v[102:103], v[106:107], 0, v[72:73]
	global_load_dwordx4 v[102:105], v[102:103], off
	ds_write_b128 v92, v[140:143] offset:1088
	s_waitcnt vmcnt(5) lgkmcnt(0)
	v_lshl_add_u64 v[140:141], v[168:169], 0, v[78:79]
	global_load_dwordx4 v[204:207], v[140:141], off
	v_lshl_add_u64 v[140:141], v[106:107], 0, v[78:79]
	global_load_dwordx4 v[160:163], v[140:141], off
	v_lshl_add_u64 v[144:145], v[106:107], 0, v[76:77]
	global_load_dwordx4 v[140:143], v[144:145], off
	ds_write_b128 v92, v[146:149] offset:2176
	s_waitcnt vmcnt(3) lgkmcnt(0)
	v_lshl_add_u64 v[144:145], v[168:169], 0, v[66:67]
	global_load_dwordx4 v[164:167], v[144:145], off
	v_lshl_add_u64 v[148:149], v[106:107], 0, v[80:81]
	global_load_dwordx4 v[144:147], v[148:149], off
	ds_write_b128 v92, v[102:105] offset:3264
	s_waitcnt vmcnt(6) lgkmcnt(0)
	v_lshl_add_u64 v[148:149], v[168:169], 0, v[68:69]
	global_load_dwordx4 v[170:173], v[148:149], off
	ds_write_b128 v92, v[156:159] offset:4352
	s_waitcnt vmcnt(3) lgkmcnt(0)
	ds_write_b128 v92, v[140:143] offset:5440
	s_waitcnt vmcnt(4) lgkmcnt(0)
	ds_write_b128 v92, v[160:163] offset:6528
	s_waitcnt vmcnt(1) lgkmcnt(0)
	ds_write_b128 v92, v[144:147] offset:7616
	s_waitcnt lgkmcnt(0)
	ds_read_u16 v138, v1
	ds_read_u16 v137, v1 offset:272
	ds_read_u16 v136, v1 offset:544
	ds_read_u16 v135, v1 offset:816
	ds_read_u16 v134, v1 offset:2176
	ds_read_u16 v133, v1 offset:2448
	ds_read_u16 v132, v1 offset:2720
	ds_read_u16 v131, v1 offset:2992
	s_waitcnt lgkmcnt(0)
	v_lshlrev_b32_e32 v138, 16, v138
	v_add_f32_e32 v138, v2, v138
	v_lshlrev_b32_e32 v137, 16, v137
	v_add_f32_e32 v137, v3, v137
	v_lshlrev_b32_e32 v136, 16, v136
	v_add_f32_e32 v136, v4, v136
	v_lshlrev_b32_e32 v135, 16, v135
	v_add_f32_e32 v135, v5, v135
	v_lshlrev_b32_e32 v134, 16, v134
	v_add_f32_e32 v134, v6, v134
	v_lshlrev_b32_e32 v133, 16, v133
	v_add_f32_e32 v133, v7, v133
	v_lshlrev_b32_e32 v132, 16, v132
	v_add_f32_e32 v132, v8, v132
	v_lshlrev_b32_e32 v131, 16, v131
	v_add_f32_e32 v131, v9, v131
	ds_read_u16 v130, v1 offset:4352
	ds_read_u16 v129, v1 offset:4624
	ds_read_u16 v128, v1 offset:4896
	ds_read_u16 v127, v1 offset:5168
	ds_read_u16 v126, v1 offset:6528
	ds_read_u16 v125, v1 offset:6800
	ds_read_u16 v124, v1 offset:7072
	s_waitcnt lgkmcnt(0)
	v_lshlrev_b32_e32 v130, 16, v130
	v_add_f32_e32 v130, v10, v130
	v_lshlrev_b32_e32 v129, 16, v129
	v_add_f32_e32 v129, v11, v129
	v_lshlrev_b32_e32 v128, 16, v128
	v_add_f32_e32 v128, v12, v128
	v_lshlrev_b32_e32 v127, 16, v127
	v_add_f32_e32 v127, v13, v127
	v_lshlrev_b32_e32 v126, 16, v126
	v_add_f32_e32 v126, v14, v126
	v_lshlrev_b32_e32 v125, 16, v125
	v_add_f32_e32 v125, v15, v125
	v_lshlrev_b32_e32 v124, 16, v124
	v_add_f32_e32 v124, v16, v124
	ds_read_u16 v2, v1 offset:7344
	s_waitcnt lgkmcnt(0)
	v_lshlrev_b32_e32 v2, 16, v2
	v_add_f32_e32 v123, v17, v2
	ds_read_u16 v122, v1 offset:64
	ds_read_u16 v121, v1 offset:336
	ds_read_u16 v120, v1 offset:608
	ds_read_u16 v119, v1 offset:880
	ds_read_u16 v118, v1 offset:2240
	ds_read_u16 v117, v1 offset:2512
	ds_read_u16 v116, v1 offset:2784
	ds_read_u16 v115, v1 offset:3056
	s_waitcnt lgkmcnt(0)
	v_lshlrev_b32_e32 v122, 16, v122
	v_add_f32_e32 v122, v18, v122
	v_lshlrev_b32_e32 v121, 16, v121
	v_add_f32_e32 v121, v19, v121
	v_lshlrev_b32_e32 v120, 16, v120
	v_add_f32_e32 v120, v20, v120
	v_lshlrev_b32_e32 v119, 16, v119
	v_add_f32_e32 v119, v21, v119
	v_lshlrev_b32_e32 v118, 16, v118
	v_add_f32_e32 v118, v22, v118
	v_lshlrev_b32_e32 v117, 16, v117
	v_add_f32_e32 v117, v23, v117
	v_lshlrev_b32_e32 v116, 16, v116
	v_add_f32_e32 v116, v24, v116
	v_lshlrev_b32_e32 v115, 16, v115
	v_add_f32_e32 v115, v25, v115
	ds_read_u16 v114, v1 offset:4416
	ds_read_u16 v113, v1 offset:4688
	ds_read_u16 v112, v1 offset:4960
	ds_read_u16 v111, v1 offset:5232
	ds_read_u16 v110, v1 offset:6592
	ds_read_u16 v109, v1 offset:6864
	ds_read_u16 v108, v1 offset:7136
	s_waitcnt lgkmcnt(0)
; #define LAS __attribute__((address_space(3)))
; DI float bf2f(bf16 b) { return __uint_as_float(((unsigned)b) << 16); }
; DI void gla_stage3(const Ctx& c0, int layer, int unit, int cb, LAS unsigned char* lds) {
;     ...
;     g3_tile_in((const bf16*)(c.ws + O_OINTRA) + row0 * 512 + h * 128, R, lane);
; #pragma unroll
;     for (int vb = 0; vb < 4; ++vb) {
; #pragma unroll
;         for (int rg = 0; rg < 16; ++rg) o[vb][rg] += bf2f(*(const LAS bf16*)(Re + ((rg & 3) + 8 * (rg >> 2)) * G3_PITCH + 64 * vb));
;         asm volatile("" ::: "memory");
;     }
;     float rs[16];
; #pragma unroll
;     for (int rg = 0; rg < 16; ++rg) { float ss = o[0][rg] * o[0][rg] + o[1][rg] * o[1][rg] + o[2][rg] * o[2][rg] + o[3][rg] * o[3][rg];
;         ss += __shfl_xor(ss, 1); ss += __shfl_xor(ss, 2); ss += __shfl_xor(ss, 4); ss += __shfl_xor(ss, 8); ss += __shfl_xor(ss, 16);
;         rs[rg] = 1.f / sqrtf(ss * (1.f / 128.f) + EPS); }
	v_lshlrev_b32_e32 v114, 16, v114
	v_add_f32_e32 v114, v26, v114
	v_lshlrev_b32_e32 v113, 16, v113
	v_add_f32_e32 v113, v27, v113
	v_lshlrev_b32_e32 v112, 16, v112
	v_add_f32_e32 v112, v28, v112
	v_lshlrev_b32_e32 v111, 16, v111
	v_add_f32_e32 v111, v29, v111
	v_lshlrev_b32_e32 v110, 16, v110
	v_add_f32_e32 v110, v30, v110
	v_lshlrev_b32_e32 v109, 16, v109
	v_add_f32_e32 v109, v31, v109
	v_lshlrev_b32_e32 v108, 16, v108
	v_add_f32_e32 v108, v32, v108
	ds_read_u16 v2, v1 offset:7408
	s_waitcnt lgkmcnt(0)
	v_lshlrev_b32_e32 v2, 16, v2
	v_add_f32_e32 v107, v33, v2
	ds_read_u16 v2, v1 offset:128
	s_waitcnt lgkmcnt(0)
	v_lshlrev_b32_e32 v2, 16, v2
	v_add_f32_e32 v106, v34, v2
	ds_read_u16 v2, v1 offset:400
	s_waitcnt lgkmcnt(0)
	v_lshlrev_b32_e32 v2, 16, v2
	v_add_f32_e32 v105, v35, v2
	ds_read_u16 v2, v1 offset:672
	s_waitcnt lgkmcnt(0)
	v_lshlrev_b32_e32 v2, 16, v2
	v_add_f32_e32 v104, v36, v2
	ds_read_u16 v2, v1 offset:944
	s_waitcnt lgkmcnt(0)
	v_lshlrev_b32_e32 v2, 16, v2
	v_add_f32_e32 v103, v37, v2
	ds_read_u16 v2, v1 offset:2304
	s_waitcnt lgkmcnt(0)
	v_lshlrev_b32_e32 v2, 16, v2
	v_add_f32_e32 v102, v38, v2
	ds_read_u16 v2, v1 offset:2576
	s_waitcnt lgkmcnt(0)
	v_lshlrev_b32_e32 v2, 16, v2
	v_add_f32_e32 v39, v39, v2
	ds_read_u16 v2, v1 offset:2848
	s_waitcnt lgkmcnt(0)
	v_lshlrev_b32_e32 v2, 16, v2
	v_add_f32_e32 v38, v40, v2
	ds_read_u16 v2, v1 offset:3120
	s_waitcnt lgkmcnt(0)
	v_lshlrev_b32_e32 v2, 16, v2
	v_add_f32_e32 v37, v41, v2
	ds_read_u16 v36, v1 offset:4480
	ds_read_u16 v34, v1 offset:4752
	ds_read_u16 v33, v1 offset:5024
	ds_read_u16 v32, v1 offset:5296
	ds_read_u16 v30, v1 offset:6656
	ds_read_u16 v29, v1 offset:6928
	ds_read_u16 v28, v1 offset:7200
	s_waitcnt lgkmcnt(0)
	v_lshlrev_b32_e32 v36, 16, v36
	v_add_f32_e32 v36, v42, v36
	v_lshlrev_b32_e32 v34, 16, v34
	v_add_f32_e32 v34, v43, v34
	v_lshlrev_b32_e32 v33, 16, v33
	v_add_f32_e32 v33, v44, v33
	v_lshlrev_b32_e32 v32, 16, v32
	v_add_f32_e32 v32, v45, v32
	v_lshlrev_b32_e32 v30, 16, v30
	v_add_f32_e32 v30, v46, v30
	v_lshlrev_b32_e32 v29, 16, v29
	v_add_f32_e32 v29, v47, v29
	v_lshlrev_b32_e32 v28, 16, v28
	v_add_f32_e32 v28, v48, v28
	ds_read_u16 v2, v1 offset:7472
	s_waitcnt lgkmcnt(0)
	v_lshlrev_b32_e32 v2, 16, v2
	v_add_f32_e32 v26, v49, v2
	ds_read_u16 v19, v1 offset:192
	ds_read_u16 v18, v1 offset:464
	ds_read_u16 v17, v1 offset:736
	ds_read_u16 v16, v1 offset:1008
	ds_read_u16 v15, v1 offset:2368
	ds_read_u16 v14, v1 offset:2640
	ds_read_u16 v13, v1 offset:2912
	ds_read_u16 v12, v1 offset:3184
	s_waitcnt lgkmcnt(0)
	v_lshlrev_b32_e32 v19, 16, v19
	v_add_f32_e32 v19, v50, v19
	v_lshlrev_b32_e32 v18, 16, v18
	v_add_f32_e32 v18, v51, v18
	v_lshlrev_b32_e32 v17, 16, v17
	v_add_f32_e32 v17, v52, v17
	v_lshlrev_b32_e32 v16, 16, v16
	v_add_f32_e32 v16, v53, v16
	v_lshlrev_b32_e32 v15, 16, v15
	v_add_f32_e32 v15, v54, v15
	v_lshlrev_b32_e32 v14, 16, v14
	v_add_f32_e32 v14, v55, v14
	v_lshlrev_b32_e32 v13, 16, v13
	v_add_f32_e32 v13, v56, v13
	v_lshlrev_b32_e32 v12, 16, v12
	v_add_f32_e32 v12, v57, v12
	ds_read_u16 v11, v1 offset:4544
	ds_read_u16 v10, v1 offset:4816
	ds_read_u16 v9, v1 offset:5088
	ds_read_u16 v8, v1 offset:5360
	ds_read_u16 v7, v1 offset:6720
	ds_read_u16 v6, v1 offset:6992
	ds_read_u16 v5, v1 offset:7264
	s_waitcnt lgkmcnt(0)
	v_lshlrev_b32_e32 v11, 16, v11
	v_add_f32_e32 v11, v58, v11
	v_lshlrev_b32_e32 v10, 16, v10
	v_add_f32_e32 v10, v59, v10
	v_lshlrev_b32_e32 v9, 16, v9
	v_add_f32_e32 v9, v60, v9
	v_lshlrev_b32_e32 v8, 16, v8
	v_add_f32_e32 v8, v61, v8
	v_lshlrev_b32_e32 v7, 16, v7
	v_add_f32_e32 v7, v62, v7
	v_lshlrev_b32_e32 v6, 16, v6
	v_add_f32_e32 v6, v63, v6
	v_lshlrev_b32_e32 v5, 16, v5
	v_add_f32_e32 v5, v64, v5
	ds_read_u16 v2, v1 offset:7536
	s_waitcnt lgkmcnt(0)
	s_waitcnt lgkmcnt(0)
	v_lshlrev_b32_e32 v2, 16, v2
	v_add_f32_e32 v4, v65, v2
	v_cndmask_b32_e32 v2, v93, v94, vcc
	v_cmp_lt_i32_e32 vcc, v96, v95
	v_lshlrev_b32_e32 v2, 2, v2
	s_nop 0
	v_cndmask_b32_e32 v3, v93, v96, vcc
	v_cmp_lt_i32_e32 vcc, v97, v95
	v_lshlrev_b32_e32 v3, 2, v3
	s_nop 0
	v_cndmask_b32_e32 v20, v93, v97, vcc
	v_cmp_lt_i32_e32 vcc, v98, v95
	v_lshlrev_b32_e32 v20, 2, v20
	s_nop 0
	v_cndmask_b32_e32 v21, v93, v98, vcc
	v_cmp_lt_i32_e32 vcc, v99, v95
	v_lshlrev_b32_e32 v47, 2, v21
	s_nop 0
	v_cndmask_b32_e32 v21, v93, v99, vcc
	v_lshlrev_b32_e32 v48, 2, v21
	v_mul_f32_e32 v21, v122, v122
	v_fmac_f32_e32 v21, v138, v138
	v_fmac_f32_e32 v21, v106, v106
	v_fmac_f32_e32 v21, v19, v19
	s_nop 1
	v_add_f32_dpp v21, v21, v21 quad_perm:[1,0,3,2] row_mask:0xf bank_mask:0xf
	s_nop 1
	v_add_f32_dpp v21, v21, v21 quad_perm:[2,3,0,1] row_mask:0xf bank_mask:0xf
	s_nop 1
	v_add_f32_dpp v21, v21, v21 row_half_mirror row_mask:0xf bank_mask:0xf
	s_nop 1
	v_add_f32_dpp v21, v21, v21 row_mirror row_mask:0xf bank_mask:0xf
	v_mov_b32_e32 v22, v21
	v_mov_b32_e32 v23, v21
	s_nop 1
	v_permlane16_swap_b32_e32 v22, v23
	v_add_f32_e32 v21, v22, v23
	v_fmamk_f32 v21, v21, 0x3c000000, v100
	v_cmp_gt_f32_e32 vcc, s33, v21
	v_mul_f32_e32 v22, 0x4f800000, v21
	s_nop 0
	v_cndmask_b32_e32 v21, v21, v22, vcc
	v_sqrt_f32_e32 v22, v21
	s_nop 0
	v_add_u32_e32 v23, -1, v22
	v_fma_f32 v24, -v23, v22, v21
	v_cmp_ge_f32_e64 s[8:9], 0, v24
	v_add_u32_e32 v24, 1, v22
	s_nop 0
	v_cndmask_b32_e64 v23, v22, v23, s[8:9]
	v_fma_f32 v22, -v24, v22, v21
	v_cmp_lt_f32_e64 s[8:9], 0, v22
	s_nop 1
	v_cndmask_b32_e64 v22, v23, v24, s[8:9]
	v_mul_f32_e32 v23, 0x37800000, v22
	v_cndmask_b32_e32 v22, v22, v23, vcc
	v_cmp_class_f32_e32 vcc, v21, v101
	s_nop 1
	v_cndmask_b32_e32 v21, v22, v21, vcc
	s_nop 0
	v_div_scale_f32 v24, vcc, 1.0, v21, 1.0
	v_rcp_f32_e32 v46, v21
	v_mul_f32_e32 v21, v121, v121
; DI void gla_stage3(const Ctx& c0, int layer, int unit, int cb, LAS unsigned char* lds) {
;     ...
;     float rs[16];
; #pragma unroll
;     for (int rg = 0; rg < 16; ++rg) { float ss = o[0][rg] * o[0][rg] + o[1][rg] * o[1][rg] + o[2][rg] * o[2][rg] + o[3][rg] * o[3][rg];
;         ss += __shfl_xor(ss, 1); ss += __shfl_xor(ss, 2); ss += __shfl_xor(ss, 4); ss += __shfl_xor(ss, 8); ss += __shfl_xor(ss, 16);
;         rs[rg] = 1.f / sqrtf(ss * (1.f / 128.f) + EPS); }
	v_fmac_f32_e32 v21, v137, v137
	v_fmac_f32_e32 v21, v105, v105
	v_fmac_f32_e32 v21, v18, v18
	s_nop 1
	v_add_f32_dpp v21, v21, v21 quad_perm:[1,0,3,2] row_mask:0xf bank_mask:0xf
	v_mul_f32_e32 v19, v19, v46
	s_nop 1
	v_add_f32_dpp v21, v21, v21 quad_perm:[2,3,0,1] row_mask:0xf bank_mask:0xf
	s_nop 1
	v_add_f32_dpp v21, v21, v21 row_half_mirror row_mask:0xf bank_mask:0xf
	s_nop 1
	v_add_f32_dpp v21, v21, v21 row_mirror row_mask:0xf bank_mask:0xf
	v_mov_b32_e32 v22, v21
	v_mov_b32_e32 v23, v21
	s_nop 1
	v_permlane16_swap_b32_e32 v22, v23
	v_add_f32_e32 v21, v22, v23
	v_fmamk_f32 v21, v21, 0x3c000000, v100
	v_cmp_gt_f32_e32 vcc, s33, v21
	v_mul_f32_e32 v22, 0x4f800000, v21
	s_nop 0
	v_cndmask_b32_e32 v21, v21, v22, vcc
	v_sqrt_f32_e32 v22, v21
	s_nop 0
	v_add_u32_e32 v23, -1, v22
	v_fma_f32 v24, -v23, v22, v21
	v_cmp_ge_f32_e64 s[8:9], 0, v24
	v_add_u32_e32 v24, 1, v22
	s_nop 0
	v_cndmask_b32_e64 v23, v22, v23, s[8:9]
	v_fma_f32 v22, -v24, v22, v21
	v_cmp_lt_f32_e64 s[8:9], 0, v22
	s_nop 1
	v_cndmask_b32_e64 v22, v23, v24, s[8:9]
	v_mul_f32_e32 v23, 0x37800000, v22
	v_cndmask_b32_e32 v22, v22, v23, vcc
	v_cmp_class_f32_e32 vcc, v21, v101
	s_nop 1
	v_cndmask_b32_e32 v21, v22, v21, vcc
	s_nop 0
	v_div_scale_f32 v24, vcc, 1.0, v21, 1.0
	v_rcp_f32_e32 v45, v21
	v_mul_f32_e32 v21, v120, v120
	v_fmac_f32_e32 v21, v136, v136
	v_fmac_f32_e32 v21, v104, v104
	v_fmac_f32_e32 v21, v17, v17
	s_nop 1
	v_add_f32_dpp v21, v21, v21 quad_perm:[1,0,3,2] row_mask:0xf bank_mask:0xf
	v_mul_f32_e32 v18, v18, v45
	s_nop 1
	v_add_f32_dpp v21, v21, v21 quad_perm:[2,3,0,1] row_mask:0xf bank_mask:0xf
	s_nop 1
	v_add_f32_dpp v21, v21, v21 row_half_mirror row_mask:0xf bank_mask:0xf
	s_nop 1
	v_add_f32_dpp v21, v21, v21 row_mirror row_mask:0xf bank_mask:0xf
	v_mov_b32_e32 v22, v21
	v_mov_b32_e32 v23, v21
	s_nop 1
	v_permlane16_swap_b32_e32 v22, v23
	v_add_f32_e32 v21, v22, v23
	v_fmamk_f32 v21, v21, 0x3c000000, v100
	v_cmp_gt_f32_e32 vcc, s33, v21
	v_mul_f32_e32 v22, 0x4f800000, v21
	s_nop 0
	v_cndmask_b32_e32 v21, v21, v22, vcc
	v_sqrt_f32_e32 v22, v21
	s_nop 0
	v_add_u32_e32 v23, -1, v22
	v_fma_f32 v24, -v23, v22, v21
	v_cmp_ge_f32_e64 s[8:9], 0, v24
	v_add_u32_e32 v24, 1, v22
	s_nop 0
	v_cndmask_b32_e64 v23, v22, v23, s[8:9]
	v_fma_f32 v22, -v24, v22, v21
	v_cmp_lt_f32_e64 s[8:9], 0, v22
	s_nop 1
	v_cndmask_b32_e64 v22, v23, v24, s[8:9]
	v_mul_f32_e32 v23, 0x37800000, v22
	v_cndmask_b32_e32 v22, v22, v23, vcc
	v_cmp_class_f32_e32 vcc, v21, v101
	s_nop 1
	v_cndmask_b32_e32 v21, v22, v21, vcc
	s_nop 0
	v_div_scale_f32 v24, vcc, 1.0, v21, 1.0
	v_rcp_f32_e32 v44, v21
	v_mul_f32_e32 v21, v119, v119
	v_fmac_f32_e32 v21, v135, v135
	v_fmac_f32_e32 v21, v103, v103
	v_fmac_f32_e32 v21, v16, v16
	s_nop 1
	v_add_f32_dpp v21, v21, v21 quad_perm:[1,0,3,2] row_mask:0xf bank_mask:0xf
	v_mul_f32_e32 v17, v17, v44
	s_nop 1
	v_add_f32_dpp v21, v21, v21 quad_perm:[2,3,0,1] row_mask:0xf bank_mask:0xf
	s_nop 1
	v_add_f32_dpp v21, v21, v21 row_half_mirror row_mask:0xf bank_mask:0xf
	s_nop 1
	v_add_f32_dpp v21, v21, v21 row_mirror row_mask:0xf bank_mask:0xf
	v_mov_b32_e32 v22, v21
	v_mov_b32_e32 v23, v21
	s_nop 1
	v_permlane16_swap_b32_e32 v22, v23
	v_add_f32_e32 v21, v22, v23
	v_fmamk_f32 v21, v21, 0x3c000000, v100
	v_cmp_gt_f32_e32 vcc, s33, v21
	v_mul_f32_e32 v22, 0x4f800000, v21
	s_nop 0
	v_cndmask_b32_e32 v21, v21, v22, vcc
	v_sqrt_f32_e32 v22, v21
	s_nop 0
	v_add_u32_e32 v23, -1, v22
	v_fma_f32 v24, -v23, v22, v21
	v_cmp_ge_f32_e64 s[8:9], 0, v24
	v_add_u32_e32 v24, 1, v22
	s_nop 0
	v_cndmask_b32_e64 v23, v22, v23, s[8:9]
	v_fma_f32 v22, -v24, v22, v21
	v_cmp_lt_f32_e64 s[8:9], 0, v22
	s_nop 1
	v_cndmask_b32_e64 v22, v23, v24, s[8:9]
	v_mul_f32_e32 v23, 0x37800000, v22
	v_cndmask_b32_e32 v22, v22, v23, vcc
	v_cmp_class_f32_e32 vcc, v21, v101
	s_nop 1
	v_cndmask_b32_e32 v21, v22, v21, vcc
	s_nop 0
	v_div_scale_f32 v24, vcc, 1.0, v21, 1.0
	v_rcp_f32_e32 v43, v21
	v_mul_f32_e32 v21, v118, v118
	v_fmac_f32_e32 v21, v134, v134
	v_fmac_f32_e32 v21, v102, v102
	v_fmac_f32_e32 v21, v15, v15
	s_nop 1
	v_add_f32_dpp v21, v21, v21 quad_perm:[1,0,3,2] row_mask:0xf bank_mask:0xf
	v_mul_f32_e32 v16, v16, v43
	s_nop 1
	v_add_f32_dpp v21, v21, v21 quad_perm:[2,3,0,1] row_mask:0xf bank_mask:0xf
	s_nop 1
	v_add_f32_dpp v21, v21, v21 row_half_mirror row_mask:0xf bank_mask:0xf
	s_nop 1
	v_add_f32_dpp v21, v21, v21 row_mirror row_mask:0xf bank_mask:0xf
	v_mov_b32_e32 v22, v21
	v_mov_b32_e32 v23, v21
	s_nop 1
	v_permlane16_swap_b32_e32 v22, v23
	v_add_f32_e32 v21, v22, v23
	v_fmamk_f32 v21, v21, 0x3c000000, v100
	v_cmp_gt_f32_e32 vcc, s33, v21
	v_mul_f32_e32 v22, 0x4f800000, v21
	s_nop 0
	v_cndmask_b32_e32 v21, v21, v22, vcc
	v_sqrt_f32_e32 v22, v21
	s_nop 0
	v_add_u32_e32 v23, -1, v22
	v_fma_f32 v24, -v23, v22, v21
	v_cmp_ge_f32_e64 s[8:9], 0, v24
	v_add_u32_e32 v24, 1, v22
	s_nop 0
	v_cndmask_b32_e64 v23, v22, v23, s[8:9]
	v_fma_f32 v22, -v24, v22, v21
	v_cmp_lt_f32_e64 s[8:9], 0, v22
	s_nop 1
	v_cndmask_b32_e64 v22, v23, v24, s[8:9]
	v_mul_f32_e32 v23, 0x37800000, v22
	v_cndmask_b32_e32 v22, v22, v23, vcc
	v_cmp_class_f32_e32 vcc, v21, v101
	s_nop 1
	v_cndmask_b32_e32 v21, v22, v21, vcc
	s_nop 0
	v_div_scale_f32 v24, vcc, 1.0, v21, 1.0
	v_rcp_f32_e32 v42, v21
	v_mul_f32_e32 v21, v117, v117
	v_fmac_f32_e32 v21, v133, v133
	v_fmac_f32_e32 v21, v39, v39
	v_fmac_f32_e32 v21, v14, v14
	s_nop 1
	v_add_f32_dpp v21, v21, v21 quad_perm:[1,0,3,2] row_mask:0xf bank_mask:0xf
	v_mul_f32_e32 v15, v15, v42
	s_nop 1
	v_add_f32_dpp v21, v21, v21 quad_perm:[2,3,0,1] row_mask:0xf bank_mask:0xf
	s_nop 1
	v_add_f32_dpp v21, v21, v21 row_half_mirror row_mask:0xf bank_mask:0xf
	s_nop 1
	v_add_f32_dpp v21, v21, v21 row_mirror row_mask:0xf bank_mask:0xf
; DI void gla_stage3(const Ctx& c0, int layer, int unit, int cb, LAS unsigned char* lds) {
;     ...
;     float rs[16];
; #pragma unroll
;     for (int rg = 0; rg < 16; ++rg) { float ss = o[0][rg] * o[0][rg] + o[1][rg] * o[1][rg] + o[2][rg] * o[2][rg] + o[3][rg] * o[3][rg];
;         ss += __shfl_xor(ss, 1); ss += __shfl_xor(ss, 2); ss += __shfl_xor(ss, 4); ss += __shfl_xor(ss, 8); ss += __shfl_xor(ss, 16);
;         rs[rg] = 1.f / sqrtf(ss * (1.f / 128.f) + EPS); }
	v_mov_b32_e32 v22, v21
	v_mov_b32_e32 v23, v21
	s_nop 1
	v_permlane16_swap_b32_e32 v22, v23
	v_add_f32_e32 v21, v22, v23
	v_fmamk_f32 v21, v21, 0x3c000000, v100
	v_cmp_gt_f32_e32 vcc, s33, v21
	v_mul_f32_e32 v22, 0x4f800000, v21
	s_nop 0
	v_cndmask_b32_e32 v21, v21, v22, vcc
	v_sqrt_f32_e32 v22, v21
	s_nop 0
	v_add_u32_e32 v23, -1, v22
	v_fma_f32 v24, -v23, v22, v21
	v_cmp_ge_f32_e64 s[8:9], 0, v24
	v_add_u32_e32 v24, 1, v22
	s_nop 0
	v_cndmask_b32_e64 v23, v22, v23, s[8:9]
	v_fma_f32 v22, -v24, v22, v21
	v_cmp_lt_f32_e64 s[8:9], 0, v22
	s_nop 1
	v_cndmask_b32_e64 v22, v23, v24, s[8:9]
	v_mul_f32_e32 v23, 0x37800000, v22
	v_cndmask_b32_e32 v22, v22, v23, vcc
	v_cmp_class_f32_e32 vcc, v21, v101
	s_nop 1
	v_cndmask_b32_e32 v21, v22, v21, vcc
	s_nop 0
	v_div_scale_f32 v24, vcc, 1.0, v21, 1.0
	v_rcp_f32_e32 v41, v21
	v_mul_f32_e32 v21, v116, v116
	v_fmac_f32_e32 v21, v132, v132
	v_fmac_f32_e32 v21, v38, v38
	v_fmac_f32_e32 v21, v13, v13
	s_nop 1
	v_add_f32_dpp v21, v21, v21 quad_perm:[1,0,3,2] row_mask:0xf bank_mask:0xf
	v_mul_f32_e32 v39, v39, v41
	v_mul_f32_e32 v14, v14, v41
	s_nop 1
	v_add_f32_dpp v21, v21, v21 quad_perm:[2,3,0,1] row_mask:0xf bank_mask:0xf
	s_nop 1
	v_add_f32_dpp v21, v21, v21 row_half_mirror row_mask:0xf bank_mask:0xf
	s_nop 1
	v_add_f32_dpp v21, v21, v21 row_mirror row_mask:0xf bank_mask:0xf
	v_mov_b32_e32 v22, v21
	v_mov_b32_e32 v23, v21
	s_nop 1
	v_permlane16_swap_b32_e32 v22, v23
	v_add_f32_e32 v21, v22, v23
	v_fmamk_f32 v21, v21, 0x3c000000, v100
	v_cmp_gt_f32_e32 vcc, s33, v21
	v_mul_f32_e32 v22, 0x4f800000, v21
	s_nop 0
	v_cndmask_b32_e32 v21, v21, v22, vcc
	v_sqrt_f32_e32 v22, v21
	s_nop 0
	v_add_u32_e32 v23, -1, v22
	v_fma_f32 v24, -v23, v22, v21
	v_cmp_ge_f32_e64 s[8:9], 0, v24
	v_add_u32_e32 v24, 1, v22
	s_nop 0
	v_cndmask_b32_e64 v23, v22, v23, s[8:9]
	v_fma_f32 v22, -v24, v22, v21
	v_cmp_lt_f32_e64 s[8:9], 0, v22
	s_nop 1
	v_cndmask_b32_e64 v22, v23, v24, s[8:9]
	v_mul_f32_e32 v23, 0x37800000, v22
	v_cndmask_b32_e32 v22, v22, v23, vcc
	v_cmp_class_f32_e32 vcc, v21, v101
	s_nop 1
	v_cndmask_b32_e32 v21, v22, v21, vcc
	s_nop 0
	v_div_scale_f32 v24, vcc, 1.0, v21, 1.0
	v_rcp_f32_e32 v40, v21
	v_mul_f32_e32 v21, v115, v115
	v_fmac_f32_e32 v21, v131, v131
	v_fmac_f32_e32 v21, v37, v37
	v_fmac_f32_e32 v21, v12, v12
	s_nop 1
	v_add_f32_dpp v21, v21, v21 quad_perm:[1,0,3,2] row_mask:0xf bank_mask:0xf
	v_mul_f32_e32 v38, v38, v40
	v_mul_f32_e32 v13, v13, v40
	s_nop 1
	v_add_f32_dpp v21, v21, v21 quad_perm:[2,3,0,1] row_mask:0xf bank_mask:0xf
	s_nop 1
	v_add_f32_dpp v21, v21, v21 row_half_mirror row_mask:0xf bank_mask:0xf
	s_nop 1
	v_add_f32_dpp v21, v21, v21 row_mirror row_mask:0xf bank_mask:0xf
	v_mov_b32_e32 v22, v21
	v_mov_b32_e32 v23, v21
	s_nop 1
	v_permlane16_swap_b32_e32 v22, v23
	v_add_f32_e32 v21, v22, v23
	v_fmamk_f32 v21, v21, 0x3c000000, v100
	v_cmp_gt_f32_e32 vcc, s33, v21
	v_mul_f32_e32 v22, 0x4f800000, v21
	s_nop 0
	v_cndmask_b32_e32 v21, v21, v22, vcc
	v_sqrt_f32_e32 v22, v21
	s_nop 0
	v_add_u32_e32 v23, -1, v22
	v_fma_f32 v24, -v23, v22, v21
	v_cmp_ge_f32_e64 s[8:9], 0, v24
	v_add_u32_e32 v24, 1, v22
	s_nop 0
	v_cndmask_b32_e64 v23, v22, v23, s[8:9]
	v_fma_f32 v22, -v24, v22, v21
	v_cmp_lt_f32_e64 s[8:9], 0, v22
	s_nop 1
	v_cndmask_b32_e64 v22, v23, v24, s[8:9]
	v_mul_f32_e32 v23, 0x37800000, v22
	v_cndmask_b32_e32 v22, v22, v23, vcc
	v_cmp_class_f32_e32 vcc, v21, v101
	s_nop 1
	v_cndmask_b32_e32 v21, v22, v21, vcc
	s_nop 0
	v_div_scale_f32 v24, vcc, 1.0, v21, 1.0
	v_rcp_f32_e32 v35, v21
	v_mul_f32_e32 v21, v114, v114
	v_fmac_f32_e32 v21, v130, v130
	v_fmac_f32_e32 v21, v36, v36
	v_fmac_f32_e32 v21, v11, v11
	s_nop 1
	v_add_f32_dpp v21, v21, v21 quad_perm:[1,0,3,2] row_mask:0xf bank_mask:0xf
	v_mul_f32_e32 v37, v37, v35
	v_mul_f32_e32 v12, v12, v35
	s_nop 1
	v_add_f32_dpp v21, v21, v21 quad_perm:[2,3,0,1] row_mask:0xf bank_mask:0xf
	s_nop 1
	v_add_f32_dpp v21, v21, v21 row_half_mirror row_mask:0xf bank_mask:0xf
	s_nop 1
	v_add_f32_dpp v21, v21, v21 row_mirror row_mask:0xf bank_mask:0xf
	v_mov_b32_e32 v22, v21
	v_mov_b32_e32 v23, v21
	s_nop 1
	v_permlane16_swap_b32_e32 v22, v23
	v_add_f32_e32 v21, v22, v23
	v_fmamk_f32 v21, v21, 0x3c000000, v100
	v_cmp_gt_f32_e32 vcc, s33, v21
	v_mul_f32_e32 v22, 0x4f800000, v21
	s_nop 0
	v_cndmask_b32_e32 v21, v21, v22, vcc
	v_sqrt_f32_e32 v22, v21
	s_nop 0
	v_add_u32_e32 v23, -1, v22
	v_fma_f32 v24, -v23, v22, v21
	v_cmp_ge_f32_e64 s[8:9], 0, v24
	v_add_u32_e32 v24, 1, v22
	s_nop 0
	v_cndmask_b32_e64 v23, v22, v23, s[8:9]
	v_fma_f32 v22, -v24, v22, v21
	v_cmp_lt_f32_e64 s[8:9], 0, v22
	s_nop 1
	v_cndmask_b32_e64 v22, v23, v24, s[8:9]
	v_mul_f32_e32 v23, 0x37800000, v22
	v_cndmask_b32_e32 v22, v22, v23, vcc
	v_cmp_class_f32_e32 vcc, v21, v101
	s_nop 1
	v_cndmask_b32_e32 v21, v22, v21, vcc
	s_nop 0
	v_div_scale_f32 v24, vcc, 1.0, v21, 1.0
	v_rcp_f32_e32 v31, v21
	v_mul_f32_e32 v21, v113, v113
	v_fmac_f32_e32 v21, v129, v129
	v_fmac_f32_e32 v21, v34, v34
	v_fmac_f32_e32 v21, v10, v10
	s_nop 1
	v_add_f32_dpp v21, v21, v21 quad_perm:[1,0,3,2] row_mask:0xf bank_mask:0xf
	v_mul_f32_e32 v36, v36, v31
	v_mul_f32_e32 v11, v11, v31
	s_nop 1
	v_add_f32_dpp v21, v21, v21 quad_perm:[2,3,0,1] row_mask:0xf bank_mask:0xf
	s_nop 1
	v_add_f32_dpp v21, v21, v21 row_half_mirror row_mask:0xf bank_mask:0xf
	s_nop 1
	v_add_f32_dpp v21, v21, v21 row_mirror row_mask:0xf bank_mask:0xf
	v_mov_b32_e32 v22, v21
	v_mov_b32_e32 v23, v21
	s_nop 1
	v_permlane16_swap_b32_e32 v22, v23
	v_add_f32_e32 v21, v22, v23
	v_fmamk_f32 v21, v21, 0x3c000000, v100
	v_cmp_gt_f32_e32 vcc, s33, v21
	v_mul_f32_e32 v22, 0x4f800000, v21
	s_nop 0
	v_cndmask_b32_e32 v21, v21, v22, vcc
	v_sqrt_f32_e32 v22, v21
	s_nop 0
; DI void gla_stage3(const Ctx& c0, int layer, int unit, int cb, LAS unsigned char* lds) {
;     ...
;     float rs[16];
; #pragma unroll
;     for (int rg = 0; rg < 16; ++rg) { float ss = o[0][rg] * o[0][rg] + o[1][rg] * o[1][rg] + o[2][rg] * o[2][rg] + o[3][rg] * o[3][rg];
;         ss += __shfl_xor(ss, 1); ss += __shfl_xor(ss, 2); ss += __shfl_xor(ss, 4); ss += __shfl_xor(ss, 8); ss += __shfl_xor(ss, 16);
;         rs[rg] = 1.f / sqrtf(ss * (1.f / 128.f) + EPS); }
	v_add_u32_e32 v23, -1, v22
	v_fma_f32 v24, -v23, v22, v21
	v_cmp_ge_f32_e64 s[8:9], 0, v24
	v_add_u32_e32 v24, 1, v22
	s_nop 0
	v_cndmask_b32_e64 v23, v22, v23, s[8:9]
	v_fma_f32 v22, -v24, v22, v21
	v_cmp_lt_f32_e64 s[8:9], 0, v22
	s_nop 1
	v_cndmask_b32_e64 v22, v23, v24, s[8:9]
	v_mul_f32_e32 v23, 0x37800000, v22
	v_cndmask_b32_e32 v22, v22, v23, vcc
	v_cmp_class_f32_e32 vcc, v21, v101
	s_nop 1
	v_cndmask_b32_e32 v21, v22, v21, vcc
	s_nop 0
	v_div_scale_f32 v24, vcc, 1.0, v21, 1.0
	v_rcp_f32_e32 v27, v21
	v_mul_f32_e32 v21, v112, v112
	v_fmac_f32_e32 v21, v128, v128
	v_fmac_f32_e32 v21, v33, v33
	v_fmac_f32_e32 v21, v9, v9
	s_nop 1
	v_add_f32_dpp v21, v21, v21 quad_perm:[1,0,3,2] row_mask:0xf bank_mask:0xf
	v_mul_f32_e32 v34, v34, v27
	v_mul_f32_e32 v10, v10, v27
	s_nop 1
	v_add_f32_dpp v21, v21, v21 quad_perm:[2,3,0,1] row_mask:0xf bank_mask:0xf
	s_nop 1
	v_add_f32_dpp v21, v21, v21 row_half_mirror row_mask:0xf bank_mask:0xf
	s_nop 1
	v_add_f32_dpp v21, v21, v21 row_mirror row_mask:0xf bank_mask:0xf
	v_mov_b32_e32 v22, v21
	v_mov_b32_e32 v23, v21
	s_nop 1
	v_permlane16_swap_b32_e32 v22, v23
	v_add_f32_e32 v21, v22, v23
	v_fmamk_f32 v21, v21, 0x3c000000, v100
	v_cmp_gt_f32_e32 vcc, s33, v21
	v_mul_f32_e32 v22, 0x4f800000, v21
	s_nop 0
	v_cndmask_b32_e32 v21, v21, v22, vcc
	v_sqrt_f32_e32 v22, v21
	s_nop 0
	v_add_u32_e32 v23, -1, v22
	v_fma_f32 v24, -v23, v22, v21
	v_cmp_ge_f32_e64 s[8:9], 0, v24
	v_add_u32_e32 v24, 1, v22
	s_nop 0
	v_cndmask_b32_e64 v23, v22, v23, s[8:9]
	v_fma_f32 v22, -v24, v22, v21
	v_cmp_lt_f32_e64 s[8:9], 0, v22
	s_nop 1
	v_cndmask_b32_e64 v22, v23, v24, s[8:9]
	v_mul_f32_e32 v23, 0x37800000, v22
	v_cndmask_b32_e32 v22, v22, v23, vcc
	v_cmp_class_f32_e32 vcc, v21, v101
	s_nop 1
	v_cndmask_b32_e32 v21, v22, v21, vcc
	s_nop 0
	v_div_scale_f32 v24, vcc, 1.0, v21, 1.0
	v_rcp_f32_e32 v25, v21
	v_mul_f32_e32 v21, v111, v111
	v_fmac_f32_e32 v21, v127, v127
	v_fmac_f32_e32 v21, v32, v32
	v_fmac_f32_e32 v21, v8, v8
	s_nop 1
	v_add_f32_dpp v21, v21, v21 quad_perm:[1,0,3,2] row_mask:0xf bank_mask:0xf
	v_mul_f32_e32 v33, v33, v25
	v_mul_f32_e32 v9, v9, v25
	s_nop 1
	v_add_f32_dpp v21, v21, v21 quad_perm:[2,3,0,1] row_mask:0xf bank_mask:0xf
	s_nop 1
	v_add_f32_dpp v21, v21, v21 row_half_mirror row_mask:0xf bank_mask:0xf
	s_nop 1
	v_add_f32_dpp v21, v21, v21 row_mirror row_mask:0xf bank_mask:0xf
	v_mov_b32_e32 v22, v21
	v_mov_b32_e32 v23, v21
	s_nop 1
	v_permlane16_swap_b32_e32 v22, v23
	v_add_f32_e32 v21, v22, v23
	v_fmamk_f32 v21, v21, 0x3c000000, v100
	v_cmp_gt_f32_e32 vcc, s33, v21
	v_mul_f32_e32 v22, 0x4f800000, v21
	s_nop 0
	v_cndmask_b32_e32 v21, v21, v22, vcc
	v_sqrt_f32_e32 v22, v21
	s_nop 0
	v_add_u32_e32 v23, -1, v22
	v_fma_f32 v24, -v23, v22, v21
	v_cmp_ge_f32_e64 s[8:9], 0, v24
	v_add_u32_e32 v24, 1, v22
	s_nop 0
	v_cndmask_b32_e64 v23, v22, v23, s[8:9]
	v_fma_f32 v22, -v24, v22, v21
	v_cmp_lt_f32_e64 s[8:9], 0, v22
	s_nop 1
	v_cndmask_b32_e64 v22, v23, v24, s[8:9]
	v_mul_f32_e32 v23, 0x37800000, v22
	v_cndmask_b32_e32 v22, v22, v23, vcc
	v_cmp_class_f32_e32 vcc, v21, v101
	s_nop 1
	v_cndmask_b32_e32 v21, v22, v21, vcc
	s_nop 0
	v_div_scale_f32 v24, vcc, 1.0, v21, 1.0
	v_rcp_f32_e32 v24, v21
	v_mul_f32_e32 v21, v110, v110
	v_fmac_f32_e32 v21, v126, v126
	v_fmac_f32_e32 v21, v30, v30
	v_fmac_f32_e32 v21, v7, v7
	s_nop 1
	v_add_f32_dpp v21, v21, v21 quad_perm:[1,0,3,2] row_mask:0xf bank_mask:0xf
	v_mul_f32_e32 v32, v32, v24
	v_mul_f32_e32 v8, v8, v24
	s_nop 1
	v_add_f32_dpp v21, v21, v21 quad_perm:[2,3,0,1] row_mask:0xf bank_mask:0xf
	s_nop 1
	v_add_f32_dpp v21, v21, v21 row_half_mirror row_mask:0xf bank_mask:0xf
	s_nop 1
	v_add_f32_dpp v21, v21, v21 row_mirror row_mask:0xf bank_mask:0xf
	v_mov_b32_e32 v22, v21
	v_mov_b32_e32 v23, v21
	s_nop 1
	v_permlane16_swap_b32_e32 v22, v23
	v_add_f32_e32 v21, v22, v23
	v_fmamk_f32 v21, v21, 0x3c000000, v100
	v_cmp_gt_f32_e32 vcc, s33, v21
	v_mul_f32_e32 v22, 0x4f800000, v21
	s_nop 0
	v_cndmask_b32_e32 v21, v21, v22, vcc
	v_sqrt_f32_e32 v22, v21
	s_nop 0
	v_add_u32_e32 v23, -1, v22
	v_fma_f32 v49, -v23, v22, v21
	v_cmp_ge_f32_e64 s[8:9], 0, v49
	v_add_u32_e32 v49, 1, v22
	s_nop 0
	v_cndmask_b32_e64 v23, v22, v23, s[8:9]
	v_fma_f32 v22, -v49, v22, v21
	v_cmp_lt_f32_e64 s[8:9], 0, v22
	s_nop 1
	v_cndmask_b32_e64 v22, v23, v49, s[8:9]
	v_mul_f32_e32 v23, 0x37800000, v22
	v_cndmask_b32_e32 v22, v22, v23, vcc
	v_cmp_class_f32_e32 vcc, v21, v101
	s_nop 1
	v_cndmask_b32_e32 v21, v22, v21, vcc
	s_nop 0
	v_div_scale_f32 v49, vcc, 1.0, v21, 1.0
	v_rcp_f32_e32 v23, v21
	v_mul_f32_e32 v21, v109, v109
	v_fmac_f32_e32 v21, v125, v125
	v_fmac_f32_e32 v21, v29, v29
	v_fmac_f32_e32 v21, v6, v6
	s_nop 1
	v_add_f32_dpp v21, v21, v21 quad_perm:[1,0,3,2] row_mask:0xf bank_mask:0xf
	v_mul_f32_e32 v30, v30, v23
	v_mul_f32_e32 v7, v7, v23
	s_nop 1
	v_add_f32_dpp v21, v21, v21 quad_perm:[2,3,0,1] row_mask:0xf bank_mask:0xf
	s_nop 1
	v_add_f32_dpp v21, v21, v21 row_half_mirror row_mask:0xf bank_mask:0xf
	s_nop 1
	v_add_f32_dpp v21, v21, v21 row_mirror row_mask:0xf bank_mask:0xf
	v_mov_b32_e32 v22, v21
	v_mov_b32_e32 v49, v21
	s_nop 1
	v_permlane16_swap_b32_e32 v22, v49
	v_add_f32_e32 v21, v22, v49
	v_fmamk_f32 v21, v21, 0x3c000000, v100
	v_cmp_gt_f32_e32 vcc, s33, v21
	v_mul_f32_e32 v22, 0x4f800000, v21
	s_nop 0
	v_cndmask_b32_e32 v21, v21, v22, vcc
	v_sqrt_f32_e32 v22, v21
	s_nop 0
	v_add_u32_e32 v49, -1, v22
	v_fma_f32 v50, -v49, v22, v21
	v_cmp_ge_f32_e64 s[8:9], 0, v50
	v_add_u32_e32 v50, 1, v22
	s_nop 0
	v_cndmask_b32_e64 v49, v22, v49, s[8:9]
	v_fma_f32 v22, -v50, v22, v21
	v_cmp_lt_f32_e64 s[8:9], 0, v22
	s_nop 1
	v_cndmask_b32_e64 v22, v49, v50, s[8:9]
	v_mul_f32_e32 v49, 0x37800000, v22
; #define LAS __attribute__((address_space(3)))
; #define LDS_WAIT() asm volatile("s_waitcnt lgkmcnt(0)" ::: "memory")
; DI unsigned cvtpk(float lo, float hi) { f32x2 v = {lo, hi}; bf16x2_t b = __builtin_convertvector(v, bf16x2_t); return __builtin_bit_cast(unsigned, b); }
; DI float bf2f(bf16 b) { return __uint_as_float(((unsigned)b) << 16); }
; DI float siluf_(float x) { return x / (1.f + __expf(-x)); }
; DI void gla_stage3(const Ctx& c0, int layer, int unit, int cb, LAS unsigned char* lds) {
;     ...
; #pragma unroll
;     for (int rg = 0; rg < 16; ++rg) { float ss = o[0][rg] * o[0][rg] + o[1][rg] * o[1][rg] + o[2][rg] * o[2][rg] + o[3][rg] * o[3][rg];
;         ss += __shfl_xor(ss, 1); ss += __shfl_xor(ss, 2); ss += __shfl_xor(ss, 4); ss += __shfl_xor(ss, 8); ss += __shfl_xor(ss, 16);
;         rs[rg] = 1.f / sqrtf(ss * (1.f / 128.f) + EPS); }
;     LDS_WAIT();
;     g3_tile_in((const bf16*)(c.ws + O_GR) + row0 * 512 + h * 128, R, lane);
; #pragma unroll
;     for (int vb = 0; vb < 4; ++vb) { const float g = gn[32 * vb + r];
; #pragma unroll
;         for (int rg = 0; rg < 16; ++rg) { LAS bf16* e = (LAS bf16*)(R + (4 * hi) * G3_PITCH + r * 2 + ((rg & 3) + 8 * (rg >> 2)) * G3_PITCH + 64 * vb);
;             const float z = bf2f(*e);
;             *e = (bf16)(cvtpk(o[vb][rg] * rs[rg] * g * siluf_(z), 0.f) & 0xffffu); }
	v_cndmask_b32_e32 v22, v22, v49, vcc
	v_cmp_class_f32_e32 vcc, v21, v101
	s_nop 1
	v_cndmask_b32_e32 v21, v22, v21, vcc
	s_nop 0
	v_div_scale_f32 v50, vcc, 1.0, v21, 1.0
	v_rcp_f32_e32 v22, v21
	v_mul_f32_e32 v21, v108, v108
	v_fmac_f32_e32 v21, v124, v124
	v_fmac_f32_e32 v21, v28, v28
	v_fmac_f32_e32 v21, v5, v5
	s_nop 1
	v_add_f32_dpp v21, v21, v21 quad_perm:[1,0,3,2] row_mask:0xf bank_mask:0xf
	v_mul_f32_e32 v29, v29, v22
	v_mul_f32_e32 v6, v6, v22
	s_nop 1
	v_add_f32_dpp v21, v21, v21 quad_perm:[2,3,0,1] row_mask:0xf bank_mask:0xf
	s_nop 1
	v_add_f32_dpp v21, v21, v21 row_half_mirror row_mask:0xf bank_mask:0xf
	s_nop 1
	v_add_f32_dpp v21, v21, v21 row_mirror row_mask:0xf bank_mask:0xf
	v_mov_b32_e32 v49, v21
	v_mov_b32_e32 v50, v21
	s_nop 1
	v_permlane16_swap_b32_e32 v49, v50
	v_add_f32_e32 v21, v49, v50
	v_fmamk_f32 v21, v21, 0x3c000000, v100
	v_cmp_gt_f32_e32 vcc, s33, v21
	v_mul_f32_e32 v49, 0x4f800000, v21
	s_nop 0
	v_cndmask_b32_e32 v21, v21, v49, vcc
	v_sqrt_f32_e32 v49, v21
	s_nop 0
	v_add_u32_e32 v50, -1, v49
	v_fma_f32 v51, -v50, v49, v21
	v_cmp_ge_f32_e64 s[8:9], 0, v51
	v_add_u32_e32 v51, 1, v49
	s_nop 0
	v_cndmask_b32_e64 v50, v49, v50, s[8:9]
	v_fma_f32 v49, -v51, v49, v21
	v_cmp_lt_f32_e64 s[8:9], 0, v49
	s_nop 1
	v_cndmask_b32_e64 v49, v50, v51, s[8:9]
	v_mul_f32_e32 v50, 0x37800000, v49
	v_cndmask_b32_e32 v49, v49, v50, vcc
	v_cmp_class_f32_e32 vcc, v21, v101
	s_nop 1
	v_cndmask_b32_e32 v21, v49, v21, vcc
	s_nop 0
	v_div_scale_f32 v51, vcc, 1.0, v21, 1.0
	v_rcp_f32_e32 v21, v21
	v_mul_f32_e32 v49, v107, v107
	v_fmac_f32_e32 v49, v123, v123
	v_fmac_f32_e32 v49, v26, v26
	v_fmac_f32_e32 v49, v4, v4
	ds_bpermute_b32 v2, v2, v49
	v_mul_f32_e32 v28, v28, v21
	v_mul_f32_e32 v5, v5, v21
	s_waitcnt lgkmcnt(0)
	v_add_f32_e32 v2, v49, v2
	ds_bpermute_b32 v3, v3, v2
	s_waitcnt lgkmcnt(0)
	v_add_f32_e32 v2, v2, v3
	ds_bpermute_b32 v3, v20, v2
	s_waitcnt lgkmcnt(0)
	v_add_f32_e32 v2, v2, v3
	ds_bpermute_b32 v3, v47, v2
	s_waitcnt lgkmcnt(0)
	v_add_f32_e32 v2, v2, v3
	ds_bpermute_b32 v3, v48, v2
	s_waitcnt lgkmcnt(0)
	v_add_f32_e32 v2, v2, v3
	v_fmamk_f32 v2, v2, 0x3c000000, v100
	v_cmp_gt_f32_e32 vcc, s33, v2
	v_mul_f32_e32 v3, 0x4f800000, v2
	s_nop 0
	v_cndmask_b32_e32 v2, v2, v3, vcc
	v_sqrt_f32_e32 v3, v2
	s_nop 0
	v_add_u32_e32 v20, -1, v3
	v_fma_f32 v47, -v20, v3, v2
	v_cmp_ge_f32_e64 s[8:9], 0, v47
	v_add_u32_e32 v47, 1, v3
	s_nop 0
	v_cndmask_b32_e64 v20, v3, v20, s[8:9]
	v_fma_f32 v3, -v47, v3, v2
	v_cmp_lt_f32_e64 s[8:9], 0, v3
	s_nop 1
	v_cndmask_b32_e64 v3, v20, v47, s[8:9]
	v_mul_f32_e32 v20, 0x37800000, v3
	v_cndmask_b32_e32 v3, v3, v20, vcc
	v_cmp_class_f32_e32 vcc, v2, v101
	s_nop 1
	v_cndmask_b32_e32 v2, v3, v2, vcc
	s_nop 0
	v_rcp_f32_e32 v20, v2
	v_mul_f32_e32 v47, v138, v46
	v_mul_f32_e32 v26, v26, v20
	v_mul_f32_e32 v4, v4, v20
	s_waitcnt vmcnt(2) lgkmcnt(0)
	ds_write_b128 v92, v[164:167]
	s_waitcnt vmcnt(0) lgkmcnt(0)
	ds_write_b128 v92, v[170:173] offset:1088
	s_waitcnt vmcnt(13) lgkmcnt(0)
	ds_write_b128 v92, v[174:177] offset:2176
	s_waitcnt vmcnt(8) lgkmcnt(0)
	ds_write_b128 v92, v[178:181] offset:3264
	s_waitcnt vmcnt(9) lgkmcnt(0)
	ds_write_b128 v92, v[196:199] offset:4352
	s_waitcnt vmcnt(10) lgkmcnt(0)
	ds_write_b128 v92, v[200:203] offset:5440
	v_lshl_add_u64 v[2:3], v[168:169], 0, v[80:81]
	s_waitcnt vmcnt(5) lgkmcnt(0)
	ds_write_b128 v92, v[204:207] offset:6528
	global_load_dwordx4 v[48:51], v[2:3], off
	s_waitcnt vmcnt(0) lgkmcnt(0)
	ds_write_b128 v92, v[48:51] offset:7616
	s_waitcnt lgkmcnt(0)
	ds_read_u16 v3, v1
	s_waitcnt lgkmcnt(0)
	v_lshlrev_b32_e32 v3, 16, v3
	v_mul_f32_e32 v48, 0xbfb8aa3b, v3
	v_exp_f32_e32 v48, v48
	s_waitcnt vmcnt(0)
	v_mul_f32_e32 v47, v47, v232
	v_add_f32_e32 v48, 1.0, v48
	v_rcp_f32_e32 v49, v48
	s_nop 0
	v_mul_f32_e32 v3, v3, v49
	v_mul_f32_e32 v3, v47, v3
	v_cvt_pk_bf16_f32 v3, v3, v3
	ds_write_b16 v1, v3
	ds_read_u16 v3, v1 offset:272
	v_mul_f32_e32 v47, v137, v45
	v_mul_f32_e32 v47, v47, v232
	s_waitcnt lgkmcnt(0)
	v_lshlrev_b32_e32 v3, 16, v3
	v_mul_f32_e32 v48, 0xbfb8aa3b, v3
	v_exp_f32_e32 v48, v48
	s_nop 0
	v_add_f32_e32 v48, 1.0, v48
	v_rcp_f32_e32 v49, v48
	s_nop 0
	v_mul_f32_e32 v3, v3, v49
	v_mul_f32_e32 v3, v47, v3
	v_cvt_pk_bf16_f32 v3, v3, v3
	ds_write_b16 v1, v3 offset:272
	ds_read_u16 v3, v1 offset:544
	v_mul_f32_e32 v47, v136, v44
	v_mul_f32_e32 v47, v47, v232
	s_waitcnt lgkmcnt(0)
	v_lshlrev_b32_e32 v3, 16, v3
	v_mul_f32_e32 v48, 0xbfb8aa3b, v3
	v_exp_f32_e32 v48, v48
	s_nop 0
	v_add_f32_e32 v48, 1.0, v48
	v_rcp_f32_e32 v49, v48
	s_nop 0
	v_mul_f32_e32 v3, v3, v49
	v_mul_f32_e32 v3, v47, v3
	v_cvt_pk_bf16_f32 v3, v3, v3
	ds_write_b16 v1, v3 offset:544
	ds_read_u16 v3, v1 offset:816
	v_mul_f32_e32 v47, v135, v43
	v_mul_f32_e32 v47, v47, v232
	s_waitcnt lgkmcnt(0)
	v_lshlrev_b32_e32 v3, 16, v3
	v_mul_f32_e32 v48, 0xbfb8aa3b, v3
	v_exp_f32_e32 v48, v48
	s_nop 0
	v_add_f32_e32 v48, 1.0, v48
	v_rcp_f32_e32 v49, v48
	s_nop 0
	v_mul_f32_e32 v3, v3, v49
	v_mul_f32_e32 v3, v47, v3
	v_cvt_pk_bf16_f32 v3, v3, v3
	ds_write_b16 v1, v3 offset:816
	ds_read_u16 v3, v1 offset:2176
	v_mul_f32_e32 v47, v134, v42
	v_mul_f32_e32 v47, v47, v232
	s_waitcnt lgkmcnt(0)
	v_lshlrev_b32_e32 v3, 16, v3
	v_mul_f32_e32 v48, 0xbfb8aa3b, v3
	v_exp_f32_e32 v48, v48
	s_nop 0
	v_add_f32_e32 v48, 1.0, v48
	v_rcp_f32_e32 v49, v48
	s_nop 0
	v_mul_f32_e32 v3, v3, v49
	v_mul_f32_e32 v3, v47, v3
	v_cvt_pk_bf16_f32 v3, v3, v3
	ds_write_b16 v1, v3 offset:2176
	ds_read_u16 v3, v1 offset:2448
	v_mul_f32_e32 v47, v133, v41
	v_mul_f32_e32 v47, v47, v232
	s_waitcnt lgkmcnt(0)
; #define LAS __attribute__((address_space(3)))
; DI unsigned cvtpk(float lo, float hi) { f32x2 v = {lo, hi}; bf16x2_t b = __builtin_convertvector(v, bf16x2_t); return __builtin_bit_cast(unsigned, b); }
; DI float bf2f(bf16 b) { return __uint_as_float(((unsigned)b) << 16); }
; DI float siluf_(float x) { return x / (1.f + __expf(-x)); }
; DI void gla_stage3(const Ctx& c0, int layer, int unit, int cb, LAS unsigned char* lds) {
;     ...
;     for (int vb = 0; vb < 4; ++vb) { const float g = gn[32 * vb + r];
; #pragma unroll
;         for (int rg = 0; rg < 16; ++rg) { LAS bf16* e = (LAS bf16*)(R + (4 * hi) * G3_PITCH + r * 2 + ((rg & 3) + 8 * (rg >> 2)) * G3_PITCH + 64 * vb);
;             const float z = bf2f(*e);
;             *e = (bf16)(cvtpk(o[vb][rg] * rs[rg] * g * siluf_(z), 0.f) & 0xffffu); }
;         asm volatile("" ::: "memory"); }
	v_lshlrev_b32_e32 v3, 16, v3
	v_mul_f32_e32 v48, 0xbfb8aa3b, v3
	v_exp_f32_e32 v48, v48
	s_nop 0
	v_add_f32_e32 v48, 1.0, v48
	v_rcp_f32_e32 v49, v48
	s_nop 0
	v_mul_f32_e32 v3, v3, v49
	v_mul_f32_e32 v3, v47, v3
	v_cvt_pk_bf16_f32 v3, v3, v3
	ds_write_b16 v1, v3 offset:2448
	ds_read_u16 v3, v1 offset:2720
	v_mul_f32_e32 v47, v132, v40
	v_mul_f32_e32 v47, v47, v232
	s_waitcnt lgkmcnt(0)
	v_lshlrev_b32_e32 v3, 16, v3
	v_mul_f32_e32 v48, 0xbfb8aa3b, v3
	v_exp_f32_e32 v48, v48
	s_nop 0
	v_add_f32_e32 v48, 1.0, v48
	v_rcp_f32_e32 v49, v48
	s_nop 0
	v_mul_f32_e32 v3, v3, v49
	v_mul_f32_e32 v3, v47, v3
	v_cvt_pk_bf16_f32 v3, v3, v3
	ds_write_b16 v1, v3 offset:2720
	ds_read_u16 v3, v1 offset:2992
	v_mul_f32_e32 v47, v131, v35
	v_mul_f32_e32 v47, v47, v232
	s_waitcnt lgkmcnt(0)
	v_lshlrev_b32_e32 v3, 16, v3
	v_mul_f32_e32 v48, 0xbfb8aa3b, v3
	v_exp_f32_e32 v48, v48
	s_nop 0
	v_add_f32_e32 v48, 1.0, v48
	v_rcp_f32_e32 v49, v48
	s_nop 0
	v_mul_f32_e32 v3, v3, v49
	v_mul_f32_e32 v3, v47, v3
	v_cvt_pk_bf16_f32 v3, v3, v3
	ds_write_b16 v1, v3 offset:2992
	ds_read_u16 v3, v1 offset:4352
	v_mul_f32_e32 v47, v130, v31
	v_mul_f32_e32 v47, v47, v232
	s_waitcnt lgkmcnt(0)
	v_lshlrev_b32_e32 v3, 16, v3
	v_mul_f32_e32 v48, 0xbfb8aa3b, v3
	v_exp_f32_e32 v48, v48
	s_nop 0
	v_add_f32_e32 v48, 1.0, v48
	v_rcp_f32_e32 v49, v48
	s_nop 0
	v_mul_f32_e32 v3, v3, v49
	v_mul_f32_e32 v3, v47, v3
	v_cvt_pk_bf16_f32 v3, v3, v3
	ds_write_b16 v1, v3 offset:4352
	ds_read_u16 v3, v1 offset:4624
	v_mul_f32_e32 v47, v129, v27
	v_mul_f32_e32 v47, v47, v232
	s_waitcnt lgkmcnt(0)
	v_lshlrev_b32_e32 v3, 16, v3
	v_mul_f32_e32 v48, 0xbfb8aa3b, v3
	v_exp_f32_e32 v48, v48
	s_nop 0
	v_add_f32_e32 v48, 1.0, v48
	v_rcp_f32_e32 v49, v48
	s_nop 0
	v_mul_f32_e32 v3, v3, v49
	v_mul_f32_e32 v3, v47, v3
	v_cvt_pk_bf16_f32 v3, v3, v3
	ds_write_b16 v1, v3 offset:4624
	ds_read_u16 v3, v1 offset:4896
	v_mul_f32_e32 v47, v128, v25
	v_mul_f32_e32 v47, v47, v232
	s_waitcnt lgkmcnt(0)
	v_lshlrev_b32_e32 v3, 16, v3
	v_mul_f32_e32 v48, 0xbfb8aa3b, v3
	v_exp_f32_e32 v48, v48
	s_nop 0
	v_add_f32_e32 v48, 1.0, v48
	v_rcp_f32_e32 v49, v48
	s_nop 0
	v_mul_f32_e32 v3, v3, v49
	v_mul_f32_e32 v3, v47, v3
	v_cvt_pk_bf16_f32 v3, v3, v3
	ds_write_b16 v1, v3 offset:4896
	ds_read_u16 v3, v1 offset:5168
	v_mul_f32_e32 v47, v127, v24
	v_mul_f32_e32 v47, v47, v232
	s_waitcnt lgkmcnt(0)
	v_lshlrev_b32_e32 v3, 16, v3
	v_mul_f32_e32 v48, 0xbfb8aa3b, v3
	v_exp_f32_e32 v48, v48
	s_nop 0
	v_add_f32_e32 v48, 1.0, v48
	v_rcp_f32_e32 v49, v48
	s_nop 0
	v_mul_f32_e32 v3, v3, v49
	v_mul_f32_e32 v3, v47, v3
	v_cvt_pk_bf16_f32 v3, v3, v3
	ds_write_b16 v1, v3 offset:5168
	ds_read_u16 v3, v1 offset:6528
	v_mul_f32_e32 v47, v126, v23
	v_mul_f32_e32 v47, v47, v232
	s_waitcnt lgkmcnt(0)
	v_lshlrev_b32_e32 v3, 16, v3
	v_mul_f32_e32 v48, 0xbfb8aa3b, v3
	v_exp_f32_e32 v48, v48
	s_nop 0
	v_add_f32_e32 v48, 1.0, v48
	v_rcp_f32_e32 v49, v48
	s_nop 0
	v_mul_f32_e32 v3, v3, v49
	v_mul_f32_e32 v3, v47, v3
	v_cvt_pk_bf16_f32 v3, v3, v3
	ds_write_b16 v1, v3 offset:6528
	ds_read_u16 v3, v1 offset:6800
	v_mul_f32_e32 v47, v125, v22
	v_mul_f32_e32 v47, v47, v232
	s_waitcnt lgkmcnt(0)
	v_lshlrev_b32_e32 v3, 16, v3
	v_mul_f32_e32 v48, 0xbfb8aa3b, v3
	v_exp_f32_e32 v48, v48
	s_nop 0
	v_add_f32_e32 v48, 1.0, v48
	v_rcp_f32_e32 v49, v48
	s_nop 0
	v_mul_f32_e32 v3, v3, v49
	v_mul_f32_e32 v3, v47, v3
	v_cvt_pk_bf16_f32 v3, v3, v3
	ds_write_b16 v1, v3 offset:6800
	ds_read_u16 v3, v1 offset:7072
	v_mul_f32_e32 v47, v124, v21
	v_mul_f32_e32 v47, v47, v232
	s_waitcnt lgkmcnt(0)
	v_lshlrev_b32_e32 v3, 16, v3
	v_mul_f32_e32 v48, 0xbfb8aa3b, v3
	v_exp_f32_e32 v48, v48
	s_nop 0
	v_add_f32_e32 v48, 1.0, v48
	v_rcp_f32_e32 v49, v48
	s_nop 0
	v_mul_f32_e32 v3, v3, v49
	v_mul_f32_e32 v3, v47, v3
	v_cvt_pk_bf16_f32 v3, v3, v3
	ds_write_b16 v1, v3 offset:7072
	ds_read_u16 v3, v1 offset:7344
	v_mul_f32_e32 v47, v123, v20
	v_mul_f32_e32 v2, v47, v232
	s_waitcnt lgkmcnt(0)
	v_lshlrev_b32_e32 v3, 16, v3
	v_mul_f32_e32 v47, 0xbfb8aa3b, v3
	v_exp_f32_e32 v47, v47
	s_nop 0
	v_add_f32_e32 v47, 1.0, v47
	v_div_scale_f32 v48, s[0:1], v47, v47, v3
	s_nop 0
	v_rcp_f32_e32 v48, v47
	s_nop 0
	v_mul_f32_e32 v3, v3, v48
	v_mul_f32_e32 v2, v2, v3
	v_cvt_pk_bf16_f32 v2, v2, s0
	ds_write_b16 v1, v2 offset:7344
	ds_read_u16 v3, v1 offset:64
	v_mul_f32_e32 v47, v122, v46
	s_waitcnt lgkmcnt(0)
	v_lshlrev_b32_e32 v3, 16, v3
	v_mul_f32_e32 v48, 0xbfb8aa3b, v3
	v_exp_f32_e32 v48, v48
	s_waitcnt vmcnt(0)
	v_mul_f32_e32 v47, v47, v234
	v_add_f32_e32 v48, 1.0, v48
	v_rcp_f32_e32 v49, v48
	s_nop 0
	v_mul_f32_e32 v3, v3, v49
	v_mul_f32_e32 v3, v47, v3
	v_cvt_pk_bf16_f32 v3, v3, v3
	ds_write_b16 v1, v3 offset:64
	ds_read_u16 v3, v1 offset:336
	v_mul_f32_e32 v47, v121, v45
	v_mul_f32_e32 v47, v47, v234
	s_waitcnt lgkmcnt(0)
	v_lshlrev_b32_e32 v3, 16, v3
	v_mul_f32_e32 v48, 0xbfb8aa3b, v3
	v_exp_f32_e32 v48, v48
	s_nop 0
	v_add_f32_e32 v48, 1.0, v48
	v_rcp_f32_e32 v49, v48
	s_nop 0
	v_mul_f32_e32 v3, v3, v49
	v_mul_f32_e32 v3, v47, v3
	v_cvt_pk_bf16_f32 v3, v3, v3
	ds_write_b16 v1, v3 offset:336
	ds_read_u16 v3, v1 offset:608
	v_mul_f32_e32 v47, v120, v44
	v_mul_f32_e32 v47, v47, v234
	s_waitcnt lgkmcnt(0)
	v_lshlrev_b32_e32 v3, 16, v3
	v_mul_f32_e32 v48, 0xbfb8aa3b, v3
	v_exp_f32_e32 v48, v48
	s_nop 0
	v_add_f32_e32 v48, 1.0, v48
	v_rcp_f32_e32 v49, v48
	s_nop 0
	v_mul_f32_e32 v3, v3, v49
	v_mul_f32_e32 v3, v47, v3
	v_cvt_pk_bf16_f32 v3, v3, v3
	ds_write_b16 v1, v3 offset:608
	ds_read_u16 v3, v1 offset:880
	v_mul_f32_e32 v47, v119, v43
	v_mul_f32_e32 v47, v47, v234
	s_waitcnt lgkmcnt(0)
; #define LAS __attribute__((address_space(3)))
; DI unsigned cvtpk(float lo, float hi) { f32x2 v = {lo, hi}; bf16x2_t b = __builtin_convertvector(v, bf16x2_t); return __builtin_bit_cast(unsigned, b); }
; DI float bf2f(bf16 b) { return __uint_as_float(((unsigned)b) << 16); }
; DI float siluf_(float x) { return x / (1.f + __expf(-x)); }
; DI void gla_stage3(const Ctx& c0, int layer, int unit, int cb, LAS unsigned char* lds) {
;     ...
;     for (int vb = 0; vb < 4; ++vb) { const float g = gn[32 * vb + r];
; #pragma unroll
;         for (int rg = 0; rg < 16; ++rg) { LAS bf16* e = (LAS bf16*)(R + (4 * hi) * G3_PITCH + r * 2 + ((rg & 3) + 8 * (rg >> 2)) * G3_PITCH + 64 * vb);
;             const float z = bf2f(*e);
;             *e = (bf16)(cvtpk(o[vb][rg] * rs[rg] * g * siluf_(z), 0.f) & 0xffffu); }
;         asm volatile("" ::: "memory"); }
	v_lshlrev_b32_e32 v3, 16, v3
	v_mul_f32_e32 v48, 0xbfb8aa3b, v3
	v_exp_f32_e32 v48, v48
	s_nop 0
	v_add_f32_e32 v48, 1.0, v48
	v_rcp_f32_e32 v49, v48
	s_nop 0
	v_mul_f32_e32 v3, v3, v49
	v_mul_f32_e32 v3, v47, v3
	v_cvt_pk_bf16_f32 v3, v3, v3
	ds_write_b16 v1, v3 offset:880
	ds_read_u16 v3, v1 offset:2240
	v_mul_f32_e32 v47, v118, v42
	v_mul_f32_e32 v47, v47, v234
	s_waitcnt lgkmcnt(0)
	v_lshlrev_b32_e32 v3, 16, v3
	v_mul_f32_e32 v48, 0xbfb8aa3b, v3
	v_exp_f32_e32 v48, v48
	s_nop 0
	v_add_f32_e32 v48, 1.0, v48
	v_rcp_f32_e32 v49, v48
	s_nop 0
	v_mul_f32_e32 v3, v3, v49
	v_mul_f32_e32 v3, v47, v3
	v_cvt_pk_bf16_f32 v3, v3, v3
	ds_write_b16 v1, v3 offset:2240
	ds_read_u16 v3, v1 offset:2512
	v_mul_f32_e32 v47, v117, v41
	v_mul_f32_e32 v47, v47, v234
	s_waitcnt lgkmcnt(0)
	v_lshlrev_b32_e32 v3, 16, v3
	v_mul_f32_e32 v48, 0xbfb8aa3b, v3
	v_exp_f32_e32 v48, v48
	s_nop 0
	v_add_f32_e32 v48, 1.0, v48
	v_rcp_f32_e32 v49, v48
	s_nop 0
	v_mul_f32_e32 v3, v3, v49
	v_mul_f32_e32 v3, v47, v3
	v_cvt_pk_bf16_f32 v3, v3, v3
	ds_write_b16 v1, v3 offset:2512
	ds_read_u16 v3, v1 offset:2784
	v_mul_f32_e32 v47, v116, v40
	v_mul_f32_e32 v47, v47, v234
	s_waitcnt lgkmcnt(0)
	v_lshlrev_b32_e32 v3, 16, v3
	v_mul_f32_e32 v48, 0xbfb8aa3b, v3
	v_exp_f32_e32 v48, v48
	s_nop 0
	v_add_f32_e32 v48, 1.0, v48
	v_rcp_f32_e32 v49, v48
	s_nop 0
	v_mul_f32_e32 v3, v3, v49
	v_mul_f32_e32 v3, v47, v3
	v_cvt_pk_bf16_f32 v3, v3, v3
	ds_write_b16 v1, v3 offset:2784
	ds_read_u16 v3, v1 offset:3056
	v_mul_f32_e32 v47, v115, v35
	v_mul_f32_e32 v47, v47, v234
	s_waitcnt lgkmcnt(0)
	v_lshlrev_b32_e32 v3, 16, v3
	v_mul_f32_e32 v48, 0xbfb8aa3b, v3
	v_exp_f32_e32 v48, v48
	s_nop 0
	v_add_f32_e32 v48, 1.0, v48
	v_rcp_f32_e32 v49, v48
	s_nop 0
	v_mul_f32_e32 v3, v3, v49
	v_mul_f32_e32 v3, v47, v3
	v_cvt_pk_bf16_f32 v3, v3, v3
	ds_write_b16 v1, v3 offset:3056
	ds_read_u16 v3, v1 offset:4416
	v_mul_f32_e32 v47, v114, v31
	v_mul_f32_e32 v47, v47, v234
	s_waitcnt lgkmcnt(0)
	v_lshlrev_b32_e32 v3, 16, v3
	v_mul_f32_e32 v48, 0xbfb8aa3b, v3
	v_exp_f32_e32 v48, v48
	s_nop 0
	v_add_f32_e32 v48, 1.0, v48
	v_rcp_f32_e32 v49, v48
	s_nop 0
	v_mul_f32_e32 v3, v3, v49
	v_mul_f32_e32 v3, v47, v3
	v_cvt_pk_bf16_f32 v3, v3, v3
	ds_write_b16 v1, v3 offset:4416
	ds_read_u16 v3, v1 offset:4688
	v_mul_f32_e32 v47, v113, v27
	v_mul_f32_e32 v47, v47, v234
	s_waitcnt lgkmcnt(0)
	v_lshlrev_b32_e32 v3, 16, v3
	v_mul_f32_e32 v48, 0xbfb8aa3b, v3
	v_exp_f32_e32 v48, v48
	s_nop 0
	v_add_f32_e32 v48, 1.0, v48
	v_rcp_f32_e32 v49, v48
	s_nop 0
	v_mul_f32_e32 v3, v3, v49
	v_mul_f32_e32 v3, v47, v3
	v_cvt_pk_bf16_f32 v3, v3, v3
	ds_write_b16 v1, v3 offset:4688
	ds_read_u16 v3, v1 offset:4960
	v_mul_f32_e32 v47, v112, v25
	v_mul_f32_e32 v47, v47, v234
	s_waitcnt lgkmcnt(0)
	v_lshlrev_b32_e32 v3, 16, v3
	v_mul_f32_e32 v48, 0xbfb8aa3b, v3
	v_exp_f32_e32 v48, v48
	s_nop 0
	v_add_f32_e32 v48, 1.0, v48
	v_rcp_f32_e32 v49, v48
	s_nop 0
	v_mul_f32_e32 v3, v3, v49
	v_mul_f32_e32 v3, v47, v3
	v_cvt_pk_bf16_f32 v3, v3, v3
	ds_write_b16 v1, v3 offset:4960
	ds_read_u16 v3, v1 offset:5232
	v_mul_f32_e32 v47, v111, v24
	v_mul_f32_e32 v47, v47, v234
	s_waitcnt lgkmcnt(0)
	v_lshlrev_b32_e32 v3, 16, v3
	v_mul_f32_e32 v48, 0xbfb8aa3b, v3
	v_exp_f32_e32 v48, v48
	s_nop 0
	v_add_f32_e32 v48, 1.0, v48
	v_rcp_f32_e32 v49, v48
	s_nop 0
	v_mul_f32_e32 v3, v3, v49
	v_mul_f32_e32 v3, v47, v3
	v_cvt_pk_bf16_f32 v3, v3, v3
	ds_write_b16 v1, v3 offset:5232
	ds_read_u16 v3, v1 offset:6592
	v_mul_f32_e32 v47, v110, v23
	v_mul_f32_e32 v47, v47, v234
	s_waitcnt lgkmcnt(0)
	v_lshlrev_b32_e32 v3, 16, v3
	v_mul_f32_e32 v48, 0xbfb8aa3b, v3
	v_exp_f32_e32 v48, v48
	s_nop 0
	v_add_f32_e32 v48, 1.0, v48
	v_rcp_f32_e32 v49, v48
	s_nop 0
	v_mul_f32_e32 v3, v3, v49
	v_mul_f32_e32 v3, v47, v3
	v_cvt_pk_bf16_f32 v3, v3, v3
	ds_write_b16 v1, v3 offset:6592
	ds_read_u16 v3, v1 offset:6864
	v_mul_f32_e32 v47, v109, v22
	v_mul_f32_e32 v47, v47, v234
	s_waitcnt lgkmcnt(0)
	v_lshlrev_b32_e32 v3, 16, v3
	v_mul_f32_e32 v48, 0xbfb8aa3b, v3
	v_exp_f32_e32 v48, v48
	s_nop 0
	v_add_f32_e32 v48, 1.0, v48
	v_rcp_f32_e32 v49, v48
	s_nop 0
	v_mul_f32_e32 v3, v3, v49
	v_mul_f32_e32 v3, v47, v3
	v_cvt_pk_bf16_f32 v3, v3, v3
	ds_write_b16 v1, v3 offset:6864
	ds_read_u16 v3, v1 offset:7136
	v_mul_f32_e32 v47, v108, v21
	v_mul_f32_e32 v47, v47, v234
	s_waitcnt lgkmcnt(0)
	v_lshlrev_b32_e32 v3, 16, v3
	v_mul_f32_e32 v48, 0xbfb8aa3b, v3
	v_exp_f32_e32 v48, v48
	s_nop 0
	v_add_f32_e32 v48, 1.0, v48
	v_rcp_f32_e32 v49, v48
	s_nop 0
	v_mul_f32_e32 v3, v3, v49
	v_mul_f32_e32 v3, v47, v3
	v_cvt_pk_bf16_f32 v3, v3, v3
	ds_write_b16 v1, v3 offset:7136
	ds_read_u16 v3, v1 offset:7408
	v_mul_f32_e32 v47, v107, v20
	v_mul_f32_e32 v2, v47, v234
	s_waitcnt lgkmcnt(0)
	v_lshlrev_b32_e32 v3, 16, v3
	v_mul_f32_e32 v47, 0xbfb8aa3b, v3
	v_exp_f32_e32 v47, v47
	s_nop 0
	v_add_f32_e32 v47, 1.0, v47
	v_div_scale_f32 v48, s[0:1], v47, v47, v3
	s_nop 0
	v_rcp_f32_e32 v48, v47
	s_nop 0
	v_mul_f32_e32 v3, v3, v48
	v_mul_f32_e32 v2, v2, v3
	v_cvt_pk_bf16_f32 v2, v2, s0
	ds_write_b16 v1, v2 offset:7408
	ds_read_u16 v3, v1 offset:128
	v_mul_f32_e32 v47, v106, v46
	s_waitcnt lgkmcnt(0)
	v_lshlrev_b32_e32 v3, 16, v3
	v_mul_f32_e32 v48, 0xbfb8aa3b, v3
	v_exp_f32_e32 v48, v48
	s_waitcnt vmcnt(0)
	v_mul_f32_e32 v47, v47, v236
	v_add_f32_e32 v48, 1.0, v48
	v_div_scale_f32 v49, s[0:1], v48, v48, v3
	v_mul_f32_e32 v39, v39, v236
	v_mul_f32_e32 v38, v38, v236
	v_mul_f32_e32 v37, v37, v236
	v_rcp_f32_e32 v49, v48
	s_nop 0
	v_mul_f32_e32 v3, v3, v49
	v_mul_f32_e32 v3, v47, v3
	v_cvt_pk_bf16_f32 v3, v3, s0
	ds_write_b16 v1, v3 offset:128
	ds_read_u16 v3, v1 offset:400
	v_mul_f32_e32 v47, v105, v45
	v_mul_f32_e32 v47, v47, v236
	v_mul_f32_e32 v36, v36, v236
	v_mul_f32_e32 v34, v34, v236
	s_waitcnt lgkmcnt(0)
; #define LAS __attribute__((address_space(3)))
; DI unsigned cvtpk(float lo, float hi) { f32x2 v = {lo, hi}; bf16x2_t b = __builtin_convertvector(v, bf16x2_t); return __builtin_bit_cast(unsigned, b); }
; DI float bf2f(bf16 b) { return __uint_as_float(((unsigned)b) << 16); }
; DI float siluf_(float x) { return x / (1.f + __expf(-x)); }
; DI void gla_stage3(const Ctx& c0, int layer, int unit, int cb, LAS unsigned char* lds) {
;     ...
;     for (int vb = 0; vb < 4; ++vb) { const float g = gn[32 * vb + r];
; #pragma unroll
;         for (int rg = 0; rg < 16; ++rg) { LAS bf16* e = (LAS bf16*)(R + (4 * hi) * G3_PITCH + r * 2 + ((rg & 3) + 8 * (rg >> 2)) * G3_PITCH + 64 * vb);
;             const float z = bf2f(*e);
;             *e = (bf16)(cvtpk(o[vb][rg] * rs[rg] * g * siluf_(z), 0.f) & 0xffffu); }
;         asm volatile("" ::: "memory"); }
	v_lshlrev_b32_e32 v3, 16, v3
	v_mul_f32_e32 v48, 0xbfb8aa3b, v3
	v_exp_f32_e32 v48, v48
	v_mul_f32_e32 v33, v33, v236
	v_mul_f32_e32 v32, v32, v236
	v_mul_f32_e32 v30, v30, v236
	v_add_f32_e32 v48, 1.0, v48
	v_div_scale_f32 v49, s[0:1], v48, v48, v3
	v_mul_f32_e32 v29, v29, v236
	v_mul_f32_e32 v28, v28, v236
	v_rcp_f32_e32 v49, v48
	s_nop 0
	v_mul_f32_e32 v3, v3, v49
	v_mul_f32_e32 v3, v47, v3
	v_cvt_pk_bf16_f32 v3, v3, s0
	ds_write_b16 v1, v3 offset:400
	ds_read_u16 v3, v1 offset:672
	v_mul_f32_e32 v47, v104, v44
	v_mul_f32_e32 v47, v47, v236
	s_waitcnt lgkmcnt(0)
	v_lshlrev_b32_e32 v3, 16, v3
	v_mul_f32_e32 v48, 0xbfb8aa3b, v3
	v_exp_f32_e32 v48, v48
	s_nop 0
	v_add_f32_e32 v48, 1.0, v48
	v_rcp_f32_e32 v49, v48
	s_nop 0
	v_mul_f32_e32 v3, v3, v49
	v_mul_f32_e32 v3, v47, v3
	v_cvt_pk_bf16_f32 v3, v3, v3
	ds_write_b16 v1, v3 offset:672
	ds_read_u16 v3, v1 offset:944
	v_mul_f32_e32 v47, v103, v43
	v_mul_f32_e32 v47, v47, v236
	s_waitcnt lgkmcnt(0)
	v_lshlrev_b32_e32 v3, 16, v3
	v_mul_f32_e32 v48, 0xbfb8aa3b, v3
	v_exp_f32_e32 v48, v48
	s_nop 0
	v_add_f32_e32 v48, 1.0, v48
	v_rcp_f32_e32 v49, v48
	s_nop 0
	v_mul_f32_e32 v3, v3, v49
	v_mul_f32_e32 v3, v47, v3
	v_cvt_pk_bf16_f32 v3, v3, v3
	ds_write_b16 v1, v3 offset:944
	ds_read_u16 v3, v1 offset:2304
	v_mul_f32_e32 v47, v102, v42
	v_mul_f32_e32 v47, v47, v236
	v_mul_f32_e32 v2, v26, v236
	s_waitcnt lgkmcnt(0)
	v_lshlrev_b32_e32 v3, 16, v3
	v_mul_f32_e32 v48, 0xbfb8aa3b, v3
	v_exp_f32_e32 v48, v48
	s_nop 0
	v_add_f32_e32 v48, 1.0, v48
	v_rcp_f32_e32 v49, v48
	s_nop 0
	v_mul_f32_e32 v3, v3, v49
	v_mul_f32_e32 v3, v47, v3
	v_cvt_pk_bf16_f32 v3, v3, v3
	ds_write_b16 v1, v3 offset:2304
	ds_read_u16 v3, v1 offset:2576
	s_waitcnt lgkmcnt(0)
	v_lshlrev_b32_e32 v3, 16, v3
	v_mul_f32_e32 v47, 0xbfb8aa3b, v3
	v_exp_f32_e32 v47, v47
	s_nop 0
	v_add_f32_e32 v47, 1.0, v47
	v_rcp_f32_e32 v48, v47
	s_nop 0
	v_mul_f32_e32 v3, v3, v48
	v_mul_f32_e32 v3, v39, v3
	v_cvt_pk_bf16_f32 v3, v3, v3
	ds_write_b16 v1, v3 offset:2576
	ds_read_u16 v3, v1 offset:2848
	s_waitcnt lgkmcnt(0)
	v_lshlrev_b32_e32 v3, 16, v3
	v_mul_f32_e32 v39, 0xbfb8aa3b, v3
	v_exp_f32_e32 v39, v39
	s_nop 0
	v_add_f32_e32 v39, 1.0, v39
	v_rcp_f32_e32 v47, v39
	s_nop 0
	v_mul_f32_e32 v3, v3, v47
	v_mul_f32_e32 v3, v38, v3
	v_cvt_pk_bf16_f32 v3, v3, v3
	ds_write_b16 v1, v3 offset:2848
	ds_read_u16 v3, v1 offset:3120
	s_waitcnt lgkmcnt(0)
	v_lshlrev_b32_e32 v3, 16, v3
	v_mul_f32_e32 v38, 0xbfb8aa3b, v3
	v_exp_f32_e32 v38, v38
	s_nop 0
	v_add_f32_e32 v38, 1.0, v38
	v_rcp_f32_e32 v39, v38
	s_nop 0
	v_mul_f32_e32 v3, v3, v39
	v_mul_f32_e32 v3, v37, v3
	v_cvt_pk_bf16_f32 v3, v3, v3
	ds_write_b16 v1, v3 offset:3120
	ds_read_u16 v3, v1 offset:4480
	s_waitcnt lgkmcnt(0)
	v_lshlrev_b32_e32 v3, 16, v3
	v_mul_f32_e32 v37, 0xbfb8aa3b, v3
	v_exp_f32_e32 v37, v37
	s_nop 0
	v_add_f32_e32 v37, 1.0, v37
	v_rcp_f32_e32 v38, v37
	s_nop 0
	v_mul_f32_e32 v3, v3, v38
	v_mul_f32_e32 v3, v36, v3
	v_cvt_pk_bf16_f32 v3, v3, v3
	ds_write_b16 v1, v3 offset:4480
	ds_read_u16 v3, v1 offset:4752
	s_waitcnt lgkmcnt(0)
	v_lshlrev_b32_e32 v3, 16, v3
	v_mul_f32_e32 v36, 0xbfb8aa3b, v3
	v_exp_f32_e32 v36, v36
	s_nop 0
	v_add_f32_e32 v36, 1.0, v36
	v_rcp_f32_e32 v37, v36
	s_nop 0
	v_mul_f32_e32 v3, v3, v37
	v_mul_f32_e32 v3, v34, v3
	v_cvt_pk_bf16_f32 v3, v3, v3
	ds_write_b16 v1, v3 offset:4752
	ds_read_u16 v3, v1 offset:5024
	s_waitcnt lgkmcnt(0)
	v_lshlrev_b32_e32 v3, 16, v3
	v_mul_f32_e32 v34, 0xbfb8aa3b, v3
	v_exp_f32_e32 v34, v34
	s_nop 0
	v_add_f32_e32 v34, 1.0, v34
	v_rcp_f32_e32 v36, v34
	s_nop 0
	v_mul_f32_e32 v3, v3, v36
	v_mul_f32_e32 v3, v33, v3
	v_cvt_pk_bf16_f32 v3, v3, v3
	ds_write_b16 v1, v3 offset:5024
	ds_read_u16 v3, v1 offset:5296
	s_waitcnt lgkmcnt(0)
	v_lshlrev_b32_e32 v3, 16, v3
	v_mul_f32_e32 v33, 0xbfb8aa3b, v3
	v_exp_f32_e32 v33, v33
	s_nop 0
	v_add_f32_e32 v33, 1.0, v33
	v_rcp_f32_e32 v34, v33
	s_nop 0
	v_mul_f32_e32 v3, v3, v34
	v_mul_f32_e32 v3, v32, v3
	v_cvt_pk_bf16_f32 v3, v3, v3
	ds_write_b16 v1, v3 offset:5296
	ds_read_u16 v3, v1 offset:6656
	s_waitcnt lgkmcnt(0)
	v_lshlrev_b32_e32 v3, 16, v3
	v_mul_f32_e32 v32, 0xbfb8aa3b, v3
	v_exp_f32_e32 v32, v32
	s_nop 0
	v_add_f32_e32 v32, 1.0, v32
	v_rcp_f32_e32 v33, v32
	s_nop 0
	v_mul_f32_e32 v3, v3, v33
	v_mul_f32_e32 v3, v30, v3
	v_cvt_pk_bf16_f32 v3, v3, v3
	ds_write_b16 v1, v3 offset:6656
	ds_read_u16 v3, v1 offset:6928
	s_waitcnt lgkmcnt(0)
	v_lshlrev_b32_e32 v3, 16, v3
	v_mul_f32_e32 v30, 0xbfb8aa3b, v3
	v_exp_f32_e32 v30, v30
	s_nop 0
	v_add_f32_e32 v30, 1.0, v30
	v_rcp_f32_e32 v32, v30
	s_nop 0
	v_mul_f32_e32 v3, v3, v32
	v_mul_f32_e32 v3, v29, v3
	v_cvt_pk_bf16_f32 v3, v3, v3
	ds_write_b16 v1, v3 offset:6928
	ds_read_u16 v3, v1 offset:7200
	s_waitcnt lgkmcnt(0)
	v_lshlrev_b32_e32 v3, 16, v3
	v_mul_f32_e32 v29, 0xbfb8aa3b, v3
	v_exp_f32_e32 v29, v29
	s_nop 0
	v_add_f32_e32 v29, 1.0, v29
	v_rcp_f32_e32 v30, v29
	s_nop 0
	v_mul_f32_e32 v3, v3, v30
	v_mul_f32_e32 v3, v28, v3
	v_cvt_pk_bf16_f32 v3, v3, v3
	ds_write_b16 v1, v3 offset:7200
	ds_read_u16 v3, v1 offset:7472
	s_waitcnt lgkmcnt(0)
	v_lshlrev_b32_e32 v3, 16, v3
	v_mul_f32_e32 v26, 0xbfb8aa3b, v3
	v_exp_f32_e32 v26, v26
	s_nop 0
	v_add_f32_e32 v26, 1.0, v26
	v_div_scale_f32 v28, s[0:1], v26, v26, v3
	s_nop 0
	v_rcp_f32_e32 v28, v26
	s_nop 0
	v_mul_f32_e32 v3, v3, v28
	v_mul_f32_e32 v2, v2, v3
	v_cvt_pk_bf16_f32 v2, v2, s0
	ds_write_b16 v1, v2 offset:7472
	ds_read_u16 v3, v1 offset:192
	s_waitcnt lgkmcnt(0)
	v_lshlrev_b32_e32 v3, 16, v3
	v_mul_f32_e32 v26, 0xbfb8aa3b, v3
	v_exp_f32_e32 v26, v26
	s_waitcnt vmcnt(31)
; #define LAS __attribute__((address_space(3)))
; #define LDS_WAIT() asm volatile("s_waitcnt lgkmcnt(0)" ::: "memory")
; DI unsigned cvtpk(float lo, float hi) { f32x2 v = {lo, hi}; bf16x2_t b = __builtin_convertvector(v, bf16x2_t); return __builtin_bit_cast(unsigned, b); }
; DI float bf2f(bf16 b) { return __uint_as_float(((unsigned)b) << 16); }
; DI float siluf_(float x) { return x / (1.f + __expf(-x)); }
; DI void g3_tile_out(bf16* g, const LAS unsigned char* R, int lane) {
;     LDS_WAIT();
; #pragma unroll
;     for (int it = 0; it < 8; ++it) { const int row = 4 * it + (lane >> 4), ch = lane & 15;
;         *(u32x4*)(g + (size_t)row * 512 + ch * 8) = *(const LAS u32x4*)(R + row * G3_PITCH + ch * 16); }
;     LDS_WAIT();
; }
; DI void gla_stage3(const Ctx& c0, int layer, int unit, int cb, LAS unsigned char* lds) {
;     ...
;     for (int vb = 0; vb < 4; ++vb) { const float g = gn[32 * vb + r];
; #pragma unroll
;         for (int rg = 0; rg < 16; ++rg) { LAS bf16* e = (LAS bf16*)(R + (4 * hi) * G3_PITCH + r * 2 + ((rg & 3) + 8 * (rg >> 2)) * G3_PITCH + 64 * vb);
;             const float z = bf2f(*e);
;             *e = (bf16)(cvtpk(o[vb][rg] * rs[rg] * g * siluf_(z), 0.f) & 0xffffu); }
;         asm volatile("" ::: "memory"); }
;     g3_tile_out((bf16*)(c.ws + O_OGLA) + row0 * 512 + h * 128, R, lane);
	v_mul_f32_e32 v19, v19, v238
	v_add_f32_e32 v26, 1.0, v26
	v_div_scale_f32 v28, s[0:1], v26, v26, v3
	v_mul_f32_e32 v18, v18, v238
	v_mul_f32_e32 v17, v17, v238
	v_mul_f32_e32 v16, v16, v238
	v_rcp_f32_e32 v28, v26
	s_nop 0
	v_mul_f32_e32 v3, v3, v28
	v_mul_f32_e32 v3, v19, v3
	v_cvt_pk_bf16_f32 v3, v3, s0
	ds_write_b16 v1, v3 offset:192
	ds_read_u16 v3, v1 offset:464
	v_mul_f32_e32 v15, v15, v238
	v_mul_f32_e32 v14, v14, v238
	v_mul_f32_e32 v13, v13, v238
	v_mul_f32_e32 v12, v12, v238
	s_waitcnt lgkmcnt(0)
	v_lshlrev_b32_e32 v3, 16, v3
	v_mul_f32_e32 v19, 0xbfb8aa3b, v3
	v_exp_f32_e32 v19, v19
	v_mul_f32_e32 v11, v11, v238
	v_mul_f32_e32 v10, v10, v238
	v_mul_f32_e32 v9, v9, v238
	v_add_f32_e32 v19, 1.0, v19
	v_div_scale_f32 v26, s[0:1], v19, v19, v3
	v_mul_f32_e32 v8, v8, v238
	v_mul_f32_e32 v7, v7, v238
	v_mul_f32_e32 v6, v6, v238
	v_rcp_f32_e32 v26, v19
	s_nop 0
	v_mul_f32_e32 v3, v3, v26
	v_mul_f32_e32 v3, v18, v3
	v_cvt_pk_bf16_f32 v3, v3, s0
	ds_write_b16 v1, v3 offset:464
	ds_read_u16 v3, v1 offset:736
	v_mul_f32_e32 v5, v5, v238
	v_mul_f32_e32 v2, v4, v238
	s_waitcnt lgkmcnt(0)
	v_lshlrev_b32_e32 v3, 16, v3
	v_mul_f32_e32 v18, 0xbfb8aa3b, v3
	v_exp_f32_e32 v18, v18
	s_nop 0
	v_add_f32_e32 v18, 1.0, v18
	v_rcp_f32_e32 v19, v18
	s_nop 0
	v_mul_f32_e32 v3, v3, v19
	v_mul_f32_e32 v3, v17, v3
	v_cvt_pk_bf16_f32 v3, v3, v3
	ds_write_b16 v1, v3 offset:736
	ds_read_u16 v3, v1 offset:1008
	s_waitcnt lgkmcnt(0)
	v_lshlrev_b32_e32 v3, 16, v3
	v_mul_f32_e32 v17, 0xbfb8aa3b, v3
	v_exp_f32_e32 v17, v17
	s_nop 0
	v_add_f32_e32 v17, 1.0, v17
	v_rcp_f32_e32 v18, v17
	s_nop 0
	v_mul_f32_e32 v3, v3, v18
	v_mul_f32_e32 v3, v16, v3
	v_cvt_pk_bf16_f32 v3, v3, v3
	ds_write_b16 v1, v3 offset:1008
	ds_read_u16 v3, v1 offset:2368
	s_waitcnt lgkmcnt(0)
	v_lshlrev_b32_e32 v3, 16, v3
	v_mul_f32_e32 v16, 0xbfb8aa3b, v3
	v_exp_f32_e32 v16, v16
	s_nop 0
	v_add_f32_e32 v16, 1.0, v16
	v_rcp_f32_e32 v17, v16
	s_nop 0
	v_mul_f32_e32 v3, v3, v17
	v_mul_f32_e32 v3, v15, v3
	v_cvt_pk_bf16_f32 v3, v3, v3
	ds_write_b16 v1, v3 offset:2368
	ds_read_u16 v3, v1 offset:2640
	s_waitcnt lgkmcnt(0)
	v_lshlrev_b32_e32 v3, 16, v3
	v_mul_f32_e32 v15, 0xbfb8aa3b, v3
	v_exp_f32_e32 v15, v15
	s_nop 0
	v_add_f32_e32 v15, 1.0, v15
	v_rcp_f32_e32 v16, v15
	s_nop 0
	v_mul_f32_e32 v3, v3, v16
	v_mul_f32_e32 v3, v14, v3
	v_cvt_pk_bf16_f32 v3, v3, v3
	ds_write_b16 v1, v3 offset:2640
	ds_read_u16 v3, v1 offset:2912
	s_waitcnt lgkmcnt(0)
	v_lshlrev_b32_e32 v3, 16, v3
	v_mul_f32_e32 v14, 0xbfb8aa3b, v3
	v_exp_f32_e32 v14, v14
	s_nop 0
	v_add_f32_e32 v14, 1.0, v14
	v_rcp_f32_e32 v15, v14
	s_nop 0
	v_mul_f32_e32 v3, v3, v15
	v_mul_f32_e32 v3, v13, v3
	v_cvt_pk_bf16_f32 v3, v3, v3
	ds_write_b16 v1, v3 offset:2912
	ds_read_u16 v3, v1 offset:3184
	s_waitcnt lgkmcnt(0)
	v_lshlrev_b32_e32 v3, 16, v3
	v_mul_f32_e32 v13, 0xbfb8aa3b, v3
	v_exp_f32_e32 v13, v13
	s_nop 0
	v_add_f32_e32 v13, 1.0, v13
	v_rcp_f32_e32 v14, v13
	s_nop 0
	v_mul_f32_e32 v3, v3, v14
	v_mul_f32_e32 v3, v12, v3
	v_cvt_pk_bf16_f32 v3, v3, v3
	ds_write_b16 v1, v3 offset:3184
	ds_read_u16 v3, v1 offset:4544
	s_waitcnt lgkmcnt(0)
	v_lshlrev_b32_e32 v3, 16, v3
	v_mul_f32_e32 v12, 0xbfb8aa3b, v3
	v_exp_f32_e32 v12, v12
	s_nop 0
	v_add_f32_e32 v12, 1.0, v12
	v_rcp_f32_e32 v13, v12
	s_nop 0
	v_mul_f32_e32 v3, v3, v13
	v_mul_f32_e32 v3, v11, v3
	v_cvt_pk_bf16_f32 v3, v3, v3
	ds_write_b16 v1, v3 offset:4544
	ds_read_u16 v3, v1 offset:4816
	s_waitcnt lgkmcnt(0)
	v_lshlrev_b32_e32 v3, 16, v3
	v_mul_f32_e32 v11, 0xbfb8aa3b, v3
	v_exp_f32_e32 v11, v11
	s_nop 0
	v_add_f32_e32 v11, 1.0, v11
	v_rcp_f32_e32 v12, v11
	s_nop 0
	v_mul_f32_e32 v3, v3, v12
	v_mul_f32_e32 v3, v10, v3
	v_cvt_pk_bf16_f32 v3, v3, v3
	ds_write_b16 v1, v3 offset:4816
	ds_read_u16 v3, v1 offset:5088
	s_waitcnt lgkmcnt(0)
	v_lshlrev_b32_e32 v3, 16, v3
	v_mul_f32_e32 v10, 0xbfb8aa3b, v3
	v_exp_f32_e32 v10, v10
	s_nop 0
	v_add_f32_e32 v10, 1.0, v10
	v_rcp_f32_e32 v11, v10
	s_nop 0
	v_mul_f32_e32 v3, v3, v11
	v_mul_f32_e32 v3, v9, v3
	v_cvt_pk_bf16_f32 v3, v3, v3
	ds_write_b16 v1, v3 offset:5088
	ds_read_u16 v3, v1 offset:5360
	s_waitcnt lgkmcnt(0)
	v_lshlrev_b32_e32 v3, 16, v3
	v_mul_f32_e32 v9, 0xbfb8aa3b, v3
	v_exp_f32_e32 v9, v9
	s_nop 0
	v_add_f32_e32 v9, 1.0, v9
	v_rcp_f32_e32 v10, v9
	s_nop 0
	v_mul_f32_e32 v3, v3, v10
	v_mul_f32_e32 v3, v8, v3
	v_cvt_pk_bf16_f32 v3, v3, v3
	ds_write_b16 v1, v3 offset:5360
	ds_read_u16 v3, v1 offset:6720
	s_waitcnt lgkmcnt(0)
	v_lshlrev_b32_e32 v3, 16, v3
	v_mul_f32_e32 v8, 0xbfb8aa3b, v3
	v_exp_f32_e32 v8, v8
	s_nop 0
	v_add_f32_e32 v8, 1.0, v8
	v_rcp_f32_e32 v9, v8
	s_nop 0
	v_mul_f32_e32 v3, v3, v9
	v_mul_f32_e32 v3, v7, v3
	v_cvt_pk_bf16_f32 v3, v3, v3
	ds_write_b16 v1, v3 offset:6720
	ds_read_u16 v3, v1 offset:6992
	s_waitcnt lgkmcnt(0)
	v_lshlrev_b32_e32 v3, 16, v3
	v_mul_f32_e32 v7, 0xbfb8aa3b, v3
	v_exp_f32_e32 v7, v7
	s_nop 0
	v_add_f32_e32 v7, 1.0, v7
	v_rcp_f32_e32 v8, v7
	s_nop 0
	v_mul_f32_e32 v3, v3, v8
	v_mul_f32_e32 v3, v6, v3
	v_cvt_pk_bf16_f32 v3, v3, v3
	ds_write_b16 v1, v3 offset:6992
	ds_read_u16 v3, v1 offset:7264
	s_waitcnt lgkmcnt(0)
	v_lshlrev_b32_e32 v3, 16, v3
	v_mul_f32_e32 v6, 0xbfb8aa3b, v3
	v_exp_f32_e32 v6, v6
	s_nop 0
	v_add_f32_e32 v6, 1.0, v6
	v_rcp_f32_e32 v7, v6
	s_nop 0
	v_mul_f32_e32 v3, v3, v7
	v_mul_f32_e32 v3, v5, v3
	v_cvt_pk_bf16_f32 v3, v3, v3
	ds_write_b16 v1, v3 offset:7264
	ds_read_u16 v3, v1 offset:7536
	s_waitcnt lgkmcnt(0)
	v_lshlrev_b32_e32 v3, 16, v3
	v_mul_f32_e32 v4, 0xbfb8aa3b, v3
	v_exp_f32_e32 v4, v4
	s_nop 0
	v_add_f32_e32 v4, 1.0, v4
	v_div_scale_f32 v5, s[0:1], v4, v4, v3
	s_nop 0
	v_rcp_f32_e32 v5, v4
	s_nop 0
	v_mul_f32_e32 v3, v3, v5
	v_mul_f32_e32 v2, v2, v3
	v_cvt_pk_bf16_f32 v2, v2, s0
	ds_write_b16 v1, v2 offset:7536
	s_waitcnt lgkmcnt(0)
	ds_read_b128 v[2:5], v92
	v_lshl_add_u64 v[6:7], v[90:91], 0, s[24:25]
	v_lshl_add_u64 v[8:9], v[6:7], 0, v[66:67]
	s_waitcnt lgkmcnt(0)
	global_store_dwordx4 v[8:9], v[2:5], off
	ds_read_b128 v[2:5], v92 offset:1088
	v_lshl_add_u64 v[8:9], v[6:7], 0, v[68:69]
	s_waitcnt lgkmcnt(0)
	global_store_dwordx4 v[8:9], v[2:5], off
	ds_read_b128 v[2:5], v92 offset:2176
	v_lshl_add_u64 v[8:9], v[6:7], 0, v[70:71]
	s_waitcnt lgkmcnt(0)
	global_store_dwordx4 v[8:9], v[2:5], off
	ds_read_b128 v[2:5], v92 offset:3264
	v_lshl_add_u64 v[8:9], v[6:7], 0, v[72:73]
	s_waitcnt lgkmcnt(0)
	global_store_dwordx4 v[8:9], v[2:5], off
	ds_read_b128 v[2:5], v92 offset:4352
	v_lshl_add_u64 v[8:9], v[6:7], 0, v[74:75]
	s_waitcnt lgkmcnt(0)
	global_store_dwordx4 v[8:9], v[2:5], off
	ds_read_b128 v[2:5], v92 offset:5440
	v_lshl_add_u64 v[8:9], v[6:7], 0, v[76:77]
	s_waitcnt lgkmcnt(0)
	global_store_dwordx4 v[8:9], v[2:5], off
	ds_read_b128 v[2:5], v92 offset:6528
	v_lshl_add_u64 v[8:9], v[6:7], 0, v[78:79]
	v_lshl_add_u64 v[6:7], v[6:7], 0, v[80:81]
	s_waitcnt lgkmcnt(0)
	global_store_dwordx4 v[8:9], v[2:5], off
	ds_read_b128 v[2:5], v92 offset:7616
	s_waitcnt lgkmcnt(0)
	global_store_dwordx4 v[6:7], v[2:5], off
	s_waitcnt lgkmcnt(0)
	s_cbranch_scc1 .LBB0_1216
